# K-loops: instructions between a MFMA segment's last MFMA and its barrier moved into the neighbouring load segments; duplicate waits dropped
# speedup vs baseline: 1.0061x; 1.0054x over previous
; #define G_STAGE(bufoff, gbase, o0, h64) do { \
;         __builtin_amdgcn_global_load_lds((const unsigned*)((const char*)(gbase) + (o0)), (LAS unsigned*)(lds + (bufoff) + ldsw), 16, 0, 0); \
;         __builtin_amdgcn_global_load_lds((const unsigned*)((const char*)(gbase) + (h64) + (o0)), (LAS unsigned*)(lds + (bufoff) + ldsw + 8192), 16, 0, 0); } while (0)
; #define G_LDA(dst, b, h) do { _Pragma("unroll") for (int m = 0; m < 4; ++m) _Pragma("unroll") for (int k = 0; k < 2; ++k) dst[m][k] = *(const LAS bf16x8*)(lds + G_SA(b, h) + aoff + m * 2048 + k * 1024); } while (0)
; #define G_LDB(dst, b, h) do { _Pragma("unroll") for (int n = 0; n < 2; ++n) _Pragma("unroll") for (int k = 0; k < 2; ++k) dst[n][k] = *(const LAS bf16x8*)(lds + G_SB(b, h) + boff + n * 2048 + k * 1024); } while (0)
; #define G_WAIT_L(n) asm volatile("s_waitcnt lgkmcnt(" #n ")" ::: "memory")
; #define G_BAR __builtin_amdgcn_s_barrier()
; #define G_SCHED __builtin_amdgcn_sched_barrier(0)
;     ...
;         for (int t = 0; t < nt; t += 2) {
;             const bool last = (t == nt - 2);
;             const char* a1 = cA + (size_t)(t + 1) * ckA;
;             const char* a2 = last ? nA : cA + (size_t)(t + 2) * ckA; const char* b2 = last ? nB : cB + (size_t)(t + 2) * kB;
;             const char* a3 = a2 + ckA; const char* b3 = b2 + kB;
;             G_LDB(B0, 0, 0); G_SCHED; G_LDA(At, 0, 0); G_STAGE(G_SA(1, 1), a1 + chA, cA0, qA);
;             G_WAIT_L(8); G_BAR; G_WAIT_L(0); G_MMA(0, 0, At, B0); G_BAR; G_SCHED;
;             G_LDB(B1, 0, 1); G_STAGE(G_SB(0, 0), b2, cB0, qB);
;             G_BAR; G_WAIT_L(0); G_MMA(0, 1, At, B1); G_BAR;
;             G_LDA(At, 0, 1); G_STAGE(G_SA(0, 0), a2, cA0, qA);
;             G_BAR; G_WAIT_L(0); G_MMA(1, 0, At, B0); G_BAR; G_SCHED;
.Ldbj_WIN_in:
.LBB0_212:
	s_add_u32 s4, s2, 0xfffc0080
	s_addc_u32 s5, s3, -1
	s_add_i32 s41, 0, 0x10000
	v_add_u32_e32 v0, s41, v167
	ds_read_b128 v[136:139], v0
	ds_read_b128 v[144:147], v0 offset:1024
	ds_read_b128 v[148:151], v0 offset:2048
	ds_read_b128 v[152:155], v0 offset:3072
	s_cmp_eq_u32 s23, 12
	s_cselect_b32 s43, s19, s5
	s_cselect_b32 s42, s18, s4
	s_cselect_b32 s51, s21, s22
	s_cselect_b32 s50, s20, s7
	v_lshl_add_u64 v[164:165], s[2:3], 0, v[142:143]
	s_add_i32 m0, s27, 0xc000
	ds_read_b128 v[156:159], v172
	ds_read_b128 v[160:163], v172 offset:1024
	ds_read_b128 v[174:177], v172 offset:2048
	ds_read_b128 v[178:181], v172 offset:3072
	ds_read_b128 v[182:185], v172 offset:4096
	ds_read_b128 v[196:199], v172 offset:5120
	ds_read_b128 v[200:203], v172 offset:6144
	ds_read_b128 v[204:207], v172 offset:7168
	global_load_lds_dwordx4 v[164:165], off
	v_lshl_add_u64 v[164:165], v[164:165], 0, s[0:1]
	s_add_i32 m0, s27, 0xe000
	s_nop 0
	global_load_lds_dwordx4 v[164:165], off
	s_waitcnt lgkmcnt(8)
	s_barrier
	s_waitcnt lgkmcnt(0)
	v_mfma_f32_16x16x32_bf16 v[132:135], v[136:139], v[156:159], v[132:135]
	v_mfma_f32_16x16x32_bf16 v[128:131], v[148:151], v[156:159], v[128:131]
	v_mfma_f32_16x16x32_bf16 v[116:119], v[136:139], v[174:177], v[116:119]
	v_mfma_f32_16x16x32_bf16 v[112:115], v[148:151], v[174:177], v[112:115]
	v_mfma_f32_16x16x32_bf16 v[100:103], v[136:139], v[182:185], v[100:103]
	v_mfma_f32_16x16x32_bf16 v[96:99], v[148:151], v[182:185], v[96:99]
	v_mfma_f32_16x16x32_bf16 v[84:87], v[136:139], v[200:203], v[84:87]
	v_mfma_f32_16x16x32_bf16 v[80:83], v[148:151], v[200:203], v[80:83]
	v_mfma_f32_16x16x32_bf16 v[132:135], v[144:147], v[160:163], v[132:135]
	v_mfma_f32_16x16x32_bf16 v[128:131], v[152:155], v[160:163], v[128:131]
	v_mfma_f32_16x16x32_bf16 v[116:119], v[144:147], v[178:181], v[116:119]
	v_mfma_f32_16x16x32_bf16 v[112:115], v[152:155], v[178:181], v[112:115]
	v_mfma_f32_16x16x32_bf16 v[100:103], v[144:147], v[196:199], v[100:103]
	v_mfma_f32_16x16x32_bf16 v[96:99], v[152:155], v[196:199], v[96:99]
	v_mfma_f32_16x16x32_bf16 v[84:87], v[144:147], v[204:207], v[84:87]
	v_mfma_f32_16x16x32_bf16 v[80:83], v[152:155], v[204:207], v[80:83]
	s_barrier
	s_add_i32 s4, 0, 0x14000
	s_add_i32 s5, s41, s26
	v_add_u32_e32 v0, s4, v167
	v_lshl_add_u64 v[164:165], s[50:51], 0, v[140:141]
	s_mov_b32 m0, s5
	ds_read_b128 v[208:211], v0
	ds_read_b128 v[212:215], v0 offset:1024
	ds_read_b128 v[216:219], v0 offset:2048
	ds_read_b128 v[220:223], v0 offset:3072
	global_load_lds_dwordx4 v[164:165], off
	v_lshl_add_u64 v[224:225], v[164:165], 0, s[0:1]
	s_add_i32 m0, s5, 0x2000
	s_nop 0
	global_load_lds_dwordx4 v[224:225], off
	s_barrier
	s_waitcnt lgkmcnt(0)
	v_mfma_f32_16x16x32_bf16 v[124:127], v[208:211], v[156:159], v[124:127]
	v_mfma_f32_16x16x32_bf16 v[120:123], v[216:219], v[156:159], v[120:123]
	v_mfma_f32_16x16x32_bf16 v[108:111], v[208:211], v[174:177], v[108:111]
	v_mfma_f32_16x16x32_bf16 v[104:107], v[216:219], v[174:177], v[104:107]
	v_mfma_f32_16x16x32_bf16 v[92:95], v[208:211], v[182:185], v[92:95]
	v_mfma_f32_16x16x32_bf16 v[88:91], v[216:219], v[182:185], v[88:91]
	v_mfma_f32_16x16x32_bf16 v[76:79], v[208:211], v[200:203], v[76:79]
	v_mfma_f32_16x16x32_bf16 v[72:75], v[216:219], v[200:203], v[72:75]
	v_mfma_f32_16x16x32_bf16 v[124:127], v[212:215], v[160:163], v[124:127]
	v_mfma_f32_16x16x32_bf16 v[120:123], v[220:223], v[160:163], v[120:123]
	v_mfma_f32_16x16x32_bf16 v[108:111], v[212:215], v[178:181], v[108:111]
	v_mfma_f32_16x16x32_bf16 v[104:107], v[220:223], v[178:181], v[104:107]
	v_mfma_f32_16x16x32_bf16 v[92:95], v[212:215], v[196:199], v[92:95]
	v_mfma_f32_16x16x32_bf16 v[88:91], v[220:223], v[196:199], v[88:91]
	v_mfma_f32_16x16x32_bf16 v[76:79], v[212:215], v[204:207], v[76:79]
	v_mfma_f32_16x16x32_bf16 v[72:75], v[220:223], v[204:207], v[72:75]
	s_barrier
	s_mov_b32 m0, s27
	v_lshl_add_u64 v[224:225], s[42:43], 0, v[2:3]
	ds_read_b128 v[156:159], v172 offset:16384
	ds_read_b128 v[160:163], v172 offset:17408
	ds_read_b128 v[174:177], v172 offset:18432
	ds_read_b128 v[178:181], v172 offset:19456
	ds_read_b128 v[182:185], v172 offset:20480
	ds_read_b128 v[196:199], v172 offset:21504
	ds_read_b128 v[200:203], v172 offset:22528
	ds_read_b128 v[204:207], v172 offset:23552
	global_load_lds_dwordx4 v[224:225], off
	v_lshl_add_u64 v[226:227], v[224:225], 0, s[0:1]
	s_mov_b32 m0, s28
	s_nop 0
	global_load_lds_dwordx4 v[226:227], off
	s_barrier
	s_waitcnt lgkmcnt(0)
	v_mfma_f32_16x16x32_bf16 v[68:71], v[136:139], v[156:159], v[68:71]
	v_mfma_f32_16x16x32_bf16 v[64:67], v[148:151], v[156:159], v[64:67]
	v_mfma_f32_16x16x32_bf16 v[52:55], v[136:139], v[174:177], v[52:55]
	v_mfma_f32_16x16x32_bf16 v[48:51], v[148:151], v[174:177], v[48:51]
	v_mfma_f32_16x16x32_bf16 v[36:39], v[136:139], v[182:185], v[36:39]
	v_mfma_f32_16x16x32_bf16 v[32:35], v[148:151], v[182:185], v[32:35]
	v_mfma_f32_16x16x32_bf16 v[20:23], v[136:139], v[200:203], v[20:23]
	v_mfma_f32_16x16x32_bf16 v[16:19], v[148:151], v[200:203], v[16:19]
	v_mfma_f32_16x16x32_bf16 v[68:71], v[144:147], v[160:163], v[68:71]
	v_mfma_f32_16x16x32_bf16 v[64:67], v[152:155], v[160:163], v[64:67]
	v_mfma_f32_16x16x32_bf16 v[52:55], v[144:147], v[178:181], v[52:55]
	v_mfma_f32_16x16x32_bf16 v[48:51], v[152:155], v[178:181], v[48:51]
	v_mfma_f32_16x16x32_bf16 v[36:39], v[144:147], v[196:199], v[36:39]
	v_mfma_f32_16x16x32_bf16 v[32:35], v[152:155], v[196:199], v[32:35]
	v_mfma_f32_16x16x32_bf16 v[20:23], v[144:147], v[204:207], v[20:23]
	v_mfma_f32_16x16x32_bf16 v[16:19], v[152:155], v[204:207], v[16:19]
	s_barrier
; #define G_STAGE(bufoff, gbase, o0, h64) do { \
;         __builtin_amdgcn_global_load_lds((const unsigned*)((const char*)(gbase) + (o0)), (LAS unsigned*)(lds + (bufoff) + ldsw), 16, 0, 0); \
;         __builtin_amdgcn_global_load_lds((const unsigned*)((const char*)(gbase) + (h64) + (o0)), (LAS unsigned*)(lds + (bufoff) + ldsw + 8192), 16, 0, 0); } while (0)
; #define G_LDA(dst, b, h) do { _Pragma("unroll") for (int m = 0; m < 4; ++m) _Pragma("unroll") for (int k = 0; k < 2; ++k) dst[m][k] = *(const LAS bf16x8*)(lds + G_SA(b, h) + aoff + m * 2048 + k * 1024); } while (0)
; #define G_LDB(dst, b, h) do { _Pragma("unroll") for (int n = 0; n < 2; ++n) _Pragma("unroll") for (int k = 0; k < 2; ++k) dst[n][k] = *(const LAS bf16x8*)(lds + G_SB(b, h) + boff + n * 2048 + k * 1024); } while (0)
; #define G_WAIT_V(n) asm volatile("s_waitcnt vmcnt(" #n ")" ::: "memory")
; #define G_WAIT_L(n) asm volatile("s_waitcnt lgkmcnt(" #n ")" ::: "memory")
; #define G_BAR __builtin_amdgcn_s_barrier()
; #define G_SCHED __builtin_amdgcn_sched_barrier(0)
;     ...
;             G_STAGE(G_SB(0, 1), b2 + chB, cB0, qB);
;             G_WAIT_V(6); G_BAR; G_MMA(1, 1, At, B1); G_BAR;
;             G_LDB(B0, 1, 0); G_SCHED; G_LDA(At, 1, 0); G_STAGE(G_SA(0, 1), a2 + chA, cA0, qA);
;             G_WAIT_L(8); G_BAR; G_WAIT_L(0); G_MMA(0, 0, At, B0); G_BAR; G_SCHED;
;             G_LDB(B1, 1, 1); G_STAGE(G_SB(1, 0), b3, cB0, qB);
	s_add_i32 s4, s4, s26
	v_lshl_add_u64 v[136:137], v[164:165], 0, s[52:53]
	s_mov_b32 m0, s4
	s_nop 0
	global_load_lds_dwordx4 v[136:137], off
	v_lshl_add_u64 v[136:137], v[164:165], 0, s[54:55]
	s_add_i32 m0, s4, 0x2000
	s_nop 0
	global_load_lds_dwordx4 v[136:137], off
	s_waitcnt vmcnt(6)
	s_barrier
	v_mfma_f32_16x16x32_bf16 v[60:63], v[208:211], v[156:159], v[60:63]
	v_mfma_f32_16x16x32_bf16 v[56:59], v[216:219], v[156:159], v[56:59]
	v_mfma_f32_16x16x32_bf16 v[44:47], v[208:211], v[174:177], v[44:47]
	v_mfma_f32_16x16x32_bf16 v[40:43], v[216:219], v[174:177], v[40:43]
	v_mfma_f32_16x16x32_bf16 v[28:31], v[208:211], v[182:185], v[28:31]
	v_mfma_f32_16x16x32_bf16 v[24:27], v[216:219], v[182:185], v[24:27]
	v_mfma_f32_16x16x32_bf16 v[12:15], v[208:211], v[200:203], v[12:15]
	v_mfma_f32_16x16x32_bf16 v[8:11], v[216:219], v[200:203], v[8:11]
	v_mfma_f32_16x16x32_bf16 v[60:63], v[212:215], v[160:163], v[60:63]
	v_mfma_f32_16x16x32_bf16 v[56:59], v[220:223], v[160:163], v[56:59]
	v_mfma_f32_16x16x32_bf16 v[44:47], v[212:215], v[178:181], v[44:47]
	v_mfma_f32_16x16x32_bf16 v[40:43], v[220:223], v[178:181], v[40:43]
	v_mfma_f32_16x16x32_bf16 v[28:31], v[212:215], v[196:199], v[28:31]
	v_mfma_f32_16x16x32_bf16 v[24:27], v[220:223], v[196:199], v[24:27]
	v_mfma_f32_16x16x32_bf16 v[12:15], v[212:215], v[204:207], v[12:15]
	v_mfma_f32_16x16x32_bf16 v[8:11], v[220:223], v[204:207], v[8:11]
	s_barrier
	s_add_i32 s4, 0, 0x18000
	v_add_u32_e32 v0, s4, v167
	ds_read_b128 v[136:139], v0
	ds_read_b128 v[144:147], v0 offset:1024
	ds_read_b128 v[148:151], v0 offset:2048
	ds_read_b128 v[152:155], v0 offset:3072
	s_mov_b32 m0, s29
	v_lshl_add_u64 v[208:209], v[224:225], 0, s[52:53]
	ds_read_b128 v[156:159], v172 offset:32768
	ds_read_b128 v[160:163], v172 offset:33792
	ds_read_b128 v[174:177], v172 offset:34816
	ds_read_b128 v[178:181], v172 offset:35840
	ds_read_b128 v[182:185], v172 offset:36864
	ds_read_b128 v[196:199], v172 offset:37888
	ds_read_b128 v[200:203], v172 offset:38912
	ds_read_b128 v[204:207], v172 offset:39936
	global_load_lds_dwordx4 v[208:209], off
	v_lshl_add_u64 v[208:209], v[224:225], 0, s[54:55]
	s_mov_b32 m0, s30
	s_nop 0
	global_load_lds_dwordx4 v[208:209], off
	s_waitcnt lgkmcnt(8)
	s_barrier
	s_waitcnt lgkmcnt(0)
	v_mfma_f32_16x16x32_bf16 v[132:135], v[136:139], v[156:159], v[132:135]
	v_mfma_f32_16x16x32_bf16 v[128:131], v[148:151], v[156:159], v[128:131]
	v_mfma_f32_16x16x32_bf16 v[116:119], v[136:139], v[174:177], v[116:119]
	v_mfma_f32_16x16x32_bf16 v[112:115], v[148:151], v[174:177], v[112:115]
	v_mfma_f32_16x16x32_bf16 v[100:103], v[136:139], v[182:185], v[100:103]
	v_mfma_f32_16x16x32_bf16 v[96:99], v[148:151], v[182:185], v[96:99]
	v_mfma_f32_16x16x32_bf16 v[84:87], v[136:139], v[200:203], v[84:87]
	v_mfma_f32_16x16x32_bf16 v[80:83], v[148:151], v[200:203], v[80:83]
	v_mfma_f32_16x16x32_bf16 v[132:135], v[144:147], v[160:163], v[132:135]
	v_mfma_f32_16x16x32_bf16 v[128:131], v[152:155], v[160:163], v[128:131]
	v_mfma_f32_16x16x32_bf16 v[116:119], v[144:147], v[178:181], v[116:119]
	v_mfma_f32_16x16x32_bf16 v[112:115], v[152:155], v[178:181], v[112:115]
	v_mfma_f32_16x16x32_bf16 v[100:103], v[144:147], v[196:199], v[100:103]
	v_mfma_f32_16x16x32_bf16 v[96:99], v[152:155], v[196:199], v[96:99]
	v_mfma_f32_16x16x32_bf16 v[84:87], v[144:147], v[204:207], v[84:87]
	v_mfma_f32_16x16x32_bf16 v[80:83], v[152:155], v[204:207], v[80:83]
	s_barrier
	s_add_i32 s5, 0, 0x1c000
	s_add_i32 s4, s4, s26
	v_add_u32_e32 v0, s5, v167
	v_lshl_add_u64 v[226:227], v[164:165], 0, s[46:47]
	s_mov_b32 m0, s4
	ds_read_b128 v[208:211], v0
	ds_read_b128 v[212:215], v0 offset:1024
	ds_read_b128 v[216:219], v0 offset:2048
	ds_read_b128 v[220:223], v0 offset:3072
	global_load_lds_dwordx4 v[226:227], off
	v_lshl_add_u64 v[226:227], v[164:165], 0, s[58:59]
	s_add_i32 m0, s4, 0x2000
	s_nop 0
	global_load_lds_dwordx4 v[226:227], off
	s_barrier
; #define G_STAGE(bufoff, gbase, o0, h64) do { \
;         __builtin_amdgcn_global_load_lds((const unsigned*)((const char*)(gbase) + (o0)), (LAS unsigned*)(lds + (bufoff) + ldsw), 16, 0, 0); \
;         __builtin_amdgcn_global_load_lds((const unsigned*)((const char*)(gbase) + (h64) + (o0)), (LAS unsigned*)(lds + (bufoff) + ldsw + 8192), 16, 0, 0); } while (0)
; #define G_LDA(dst, b, h) do { _Pragma("unroll") for (int m = 0; m < 4; ++m) _Pragma("unroll") for (int k = 0; k < 2; ++k) dst[m][k] = *(const LAS bf16x8*)(lds + G_SA(b, h) + aoff + m * 2048 + k * 1024); } while (0)
; #define G_LDB(dst, b, h) do { _Pragma("unroll") for (int n = 0; n < 2; ++n) _Pragma("unroll") for (int k = 0; k < 2; ++k) dst[n][k] = *(const LAS bf16x8*)(lds + G_SB(b, h) + boff + n * 2048 + k * 1024); } while (0)
; #define G_WAIT_V(n) asm volatile("s_waitcnt vmcnt(" #n ")" ::: "memory")
; #define G_WAIT_L(n) asm volatile("s_waitcnt lgkmcnt(" #n ")" ::: "memory")
; #define G_BAR __builtin_amdgcn_s_barrier()
; #define G_SCHED __builtin_amdgcn_sched_barrier(0)
;     ...
;             G_WAIT_L(8); G_BAR; G_WAIT_L(0); G_MMA(0, 0, At, B0); G_BAR; G_SCHED;
;             G_LDB(B1, 1, 1); G_STAGE(G_SB(1, 0), b3, cB0, qB);
;             G_BAR; G_WAIT_L(0); G_MMA(0, 1, At, B1); G_BAR;
;             G_LDA(At, 1, 1); G_STAGE(G_SA(1, 0), a3, cA0, qA);
;             G_BAR; G_WAIT_L(0); G_MMA(1, 0, At, B0); G_BAR; G_SCHED;
;             G_STAGE(G_SB(1, 1), b3 + chB, cB0, qB);
;             G_WAIT_V(6); G_BAR; G_MMA(1, 1, At, B1); G_BAR;
;         }
	s_waitcnt lgkmcnt(0)
	v_mfma_f32_16x16x32_bf16 v[124:127], v[208:211], v[156:159], v[124:127]
	v_mfma_f32_16x16x32_bf16 v[120:123], v[216:219], v[156:159], v[120:123]
	v_mfma_f32_16x16x32_bf16 v[108:111], v[208:211], v[174:177], v[108:111]
	v_mfma_f32_16x16x32_bf16 v[104:107], v[216:219], v[174:177], v[104:107]
	v_mfma_f32_16x16x32_bf16 v[92:95], v[208:211], v[182:185], v[92:95]
	v_mfma_f32_16x16x32_bf16 v[88:91], v[216:219], v[182:185], v[88:91]
	v_mfma_f32_16x16x32_bf16 v[76:79], v[208:211], v[200:203], v[76:79]
	v_mfma_f32_16x16x32_bf16 v[72:75], v[216:219], v[200:203], v[72:75]
	v_mfma_f32_16x16x32_bf16 v[124:127], v[212:215], v[160:163], v[124:127]
	v_mfma_f32_16x16x32_bf16 v[120:123], v[220:223], v[160:163], v[120:123]
	v_mfma_f32_16x16x32_bf16 v[108:111], v[212:215], v[178:181], v[108:111]
	v_mfma_f32_16x16x32_bf16 v[104:107], v[220:223], v[178:181], v[104:107]
	v_mfma_f32_16x16x32_bf16 v[92:95], v[212:215], v[196:199], v[92:95]
	v_mfma_f32_16x16x32_bf16 v[88:91], v[220:223], v[196:199], v[88:91]
	v_mfma_f32_16x16x32_bf16 v[76:79], v[212:215], v[204:207], v[76:79]
	v_mfma_f32_16x16x32_bf16 v[72:75], v[220:223], v[204:207], v[72:75]
	s_barrier
	s_mov_b32 m0, s31
	v_lshl_add_u64 v[226:227], v[224:225], 0, s[46:47]
	ds_read_b128 v[156:159], v172 offset:49152
	ds_read_b128 v[160:163], v172 offset:50176
	ds_read_b128 v[174:177], v172 offset:51200
	ds_read_b128 v[178:181], v172 offset:52224
	ds_read_b128 v[182:185], v172 offset:53248
	ds_read_b128 v[196:199], v172 offset:54272
	ds_read_b128 v[200:203], v172 offset:55296
	ds_read_b128 v[204:207], v172 offset:56320
	global_load_lds_dwordx4 v[226:227], off
	v_lshl_add_u64 v[224:225], v[224:225], 0, s[58:59]
	s_mov_b32 m0, s34
	s_nop 0
	global_load_lds_dwordx4 v[224:225], off
	s_barrier
	s_waitcnt lgkmcnt(0)
	v_mfma_f32_16x16x32_bf16 v[68:71], v[136:139], v[156:159], v[68:71]
	v_mfma_f32_16x16x32_bf16 v[64:67], v[148:151], v[156:159], v[64:67]
	v_mfma_f32_16x16x32_bf16 v[52:55], v[136:139], v[174:177], v[52:55]
	v_mfma_f32_16x16x32_bf16 v[48:51], v[148:151], v[174:177], v[48:51]
	v_mfma_f32_16x16x32_bf16 v[36:39], v[136:139], v[182:185], v[36:39]
	v_mfma_f32_16x16x32_bf16 v[32:35], v[148:151], v[182:185], v[32:35]
	v_mfma_f32_16x16x32_bf16 v[20:23], v[136:139], v[200:203], v[20:23]
	v_mfma_f32_16x16x32_bf16 v[16:19], v[148:151], v[200:203], v[16:19]
	v_mfma_f32_16x16x32_bf16 v[68:71], v[144:147], v[160:163], v[68:71]
	v_mfma_f32_16x16x32_bf16 v[64:67], v[152:155], v[160:163], v[64:67]
	v_mfma_f32_16x16x32_bf16 v[52:55], v[144:147], v[178:181], v[52:55]
	v_mfma_f32_16x16x32_bf16 v[48:51], v[152:155], v[178:181], v[48:51]
	v_mfma_f32_16x16x32_bf16 v[36:39], v[144:147], v[196:199], v[36:39]
	v_mfma_f32_16x16x32_bf16 v[32:35], v[152:155], v[196:199], v[32:35]
	v_mfma_f32_16x16x32_bf16 v[20:23], v[144:147], v[204:207], v[20:23]
	v_mfma_f32_16x16x32_bf16 v[16:19], v[152:155], v[204:207], v[16:19]
	s_barrier
	s_add_i32 s4, s5, s26
	v_lshl_add_u64 v[136:137], v[164:165], 0, s[62:63]
	s_mov_b32 m0, s4
	s_nop 0
	global_load_lds_dwordx4 v[136:137], off
	v_lshl_add_u64 v[136:137], v[164:165], 0, s[64:65]
	s_add_i32 m0, s4, 0x2000
	s_nop 0
	global_load_lds_dwordx4 v[136:137], off
	s_add_i32 s23, s23, 2
	s_add_u32 s2, s2, 0x100
	s_addc_u32 s3, s3, 0
	s_add_u32 s7, s7, 0x100
	s_addc_u32 s22, s22, 0
	s_cmp_gt_u32 s23, 13
	s_waitcnt vmcnt(6)
	s_barrier
	v_mfma_f32_16x16x32_bf16 v[60:63], v[208:211], v[156:159], v[60:63]
	v_mfma_f32_16x16x32_bf16 v[56:59], v[216:219], v[156:159], v[56:59]
	v_mfma_f32_16x16x32_bf16 v[44:47], v[208:211], v[174:177], v[44:47]
	v_mfma_f32_16x16x32_bf16 v[40:43], v[216:219], v[174:177], v[40:43]
	v_mfma_f32_16x16x32_bf16 v[28:31], v[208:211], v[182:185], v[28:31]
	v_mfma_f32_16x16x32_bf16 v[24:27], v[216:219], v[182:185], v[24:27]
	v_mfma_f32_16x16x32_bf16 v[12:15], v[208:211], v[200:203], v[12:15]
	v_mfma_f32_16x16x32_bf16 v[8:11], v[216:219], v[200:203], v[8:11]
	v_mfma_f32_16x16x32_bf16 v[60:63], v[212:215], v[160:163], v[60:63]
	v_mfma_f32_16x16x32_bf16 v[56:59], v[220:223], v[160:163], v[56:59]
	v_mfma_f32_16x16x32_bf16 v[44:47], v[212:215], v[178:181], v[44:47]
	v_mfma_f32_16x16x32_bf16 v[40:43], v[220:223], v[178:181], v[40:43]
	v_mfma_f32_16x16x32_bf16 v[28:31], v[212:215], v[196:199], v[28:31]
	v_mfma_f32_16x16x32_bf16 v[24:27], v[220:223], v[196:199], v[24:27]
	v_mfma_f32_16x16x32_bf16 v[12:15], v[212:215], v[204:207], v[12:15]
	v_mfma_f32_16x16x32_bf16 v[8:11], v[220:223], v[204:207], v[8:11]
	s_cbranch_scc0 .Ldb_WIN_cont
	v_readfirstlane_b32 s101, v186
	s_cmpk_gt_u32 s101, 0xff
	s_cbranch_scc1 .Ldb_WIN_exit
	s_barrier
	s_branch .Ldb_WIN_exit

; #define G_STAGE(bufoff, gbase, o0, h64) do { \
;         __builtin_amdgcn_global_load_lds((const unsigned*)((const char*)(gbase) + (o0)), (LAS unsigned*)(lds + (bufoff) + ldsw), 16, 0, 0); \
;         __builtin_amdgcn_global_load_lds((const unsigned*)((const char*)(gbase) + (h64) + (o0)), (LAS unsigned*)(lds + (bufoff) + ldsw + 8192), 16, 0, 0); } while (0)
; #define G_LDA(dst, b, h) do { _Pragma("unroll") for (int m = 0; m < 4; ++m) _Pragma("unroll") for (int k = 0; k < 2; ++k) dst[m][k] = *(const LAS bf16x8*)(lds + G_SA(b, h) + aoff + m * 2048 + k * 1024); } while (0)
; #define G_LDB(dst, b, h) do { _Pragma("unroll") for (int n = 0; n < 2; ++n) _Pragma("unroll") for (int k = 0; k < 2; ++k) dst[n][k] = *(const LAS bf16x8*)(lds + G_SB(b, h) + boff + n * 2048 + k * 1024); } while (0)
; #define G_WAIT_L(n) asm volatile("s_waitcnt lgkmcnt(" #n ")" ::: "memory")
; #define G_BAR __builtin_amdgcn_s_barrier()
; #define G_SCHED __builtin_amdgcn_sched_barrier(0)
;     ...
;         for (int t = 0; t < nt; t += 2) {
;             const bool last = (t == nt - 2);
;             const char* a1 = cA + (size_t)(t + 1) * ckA;
;             const char* a2 = last ? nA : cA + (size_t)(t + 2) * ckA; const char* b2 = last ? nB : cB + (size_t)(t + 2) * kB;
;             const char* a3 = a2 + ckA; const char* b3 = b2 + kB;
;             G_LDB(B0, 0, 0); G_SCHED; G_LDA(At, 0, 0); G_STAGE(G_SA(1, 1), a1 + chA, cA0, qA);
;             G_WAIT_L(8); G_BAR; G_WAIT_L(0); G_MMA(0, 0, At, B0); G_BAR; G_SCHED;
;             G_LDB(B1, 0, 1); G_STAGE(G_SB(0, 0), b2, cB0, qB);
;             G_BAR; G_WAIT_L(0); G_MMA(0, 1, At, B1); G_BAR;
;             G_LDA(At, 0, 1); G_STAGE(G_SA(0, 0), a2, cA0, qA);
;             G_BAR; G_WAIT_L(0); G_MMA(1, 0, At, B0); G_BAR; G_SCHED;
.Ldbj_SSM1_in:
.LBB0_450:
	s_add_u32 s4, s6, 0xfffe0080
	s_addc_u32 s5, s7, -1
	s_add_i32 s41, 0, 0x10000
	v_add_u32_e32 v0, s41, v145
	ds_read_b128 v[140:143], v0
	ds_read_b128 v[148:151], v0 offset:1024
	ds_read_b128 v[152:155], v0 offset:2048
	ds_read_b128 v[156:159], v0 offset:3072
	s_cmp_eq_u32 s21, 4
	s_cselect_b32 s23, s11, s5
	s_cselect_b32 s22, s10, s4
	s_cselect_b32 s43, s17, s20
	s_cselect_b32 s42, s16, s19
	v_lshl_add_u64 v[184:185], s[6:7], 0, v[138:139]
	s_add_i32 m0, s27, 0xc000
	ds_read_b128 v[160:163], v146
	ds_read_b128 v[164:167], v146 offset:1024
	ds_read_b128 v[172:175], v146 offset:2048
	ds_read_b128 v[176:179], v146 offset:3072
	ds_read_b128 v[180:183], v146 offset:4096
	ds_read_b128 v[196:199], v146 offset:5120
	ds_read_b128 v[200:203], v146 offset:6144
	ds_read_b128 v[204:207], v146 offset:7168
	global_load_lds_dwordx4 v[184:185], off
	v_lshl_add_u64 v[184:185], v[184:185], 0, s[52:53]
	s_add_i32 m0, s27, 0xe000
	s_nop 0
	global_load_lds_dwordx4 v[184:185], off
	s_waitcnt lgkmcnt(8)
	s_barrier
	s_waitcnt lgkmcnt(0)
	v_mfma_f32_16x16x32_bf16 v[132:135], v[140:143], v[160:163], v[132:135]
	v_mfma_f32_16x16x32_bf16 v[128:131], v[152:155], v[160:163], v[128:131]
	v_mfma_f32_16x16x32_bf16 v[116:119], v[140:143], v[172:175], v[116:119]
	v_mfma_f32_16x16x32_bf16 v[112:115], v[152:155], v[172:175], v[112:115]
	v_mfma_f32_16x16x32_bf16 v[100:103], v[140:143], v[180:183], v[100:103]
	v_mfma_f32_16x16x32_bf16 v[96:99], v[152:155], v[180:183], v[96:99]
	v_mfma_f32_16x16x32_bf16 v[84:87], v[140:143], v[200:203], v[84:87]
	v_mfma_f32_16x16x32_bf16 v[80:83], v[152:155], v[200:203], v[80:83]
	v_mfma_f32_16x16x32_bf16 v[132:135], v[148:151], v[164:167], v[132:135]
	v_mfma_f32_16x16x32_bf16 v[128:131], v[156:159], v[164:167], v[128:131]
	v_mfma_f32_16x16x32_bf16 v[116:119], v[148:151], v[176:179], v[116:119]
	v_mfma_f32_16x16x32_bf16 v[112:115], v[156:159], v[176:179], v[112:115]
	v_mfma_f32_16x16x32_bf16 v[100:103], v[148:151], v[196:199], v[100:103]
	v_mfma_f32_16x16x32_bf16 v[96:99], v[156:159], v[196:199], v[96:99]
	v_mfma_f32_16x16x32_bf16 v[84:87], v[148:151], v[204:207], v[84:87]
	v_mfma_f32_16x16x32_bf16 v[80:83], v[156:159], v[204:207], v[80:83]
	s_barrier
	s_add_i32 s4, 0, 0x14000
	s_add_i32 s5, s41, s26
	v_add_u32_e32 v0, s4, v145
	v_lshl_add_u64 v[184:185], s[42:43], 0, v[136:137]
	s_mov_b32 m0, s5
	ds_read_b128 v[208:211], v0
	ds_read_b128 v[212:215], v0 offset:1024
	ds_read_b128 v[216:219], v0 offset:2048
	ds_read_b128 v[220:223], v0 offset:3072
	global_load_lds_dwordx4 v[184:185], off
	v_lshl_add_u64 v[224:225], v[184:185], 0, s[52:53]
	s_add_i32 m0, s5, 0x2000
	s_nop 0
	global_load_lds_dwordx4 v[224:225], off
	s_barrier
	s_waitcnt lgkmcnt(0)
	v_mfma_f32_16x16x32_bf16 v[124:127], v[208:211], v[160:163], v[124:127]
	v_mfma_f32_16x16x32_bf16 v[120:123], v[216:219], v[160:163], v[120:123]
	v_mfma_f32_16x16x32_bf16 v[108:111], v[208:211], v[172:175], v[108:111]
	v_mfma_f32_16x16x32_bf16 v[104:107], v[216:219], v[172:175], v[104:107]
	v_mfma_f32_16x16x32_bf16 v[92:95], v[208:211], v[180:183], v[92:95]
	v_mfma_f32_16x16x32_bf16 v[88:91], v[216:219], v[180:183], v[88:91]
	v_mfma_f32_16x16x32_bf16 v[76:79], v[208:211], v[200:203], v[76:79]
	v_mfma_f32_16x16x32_bf16 v[72:75], v[216:219], v[200:203], v[72:75]
	v_mfma_f32_16x16x32_bf16 v[124:127], v[212:215], v[164:167], v[124:127]
	v_mfma_f32_16x16x32_bf16 v[120:123], v[220:223], v[164:167], v[120:123]
	v_mfma_f32_16x16x32_bf16 v[108:111], v[212:215], v[176:179], v[108:111]
	v_mfma_f32_16x16x32_bf16 v[104:107], v[220:223], v[176:179], v[104:107]
	v_mfma_f32_16x16x32_bf16 v[92:95], v[212:215], v[196:199], v[92:95]
	v_mfma_f32_16x16x32_bf16 v[88:91], v[220:223], v[196:199], v[88:91]
	v_mfma_f32_16x16x32_bf16 v[76:79], v[212:215], v[204:207], v[76:79]
	v_mfma_f32_16x16x32_bf16 v[72:75], v[220:223], v[204:207], v[72:75]
	s_barrier
	s_mov_b32 m0, s27
	v_lshl_add_u64 v[224:225], s[22:23], 0, v[2:3]
	ds_read_b128 v[160:163], v146 offset:16384
	ds_read_b128 v[164:167], v146 offset:17408
	ds_read_b128 v[172:175], v146 offset:18432
	ds_read_b128 v[176:179], v146 offset:19456
	ds_read_b128 v[180:183], v146 offset:20480
	ds_read_b128 v[196:199], v146 offset:21504
	ds_read_b128 v[200:203], v146 offset:22528
	ds_read_b128 v[204:207], v146 offset:23552
	global_load_lds_dwordx4 v[224:225], off
	v_lshl_add_u64 v[226:227], v[224:225], 0, s[52:53]
	s_mov_b32 m0, s28
	s_nop 0
	global_load_lds_dwordx4 v[226:227], off
	s_barrier
	s_waitcnt lgkmcnt(0)
	v_mfma_f32_16x16x32_bf16 v[68:71], v[140:143], v[160:163], v[68:71]
	v_mfma_f32_16x16x32_bf16 v[64:67], v[152:155], v[160:163], v[64:67]
	v_mfma_f32_16x16x32_bf16 v[52:55], v[140:143], v[172:175], v[52:55]
	v_mfma_f32_16x16x32_bf16 v[48:51], v[152:155], v[172:175], v[48:51]
	v_mfma_f32_16x16x32_bf16 v[36:39], v[140:143], v[180:183], v[36:39]
	v_mfma_f32_16x16x32_bf16 v[32:35], v[152:155], v[180:183], v[32:35]
	v_mfma_f32_16x16x32_bf16 v[20:23], v[140:143], v[200:203], v[20:23]
	v_mfma_f32_16x16x32_bf16 v[16:19], v[152:155], v[200:203], v[16:19]
	v_mfma_f32_16x16x32_bf16 v[68:71], v[148:151], v[164:167], v[68:71]
	v_mfma_f32_16x16x32_bf16 v[64:67], v[156:159], v[164:167], v[64:67]
	v_mfma_f32_16x16x32_bf16 v[52:55], v[148:151], v[176:179], v[52:55]
	v_mfma_f32_16x16x32_bf16 v[48:51], v[156:159], v[176:179], v[48:51]
	v_mfma_f32_16x16x32_bf16 v[36:39], v[148:151], v[196:199], v[36:39]
	v_mfma_f32_16x16x32_bf16 v[32:35], v[156:159], v[196:199], v[32:35]
	v_mfma_f32_16x16x32_bf16 v[20:23], v[148:151], v[204:207], v[20:23]
	v_mfma_f32_16x16x32_bf16 v[16:19], v[156:159], v[204:207], v[16:19]
	s_barrier
; #define G_STAGE(bufoff, gbase, o0, h64) do { \
;         __builtin_amdgcn_global_load_lds((const unsigned*)((const char*)(gbase) + (o0)), (LAS unsigned*)(lds + (bufoff) + ldsw), 16, 0, 0); \
;         __builtin_amdgcn_global_load_lds((const unsigned*)((const char*)(gbase) + (h64) + (o0)), (LAS unsigned*)(lds + (bufoff) + ldsw + 8192), 16, 0, 0); } while (0)
; #define G_LDA(dst, b, h) do { _Pragma("unroll") for (int m = 0; m < 4; ++m) _Pragma("unroll") for (int k = 0; k < 2; ++k) dst[m][k] = *(const LAS bf16x8*)(lds + G_SA(b, h) + aoff + m * 2048 + k * 1024); } while (0)
; #define G_LDB(dst, b, h) do { _Pragma("unroll") for (int n = 0; n < 2; ++n) _Pragma("unroll") for (int k = 0; k < 2; ++k) dst[n][k] = *(const LAS bf16x8*)(lds + G_SB(b, h) + boff + n * 2048 + k * 1024); } while (0)
; #define G_WAIT_V(n) asm volatile("s_waitcnt vmcnt(" #n ")" ::: "memory")
; #define G_WAIT_L(n) asm volatile("s_waitcnt lgkmcnt(" #n ")" ::: "memory")
; #define G_BAR __builtin_amdgcn_s_barrier()
; #define G_SCHED __builtin_amdgcn_sched_barrier(0)
;     ...
;             G_STAGE(G_SB(0, 1), b2 + chB, cB0, qB);
;             G_WAIT_V(6); G_BAR; G_MMA(1, 1, At, B1); G_BAR;
;             G_LDB(B0, 1, 0); G_SCHED; G_LDA(At, 1, 0); G_STAGE(G_SA(0, 1), a2 + chA, cA0, qA);
;             G_WAIT_L(8); G_BAR; G_WAIT_L(0); G_MMA(0, 0, At, B0); G_BAR; G_SCHED;
;             G_LDB(B1, 1, 1); G_STAGE(G_SB(1, 0), b3, cB0, qB);
	s_add_i32 s4, s4, s26
	v_lshl_add_u64 v[140:141], v[184:185], 0, s[0:1]
	s_mov_b32 m0, s4
	s_nop 0
	global_load_lds_dwordx4 v[140:141], off
	v_lshl_add_u64 v[140:141], v[184:185], 0, s[54:55]
	s_add_i32 m0, s4, 0x2000
	s_nop 0
	global_load_lds_dwordx4 v[140:141], off
	s_waitcnt vmcnt(6)
	s_barrier
	v_mfma_f32_16x16x32_bf16 v[60:63], v[208:211], v[160:163], v[60:63]
	v_mfma_f32_16x16x32_bf16 v[56:59], v[216:219], v[160:163], v[56:59]
	v_mfma_f32_16x16x32_bf16 v[44:47], v[208:211], v[172:175], v[44:47]
	v_mfma_f32_16x16x32_bf16 v[40:43], v[216:219], v[172:175], v[40:43]
	v_mfma_f32_16x16x32_bf16 v[28:31], v[208:211], v[180:183], v[28:31]
	v_mfma_f32_16x16x32_bf16 v[24:27], v[216:219], v[180:183], v[24:27]
	v_mfma_f32_16x16x32_bf16 v[12:15], v[208:211], v[200:203], v[12:15]
	v_mfma_f32_16x16x32_bf16 v[8:11], v[216:219], v[200:203], v[8:11]
	v_mfma_f32_16x16x32_bf16 v[60:63], v[212:215], v[164:167], v[60:63]
	v_mfma_f32_16x16x32_bf16 v[56:59], v[220:223], v[164:167], v[56:59]
	v_mfma_f32_16x16x32_bf16 v[44:47], v[212:215], v[176:179], v[44:47]
	v_mfma_f32_16x16x32_bf16 v[40:43], v[220:223], v[176:179], v[40:43]
	v_mfma_f32_16x16x32_bf16 v[28:31], v[212:215], v[196:199], v[28:31]
	v_mfma_f32_16x16x32_bf16 v[24:27], v[220:223], v[196:199], v[24:27]
	v_mfma_f32_16x16x32_bf16 v[12:15], v[212:215], v[204:207], v[12:15]
	v_mfma_f32_16x16x32_bf16 v[8:11], v[220:223], v[204:207], v[8:11]
	s_barrier
	s_add_i32 s4, 0, 0x18000
	v_add_u32_e32 v0, s4, v145
	ds_read_b128 v[140:143], v0
	ds_read_b128 v[148:151], v0 offset:1024
	ds_read_b128 v[152:155], v0 offset:2048
	ds_read_b128 v[156:159], v0 offset:3072
	s_mov_b32 m0, s29
	v_lshl_add_u64 v[208:209], v[224:225], 0, s[0:1]
	ds_read_b128 v[160:163], v146 offset:32768
	ds_read_b128 v[164:167], v146 offset:33792
	ds_read_b128 v[172:175], v146 offset:34816
	ds_read_b128 v[176:179], v146 offset:35840
	ds_read_b128 v[180:183], v146 offset:36864
	ds_read_b128 v[196:199], v146 offset:37888
	ds_read_b128 v[200:203], v146 offset:38912
	ds_read_b128 v[204:207], v146 offset:39936
	global_load_lds_dwordx4 v[208:209], off
	v_lshl_add_u64 v[208:209], v[224:225], 0, s[54:55]
	s_mov_b32 m0, s30
	s_nop 0
	global_load_lds_dwordx4 v[208:209], off
	s_waitcnt lgkmcnt(8)
	s_barrier
	s_waitcnt lgkmcnt(0)
	v_mfma_f32_16x16x32_bf16 v[132:135], v[140:143], v[160:163], v[132:135]
	v_mfma_f32_16x16x32_bf16 v[128:131], v[152:155], v[160:163], v[128:131]
	v_mfma_f32_16x16x32_bf16 v[116:119], v[140:143], v[172:175], v[116:119]
	v_mfma_f32_16x16x32_bf16 v[112:115], v[152:155], v[172:175], v[112:115]
	v_mfma_f32_16x16x32_bf16 v[100:103], v[140:143], v[180:183], v[100:103]
	v_mfma_f32_16x16x32_bf16 v[96:99], v[152:155], v[180:183], v[96:99]
	v_mfma_f32_16x16x32_bf16 v[84:87], v[140:143], v[200:203], v[84:87]
	v_mfma_f32_16x16x32_bf16 v[80:83], v[152:155], v[200:203], v[80:83]
	v_mfma_f32_16x16x32_bf16 v[132:135], v[148:151], v[164:167], v[132:135]
	v_mfma_f32_16x16x32_bf16 v[128:131], v[156:159], v[164:167], v[128:131]
	v_mfma_f32_16x16x32_bf16 v[116:119], v[148:151], v[176:179], v[116:119]
	v_mfma_f32_16x16x32_bf16 v[112:115], v[156:159], v[176:179], v[112:115]
	v_mfma_f32_16x16x32_bf16 v[100:103], v[148:151], v[196:199], v[100:103]
	v_mfma_f32_16x16x32_bf16 v[96:99], v[156:159], v[196:199], v[96:99]
	v_mfma_f32_16x16x32_bf16 v[84:87], v[148:151], v[204:207], v[84:87]
	v_mfma_f32_16x16x32_bf16 v[80:83], v[156:159], v[204:207], v[80:83]
	s_barrier
	s_add_i32 s5, 0, 0x1c000
	s_add_i32 s4, s4, s26
	v_add_u32_e32 v0, s5, v145
	v_lshl_add_u64 v[226:227], v[184:185], 0, s[46:47]
	s_mov_b32 m0, s4
	ds_read_b128 v[208:211], v0
	ds_read_b128 v[212:215], v0 offset:1024
	ds_read_b128 v[216:219], v0 offset:2048
	ds_read_b128 v[220:223], v0 offset:3072
	global_load_lds_dwordx4 v[226:227], off
	v_lshl_add_u64 v[226:227], v[184:185], 0, s[58:59]
	s_add_i32 m0, s4, 0x2000
	s_nop 0
	global_load_lds_dwordx4 v[226:227], off
	s_barrier
; #define G_STAGE(bufoff, gbase, o0, h64) do { \
;         __builtin_amdgcn_global_load_lds((const unsigned*)((const char*)(gbase) + (o0)), (LAS unsigned*)(lds + (bufoff) + ldsw), 16, 0, 0); \
;         __builtin_amdgcn_global_load_lds((const unsigned*)((const char*)(gbase) + (h64) + (o0)), (LAS unsigned*)(lds + (bufoff) + ldsw + 8192), 16, 0, 0); } while (0)
; #define G_LDA(dst, b, h) do { _Pragma("unroll") for (int m = 0; m < 4; ++m) _Pragma("unroll") for (int k = 0; k < 2; ++k) dst[m][k] = *(const LAS bf16x8*)(lds + G_SA(b, h) + aoff + m * 2048 + k * 1024); } while (0)
; #define G_LDB(dst, b, h) do { _Pragma("unroll") for (int n = 0; n < 2; ++n) _Pragma("unroll") for (int k = 0; k < 2; ++k) dst[n][k] = *(const LAS bf16x8*)(lds + G_SB(b, h) + boff + n * 2048 + k * 1024); } while (0)
; #define G_WAIT_V(n) asm volatile("s_waitcnt vmcnt(" #n ")" ::: "memory")
; #define G_WAIT_L(n) asm volatile("s_waitcnt lgkmcnt(" #n ")" ::: "memory")
; #define G_BAR __builtin_amdgcn_s_barrier()
; #define G_SCHED __builtin_amdgcn_sched_barrier(0)
;     ...
;             G_WAIT_L(8); G_BAR; G_WAIT_L(0); G_MMA(0, 0, At, B0); G_BAR; G_SCHED;
;             G_LDB(B1, 1, 1); G_STAGE(G_SB(1, 0), b3, cB0, qB);
;             G_BAR; G_WAIT_L(0); G_MMA(0, 1, At, B1); G_BAR;
;             G_LDA(At, 1, 1); G_STAGE(G_SA(1, 0), a3, cA0, qA);
;             G_BAR; G_WAIT_L(0); G_MMA(1, 0, At, B0); G_BAR; G_SCHED;
;             G_STAGE(G_SB(1, 1), b3 + chB, cB0, qB);
;             G_WAIT_V(6); G_BAR; G_MMA(1, 1, At, B1); G_BAR;
;         }
	s_waitcnt lgkmcnt(0)
	v_mfma_f32_16x16x32_bf16 v[124:127], v[208:211], v[160:163], v[124:127]
	v_mfma_f32_16x16x32_bf16 v[120:123], v[216:219], v[160:163], v[120:123]
	v_mfma_f32_16x16x32_bf16 v[108:111], v[208:211], v[172:175], v[108:111]
	v_mfma_f32_16x16x32_bf16 v[104:107], v[216:219], v[172:175], v[104:107]
	v_mfma_f32_16x16x32_bf16 v[92:95], v[208:211], v[180:183], v[92:95]
	v_mfma_f32_16x16x32_bf16 v[88:91], v[216:219], v[180:183], v[88:91]
	v_mfma_f32_16x16x32_bf16 v[76:79], v[208:211], v[200:203], v[76:79]
	v_mfma_f32_16x16x32_bf16 v[72:75], v[216:219], v[200:203], v[72:75]
	v_mfma_f32_16x16x32_bf16 v[124:127], v[212:215], v[164:167], v[124:127]
	v_mfma_f32_16x16x32_bf16 v[120:123], v[220:223], v[164:167], v[120:123]
	v_mfma_f32_16x16x32_bf16 v[108:111], v[212:215], v[176:179], v[108:111]
	v_mfma_f32_16x16x32_bf16 v[104:107], v[220:223], v[176:179], v[104:107]
	v_mfma_f32_16x16x32_bf16 v[92:95], v[212:215], v[196:199], v[92:95]
	v_mfma_f32_16x16x32_bf16 v[88:91], v[220:223], v[196:199], v[88:91]
	v_mfma_f32_16x16x32_bf16 v[76:79], v[212:215], v[204:207], v[76:79]
	v_mfma_f32_16x16x32_bf16 v[72:75], v[220:223], v[204:207], v[72:75]
	s_barrier
	s_mov_b32 m0, s31
	v_lshl_add_u64 v[226:227], v[224:225], 0, s[46:47]
	ds_read_b128 v[160:163], v146 offset:49152
	ds_read_b128 v[164:167], v146 offset:50176
	ds_read_b128 v[172:175], v146 offset:51200
	ds_read_b128 v[176:179], v146 offset:52224
	ds_read_b128 v[180:183], v146 offset:53248
	ds_read_b128 v[196:199], v146 offset:54272
	ds_read_b128 v[200:203], v146 offset:55296
	ds_read_b128 v[204:207], v146 offset:56320
	global_load_lds_dwordx4 v[226:227], off
	v_lshl_add_u64 v[224:225], v[224:225], 0, s[58:59]
	s_mov_b32 m0, s33
	s_nop 0
	global_load_lds_dwordx4 v[224:225], off
	s_barrier
	s_waitcnt lgkmcnt(0)
	v_mfma_f32_16x16x32_bf16 v[68:71], v[140:143], v[160:163], v[68:71]
	v_mfma_f32_16x16x32_bf16 v[64:67], v[152:155], v[160:163], v[64:67]
	v_mfma_f32_16x16x32_bf16 v[52:55], v[140:143], v[172:175], v[52:55]
	v_mfma_f32_16x16x32_bf16 v[48:51], v[152:155], v[172:175], v[48:51]
	v_mfma_f32_16x16x32_bf16 v[36:39], v[140:143], v[180:183], v[36:39]
	v_mfma_f32_16x16x32_bf16 v[32:35], v[152:155], v[180:183], v[32:35]
	v_mfma_f32_16x16x32_bf16 v[20:23], v[140:143], v[200:203], v[20:23]
	v_mfma_f32_16x16x32_bf16 v[16:19], v[152:155], v[200:203], v[16:19]
	v_mfma_f32_16x16x32_bf16 v[68:71], v[148:151], v[164:167], v[68:71]
	v_mfma_f32_16x16x32_bf16 v[64:67], v[156:159], v[164:167], v[64:67]
	v_mfma_f32_16x16x32_bf16 v[52:55], v[148:151], v[176:179], v[52:55]
	v_mfma_f32_16x16x32_bf16 v[48:51], v[156:159], v[176:179], v[48:51]
	v_mfma_f32_16x16x32_bf16 v[36:39], v[148:151], v[196:199], v[36:39]
	v_mfma_f32_16x16x32_bf16 v[32:35], v[156:159], v[196:199], v[32:35]
	v_mfma_f32_16x16x32_bf16 v[20:23], v[148:151], v[204:207], v[20:23]
	v_mfma_f32_16x16x32_bf16 v[16:19], v[156:159], v[204:207], v[16:19]
	s_barrier
	s_add_i32 s4, s5, s26
	v_lshl_add_u64 v[140:141], v[184:185], 0, s[50:51]
	s_mov_b32 m0, s4
	s_nop 0
	global_load_lds_dwordx4 v[140:141], off
	v_lshl_add_u64 v[140:141], v[184:185], 0, s[62:63]
	s_add_i32 m0, s4, 0x2000
	s_nop 0
	global_load_lds_dwordx4 v[140:141], off
	s_add_i32 s21, s21, 2
	s_add_u32 s6, s6, 0x100
	s_addc_u32 s7, s7, 0
	s_add_u32 s19, s19, 0x100
	s_addc_u32 s20, s20, 0
	s_cmp_gt_u32 s21, 5
	s_waitcnt vmcnt(6)
	s_barrier
	v_mfma_f32_16x16x32_bf16 v[60:63], v[208:211], v[160:163], v[60:63]
	v_mfma_f32_16x16x32_bf16 v[56:59], v[216:219], v[160:163], v[56:59]
	v_mfma_f32_16x16x32_bf16 v[44:47], v[208:211], v[172:175], v[44:47]
	v_mfma_f32_16x16x32_bf16 v[40:43], v[216:219], v[172:175], v[40:43]
	v_mfma_f32_16x16x32_bf16 v[28:31], v[208:211], v[180:183], v[28:31]
	v_mfma_f32_16x16x32_bf16 v[24:27], v[216:219], v[180:183], v[24:27]
	v_mfma_f32_16x16x32_bf16 v[12:15], v[208:211], v[200:203], v[12:15]
	v_mfma_f32_16x16x32_bf16 v[8:11], v[216:219], v[200:203], v[8:11]
	v_mfma_f32_16x16x32_bf16 v[60:63], v[212:215], v[164:167], v[60:63]
	v_mfma_f32_16x16x32_bf16 v[56:59], v[220:223], v[164:167], v[56:59]
	v_mfma_f32_16x16x32_bf16 v[44:47], v[212:215], v[176:179], v[44:47]
	v_mfma_f32_16x16x32_bf16 v[40:43], v[220:223], v[176:179], v[40:43]
	v_mfma_f32_16x16x32_bf16 v[28:31], v[212:215], v[196:199], v[28:31]
	v_mfma_f32_16x16x32_bf16 v[24:27], v[220:223], v[196:199], v[24:27]
	v_mfma_f32_16x16x32_bf16 v[12:15], v[212:215], v[204:207], v[12:15]
	v_mfma_f32_16x16x32_bf16 v[8:11], v[220:223], v[204:207], v[8:11]
	s_cbranch_scc0 .Ldb_SSM1_cont
	v_readfirstlane_b32 s101, v186
	s_cmpk_gt_u32 s101, 0xff
	s_cbranch_scc1 .Ldb_SSM1_exit
	s_barrier
	s_branch .Ldb_SSM1_exit

; #define G_STAGE(bufoff, gbase, o0, h64) do { \
;         __builtin_amdgcn_global_load_lds((const unsigned*)((const char*)(gbase) + (o0)), (LAS unsigned*)(lds + (bufoff) + ldsw), 16, 0, 0); \
;         __builtin_amdgcn_global_load_lds((const unsigned*)((const char*)(gbase) + (h64) + (o0)), (LAS unsigned*)(lds + (bufoff) + ldsw + 8192), 16, 0, 0); } while (0)
; #define G_LDA(dst, b, h) do { _Pragma("unroll") for (int m = 0; m < 4; ++m) _Pragma("unroll") for (int k = 0; k < 2; ++k) dst[m][k] = *(const LAS bf16x8*)(lds + G_SA(b, h) + aoff + m * 2048 + k * 1024); } while (0)
; #define G_LDB(dst, b, h) do { _Pragma("unroll") for (int n = 0; n < 2; ++n) _Pragma("unroll") for (int k = 0; k < 2; ++k) dst[n][k] = *(const LAS bf16x8*)(lds + G_SB(b, h) + boff + n * 2048 + k * 1024); } while (0)
; #define G_WAIT_L(n) asm volatile("s_waitcnt lgkmcnt(" #n ")" ::: "memory")
; #define G_BAR __builtin_amdgcn_s_barrier()
; #define G_SCHED __builtin_amdgcn_sched_barrier(0)
;     ...
;             const char* a1 = cA + (size_t)(t + 1) * ckA;
;             const char* a2 = last ? nA : cA + (size_t)(t + 2) * ckA; const char* b2 = last ? nB : cB + (size_t)(t + 2) * kB;
;             const char* a3 = a2 + ckA; const char* b3 = b2 + kB;
;             G_LDB(B0, 0, 0); G_SCHED; G_LDA(At, 0, 0); G_STAGE(G_SA(1, 1), a1 + chA, cA0, qA);
;             G_WAIT_L(8); G_BAR; G_WAIT_L(0); G_MMA(0, 0, At, B0); G_BAR; G_SCHED;
;             G_LDB(B1, 0, 1); G_STAGE(G_SB(0, 0), b2, cB0, qB);
;             G_BAR; G_WAIT_L(0); G_MMA(0, 1, At, B1); G_BAR;
;             G_LDA(At, 0, 1); G_STAGE(G_SA(0, 0), a2, cA0, qA);
;             G_BAR; G_WAIT_L(0); G_MMA(1, 0, At, B0); G_BAR; G_SCHED;
.Ldbj_SSM2_in:
.LBB0_742:
	s_add_u32 s36, s2, s30
	s_addc_u32 s37, s3, s31
	s_add_u32 s19, s36, 0x100
	s_addc_u32 s35, s37, 0
	s_and_b64 s[4:5], s[26:27], exec
	s_cselect_b32 s34, s12, s19
	s_cselect_b32 s35, s13, s35
	s_add_u32 s4, s20, s30
	s_addc_u32 s5, s21, s31
	s_add_u32 s19, s4, 0x100
	s_addc_u32 s30, s5, 0
	s_add_i32 s44, 0, 0x10000
	v_add_u32_e32 v0, s44, v183
	ds_read_b128 v[56:59], v0
	ds_read_b128 v[60:63], v0 offset:1024
	ds_read_b128 v[144:147], v0 offset:2048
	ds_read_b128 v[148:151], v0 offset:3072
	s_and_b64 s[4:5], s[26:27], exec
	s_cselect_b32 s26, s16, s19
	s_cselect_b32 s27, s17, s30
	s_add_i32 s48, 0, 0x14000
	s_add_i32 s31, 0, 0x18000
	s_add_i32 s19, 0, 0x1c000
	s_add_i32 s49, s44, s38
	s_add_i32 s63, s48, s38
	s_add_i32 s30, s31, s38
	s_add_i32 s65, s19, s38
	s_add_i32 m0, s43, 0xc000
	s_add_i32 s45, s43, 0xe000
	s_add_i32 s66, s49, 0x2000
	s_add_i32 s62, s63, 0x2000
	s_add_i32 s67, s30, 0x2000
	s_add_i32 s64, s65, 0x2000
	v_lshl_add_u64 v[166:167], s[36:37], 0, v[160:161]
	s_mov_b64 s[4:5], 0x200080
	v_lshl_add_u64 v[180:181], v[166:167], 0, s[4:5]
	s_mov_b64 s[4:5], 0x300080
	ds_read_b128 v[152:155], v184
	ds_read_b128 v[156:159], v184 offset:1024
	ds_read_b128 v[162:165], v184 offset:2048
	ds_read_b128 v[172:175], v184 offset:3072
	ds_read_b128 v[176:179], v184 offset:4096
	ds_read_b128 v[196:199], v184 offset:5120
	ds_read_b128 v[200:203], v184 offset:6144
	ds_read_b128 v[204:207], v184 offset:7168
	global_load_lds_dwordx4 v[180:181], off
	v_lshl_add_u64 v[166:167], v[166:167], 0, s[4:5]
	s_mov_b32 m0, s45
	s_nop 0
	global_load_lds_dwordx4 v[166:167], off
	s_waitcnt lgkmcnt(8)
	s_barrier
	s_waitcnt lgkmcnt(0)
	v_mfma_f32_16x16x32_bf16 v[140:143], v[56:59], v[152:155], v[140:143]
	v_mfma_f32_16x16x32_bf16 v[136:139], v[144:147], v[152:155], v[136:139]
	v_mfma_f32_16x16x32_bf16 v[124:127], v[56:59], v[162:165], v[124:127]
	v_mfma_f32_16x16x32_bf16 v[120:123], v[144:147], v[162:165], v[120:123]
	v_mfma_f32_16x16x32_bf16 v[108:111], v[56:59], v[176:179], v[108:111]
	v_mfma_f32_16x16x32_bf16 v[104:107], v[144:147], v[176:179], v[104:107]
	v_mfma_f32_16x16x32_bf16 v[92:95], v[56:59], v[200:203], v[92:95]
	v_mfma_f32_16x16x32_bf16 v[88:91], v[144:147], v[200:203], v[88:91]
	v_mfma_f32_16x16x32_bf16 v[140:143], v[60:63], v[156:159], v[140:143]
	v_mfma_f32_16x16x32_bf16 v[136:139], v[148:151], v[156:159], v[136:139]
	v_mfma_f32_16x16x32_bf16 v[124:127], v[60:63], v[172:175], v[124:127]
	v_mfma_f32_16x16x32_bf16 v[120:123], v[148:151], v[172:175], v[120:123]
	v_mfma_f32_16x16x32_bf16 v[108:111], v[60:63], v[196:199], v[108:111]
	v_mfma_f32_16x16x32_bf16 v[104:107], v[148:151], v[196:199], v[104:107]
	v_mfma_f32_16x16x32_bf16 v[92:95], v[60:63], v[204:207], v[92:95]
	v_mfma_f32_16x16x32_bf16 v[88:91], v[148:151], v[204:207], v[88:91]
	s_barrier
	s_mov_b32 m0, s49
	v_add_u32_e32 v0, s48, v183
	v_lshl_add_u64 v[166:167], s[26:27], 0, v[2:3]
	ds_read_b128 v[208:211], v0
	ds_read_b128 v[212:215], v0 offset:1024
	ds_read_b128 v[216:219], v0 offset:2048
	ds_read_b128 v[220:223], v0 offset:3072
	global_load_lds_dwordx4 v[166:167], off
	v_lshl_add_u64 v[180:181], v[166:167], 0, s[92:93]
	s_mov_b32 m0, s66
	s_nop 0
	global_load_lds_dwordx4 v[180:181], off
	s_barrier
	s_waitcnt lgkmcnt(0)
	v_mfma_f32_16x16x32_bf16 v[132:135], v[208:211], v[152:155], v[132:135]
	v_mfma_f32_16x16x32_bf16 v[128:131], v[216:219], v[152:155], v[128:131]
	v_mfma_f32_16x16x32_bf16 v[116:119], v[208:211], v[162:165], v[116:119]
	v_mfma_f32_16x16x32_bf16 v[112:115], v[216:219], v[162:165], v[112:115]
	v_mfma_f32_16x16x32_bf16 v[100:103], v[208:211], v[176:179], v[100:103]
	v_mfma_f32_16x16x32_bf16 v[96:99], v[216:219], v[176:179], v[96:99]
	v_mfma_f32_16x16x32_bf16 v[84:87], v[208:211], v[200:203], v[84:87]
	v_mfma_f32_16x16x32_bf16 v[80:83], v[216:219], v[200:203], v[80:83]
	v_mfma_f32_16x16x32_bf16 v[132:135], v[212:215], v[156:159], v[132:135]
	v_mfma_f32_16x16x32_bf16 v[128:131], v[220:223], v[156:159], v[128:131]
	v_mfma_f32_16x16x32_bf16 v[116:119], v[212:215], v[172:175], v[116:119]
	v_mfma_f32_16x16x32_bf16 v[112:115], v[220:223], v[172:175], v[112:115]
	v_mfma_f32_16x16x32_bf16 v[100:103], v[212:215], v[196:199], v[100:103]
	v_mfma_f32_16x16x32_bf16 v[96:99], v[220:223], v[196:199], v[96:99]
	v_mfma_f32_16x16x32_bf16 v[84:87], v[212:215], v[204:207], v[84:87]
	v_mfma_f32_16x16x32_bf16 v[80:83], v[220:223], v[204:207], v[80:83]
	s_barrier
	s_mov_b32 m0, s43
	v_lshl_add_u64 v[180:181], s[34:35], 0, v[160:161]
	ds_read_b128 v[152:155], v184 offset:16384
	ds_read_b128 v[156:159], v184 offset:17408
	ds_read_b128 v[162:165], v184 offset:18432
	ds_read_b128 v[172:175], v184 offset:19456
	ds_read_b128 v[176:179], v184 offset:20480
	ds_read_b128 v[196:199], v184 offset:21504
	ds_read_b128 v[200:203], v184 offset:22528
	ds_read_b128 v[204:207], v184 offset:23552
	global_load_lds_dwordx4 v[180:181], off
	v_lshl_add_u64 v[224:225], v[180:181], 0, s[88:89]
	s_mov_b32 m0, s50
	s_nop 0
	global_load_lds_dwordx4 v[224:225], off
	s_barrier
	s_waitcnt lgkmcnt(0)
	v_mfma_f32_16x16x32_bf16 v[76:79], v[56:59], v[152:155], v[76:79]
	v_mfma_f32_16x16x32_bf16 v[72:75], v[144:147], v[152:155], v[72:75]
	v_mfma_f32_16x16x32_bf16 v[52:55], v[56:59], v[162:165], v[52:55]
	v_mfma_f32_16x16x32_bf16 v[48:51], v[144:147], v[162:165], v[48:51]
	v_mfma_f32_16x16x32_bf16 v[36:39], v[56:59], v[176:179], v[36:39]
	v_mfma_f32_16x16x32_bf16 v[32:35], v[144:147], v[176:179], v[32:35]
	v_mfma_f32_16x16x32_bf16 v[20:23], v[56:59], v[200:203], v[20:23]
	v_mfma_f32_16x16x32_bf16 v[16:19], v[144:147], v[200:203], v[16:19]
	v_mfma_f32_16x16x32_bf16 v[76:79], v[60:63], v[156:159], v[76:79]
	v_mfma_f32_16x16x32_bf16 v[72:75], v[148:151], v[156:159], v[72:75]
	v_mfma_f32_16x16x32_bf16 v[52:55], v[60:63], v[172:175], v[52:55]
	v_mfma_f32_16x16x32_bf16 v[48:51], v[148:151], v[172:175], v[48:51]
	v_mfma_f32_16x16x32_bf16 v[36:39], v[60:63], v[196:199], v[36:39]
	v_mfma_f32_16x16x32_bf16 v[32:35], v[148:151], v[196:199], v[32:35]
	v_mfma_f32_16x16x32_bf16 v[20:23], v[60:63], v[204:207], v[20:23]
	v_mfma_f32_16x16x32_bf16 v[16:19], v[148:151], v[204:207], v[16:19]
	s_barrier
; #define G_STAGE(bufoff, gbase, o0, h64) do { \
;         __builtin_amdgcn_global_load_lds((const unsigned*)((const char*)(gbase) + (o0)), (LAS unsigned*)(lds + (bufoff) + ldsw), 16, 0, 0); \
;         __builtin_amdgcn_global_load_lds((const unsigned*)((const char*)(gbase) + (h64) + (o0)), (LAS unsigned*)(lds + (bufoff) + ldsw + 8192), 16, 0, 0); } while (0)
; #define G_LDA(dst, b, h) do { _Pragma("unroll") for (int m = 0; m < 4; ++m) _Pragma("unroll") for (int k = 0; k < 2; ++k) dst[m][k] = *(const LAS bf16x8*)(lds + G_SA(b, h) + aoff + m * 2048 + k * 1024); } while (0)
; #define G_LDB(dst, b, h) do { _Pragma("unroll") for (int n = 0; n < 2; ++n) _Pragma("unroll") for (int k = 0; k < 2; ++k) dst[n][k] = *(const LAS bf16x8*)(lds + G_SB(b, h) + boff + n * 2048 + k * 1024); } while (0)
; #define G_WAIT_V(n) asm volatile("s_waitcnt vmcnt(" #n ")" ::: "memory")
; #define G_WAIT_L(n) asm volatile("s_waitcnt lgkmcnt(" #n ")" ::: "memory")
; #define G_BAR __builtin_amdgcn_s_barrier()
; #define G_SCHED __builtin_amdgcn_sched_barrier(0)
;     ...
;             G_STAGE(G_SB(0, 1), b2 + chB, cB0, qB);
;             G_WAIT_V(6); G_BAR; G_MMA(1, 1, At, B1); G_BAR;
;             G_LDB(B0, 1, 0); G_SCHED; G_LDA(At, 1, 0); G_STAGE(G_SA(0, 1), a2 + chA, cA0, qA);
;             G_WAIT_L(8); G_BAR; G_WAIT_L(0); G_MMA(0, 0, At, B0); G_BAR; G_SCHED;
;             G_LDB(B1, 1, 1); G_STAGE(G_SB(1, 0), b3, cB0, qB);
	s_mov_b32 m0, s63
	v_lshl_add_u64 v[56:57], v[166:167], 0, s[82:83]
	global_load_lds_dwordx4 v[56:57], off
	v_lshl_add_u64 v[56:57], v[166:167], 0, s[94:95]
	s_mov_b32 m0, s62
	s_nop 0
	global_load_lds_dwordx4 v[56:57], off
	s_waitcnt vmcnt(6)
	s_barrier
	v_mfma_f32_16x16x32_bf16 v[44:47], v[208:211], v[162:165], v[44:47]
	v_mfma_f32_16x16x32_bf16 v[40:43], v[216:219], v[162:165], v[40:43]
	v_mfma_f32_16x16x32_bf16 v[28:31], v[208:211], v[176:179], v[28:31]
	v_mfma_f32_16x16x32_bf16 v[24:27], v[216:219], v[176:179], v[24:27]
	v_mfma_f32_16x16x32_bf16 v[12:15], v[208:211], v[200:203], v[12:15]
	v_mfma_f32_16x16x32_bf16 v[8:11], v[216:219], v[200:203], v[8:11]
	v_mfma_f32_16x16x32_bf16 v[56:59], v[208:211], v[152:155], v[68:71]
	v_mfma_f32_16x16x32_bf16 v[60:63], v[216:219], v[152:155], v[64:67]
	v_mfma_f32_16x16x32_bf16 v[44:47], v[212:215], v[172:175], v[44:47]
	v_mfma_f32_16x16x32_bf16 v[40:43], v[220:223], v[172:175], v[40:43]
	v_mfma_f32_16x16x32_bf16 v[28:31], v[212:215], v[196:199], v[28:31]
	v_mfma_f32_16x16x32_bf16 v[24:27], v[220:223], v[196:199], v[24:27]
	v_mfma_f32_16x16x32_bf16 v[12:15], v[212:215], v[204:207], v[12:15]
	v_mfma_f32_16x16x32_bf16 v[8:11], v[220:223], v[204:207], v[8:11]
	v_mfma_f32_16x16x32_bf16 v[56:59], v[212:215], v[156:159], v[56:59]
	v_mfma_f32_16x16x32_bf16 v[60:63], v[220:223], v[156:159], v[60:63]
	s_barrier
	v_add_u32_e32 v0, s31, v183
	ds_read_b128 v[64:67], v0
	ds_read_b128 v[68:71], v0 offset:1024
	ds_read_b128 v[144:147], v0 offset:2048
	ds_read_b128 v[148:151], v0 offset:3072
	s_mov_b32 m0, s51
	v_lshl_add_u64 v[208:209], v[180:181], 0, s[86:87]
	ds_read_b128 v[152:155], v184 offset:32768
	ds_read_b128 v[156:159], v184 offset:33792
	ds_read_b128 v[162:165], v184 offset:34816
	ds_read_b128 v[172:175], v184 offset:35840
	ds_read_b128 v[176:179], v184 offset:36864
	ds_read_b128 v[196:199], v184 offset:37888
	ds_read_b128 v[200:203], v184 offset:38912
	ds_read_b128 v[204:207], v184 offset:39936
	global_load_lds_dwordx4 v[208:209], off
	v_lshl_add_u64 v[208:209], v[180:181], 0, s[96:97]
	s_mov_b32 m0, s52
	s_nop 0
	global_load_lds_dwordx4 v[208:209], off
	s_waitcnt lgkmcnt(8)
	s_barrier
	s_waitcnt lgkmcnt(0)
	v_mfma_f32_16x16x32_bf16 v[140:143], v[64:67], v[152:155], v[140:143]
	v_mfma_f32_16x16x32_bf16 v[136:139], v[144:147], v[152:155], v[136:139]
	v_mfma_f32_16x16x32_bf16 v[124:127], v[64:67], v[162:165], v[124:127]
	v_mfma_f32_16x16x32_bf16 v[120:123], v[144:147], v[162:165], v[120:123]
	v_mfma_f32_16x16x32_bf16 v[108:111], v[64:67], v[176:179], v[108:111]
	v_mfma_f32_16x16x32_bf16 v[104:107], v[144:147], v[176:179], v[104:107]
	v_mfma_f32_16x16x32_bf16 v[92:95], v[64:67], v[200:203], v[92:95]
	v_mfma_f32_16x16x32_bf16 v[88:91], v[144:147], v[200:203], v[88:91]
	v_mfma_f32_16x16x32_bf16 v[140:143], v[68:71], v[156:159], v[140:143]
	v_mfma_f32_16x16x32_bf16 v[136:139], v[148:151], v[156:159], v[136:139]
	v_mfma_f32_16x16x32_bf16 v[124:127], v[68:71], v[172:175], v[124:127]
	v_mfma_f32_16x16x32_bf16 v[120:123], v[148:151], v[172:175], v[120:123]
	v_mfma_f32_16x16x32_bf16 v[108:111], v[68:71], v[196:199], v[108:111]
	v_mfma_f32_16x16x32_bf16 v[104:107], v[148:151], v[196:199], v[104:107]
	v_mfma_f32_16x16x32_bf16 v[92:95], v[68:71], v[204:207], v[92:95]
	v_mfma_f32_16x16x32_bf16 v[88:91], v[148:151], v[204:207], v[88:91]
	s_barrier
	s_mov_b32 m0, s30
	v_add_u32_e32 v0, s19, v183
	v_lshl_add_u64 v[224:225], v[166:167], 0, s[46:47]
	ds_read_b128 v[208:211], v0
	ds_read_b128 v[212:215], v0 offset:1024
	ds_read_b128 v[216:219], v0 offset:2048
	ds_read_b128 v[220:223], v0 offset:3072
	global_load_lds_dwordx4 v[224:225], off
	v_lshl_add_u64 v[224:225], v[166:167], 0, s[70:71]
	s_mov_b32 m0, s67
	s_nop 0
	global_load_lds_dwordx4 v[224:225], off
	s_barrier
; #define G_STAGE(bufoff, gbase, o0, h64) do { \
;         __builtin_amdgcn_global_load_lds((const unsigned*)((const char*)(gbase) + (o0)), (LAS unsigned*)(lds + (bufoff) + ldsw), 16, 0, 0); \
;         __builtin_amdgcn_global_load_lds((const unsigned*)((const char*)(gbase) + (h64) + (o0)), (LAS unsigned*)(lds + (bufoff) + ldsw + 8192), 16, 0, 0); } while (0)
; #define G_LDA(dst, b, h) do { _Pragma("unroll") for (int m = 0; m < 4; ++m) _Pragma("unroll") for (int k = 0; k < 2; ++k) dst[m][k] = *(const LAS bf16x8*)(lds + G_SA(b, h) + aoff + m * 2048 + k * 1024); } while (0)
; #define G_LDB(dst, b, h) do { _Pragma("unroll") for (int n = 0; n < 2; ++n) _Pragma("unroll") for (int k = 0; k < 2; ++k) dst[n][k] = *(const LAS bf16x8*)(lds + G_SB(b, h) + boff + n * 2048 + k * 1024); } while (0)
; #define G_WAIT_V(n) asm volatile("s_waitcnt vmcnt(" #n ")" ::: "memory")
; #define G_WAIT_L(n) asm volatile("s_waitcnt lgkmcnt(" #n ")" ::: "memory")
; #define G_BAR __builtin_amdgcn_s_barrier()
; #define G_SCHED __builtin_amdgcn_sched_barrier(0)
;     ...
;             G_WAIT_L(8); G_BAR; G_WAIT_L(0); G_MMA(0, 0, At, B0); G_BAR; G_SCHED;
;             G_LDB(B1, 1, 1); G_STAGE(G_SB(1, 0), b3, cB0, qB);
;             G_BAR; G_WAIT_L(0); G_MMA(0, 1, At, B1); G_BAR;
;             G_LDA(At, 1, 1); G_STAGE(G_SA(1, 0), a3, cA0, qA);
;             G_BAR; G_WAIT_L(0); G_MMA(1, 0, At, B0); G_BAR; G_SCHED;
;             G_STAGE(G_SB(1, 1), b3 + chB, cB0, qB);
;             G_WAIT_V(6); G_BAR; G_MMA(1, 1, At, B1); G_BAR;
;         }
	s_waitcnt lgkmcnt(0)
	v_mfma_f32_16x16x32_bf16 v[132:135], v[208:211], v[152:155], v[132:135]
	v_mfma_f32_16x16x32_bf16 v[128:131], v[216:219], v[152:155], v[128:131]
	v_mfma_f32_16x16x32_bf16 v[116:119], v[208:211], v[162:165], v[116:119]
	v_mfma_f32_16x16x32_bf16 v[112:115], v[216:219], v[162:165], v[112:115]
	v_mfma_f32_16x16x32_bf16 v[100:103], v[208:211], v[176:179], v[100:103]
	v_mfma_f32_16x16x32_bf16 v[96:99], v[216:219], v[176:179], v[96:99]
	v_mfma_f32_16x16x32_bf16 v[84:87], v[208:211], v[200:203], v[84:87]
	v_mfma_f32_16x16x32_bf16 v[80:83], v[216:219], v[200:203], v[80:83]
	v_mfma_f32_16x16x32_bf16 v[132:135], v[212:215], v[156:159], v[132:135]
	v_mfma_f32_16x16x32_bf16 v[128:131], v[220:223], v[156:159], v[128:131]
	v_mfma_f32_16x16x32_bf16 v[116:119], v[212:215], v[172:175], v[116:119]
	v_mfma_f32_16x16x32_bf16 v[112:115], v[220:223], v[172:175], v[112:115]
	v_mfma_f32_16x16x32_bf16 v[100:103], v[212:215], v[196:199], v[100:103]
	v_mfma_f32_16x16x32_bf16 v[96:99], v[220:223], v[196:199], v[96:99]
	v_mfma_f32_16x16x32_bf16 v[84:87], v[212:215], v[204:207], v[84:87]
	v_mfma_f32_16x16x32_bf16 v[80:83], v[220:223], v[204:207], v[80:83]
	s_barrier
	s_mov_b32 m0, s53
	v_lshl_add_u64 v[224:225], v[180:181], 0, s[46:47]
	ds_read_b128 v[152:155], v184 offset:49152
	ds_read_b128 v[156:159], v184 offset:50176
	ds_read_b128 v[162:165], v184 offset:51200
	ds_read_b128 v[172:175], v184 offset:52224
	ds_read_b128 v[176:179], v184 offset:53248
	ds_read_b128 v[196:199], v184 offset:54272
	ds_read_b128 v[200:203], v184 offset:55296
	ds_read_b128 v[204:207], v184 offset:56320
	global_load_lds_dwordx4 v[224:225], off
	v_lshl_add_u64 v[180:181], v[180:181], 0, s[68:69]
	s_mov_b32 m0, s54
	s_nop 0
	global_load_lds_dwordx4 v[180:181], off
	s_barrier
	s_waitcnt lgkmcnt(0)
	v_mfma_f32_16x16x32_bf16 v[76:79], v[64:67], v[152:155], v[76:79]
	v_mfma_f32_16x16x32_bf16 v[72:75], v[144:147], v[152:155], v[72:75]
	v_mfma_f32_16x16x32_bf16 v[52:55], v[64:67], v[162:165], v[52:55]
	v_mfma_f32_16x16x32_bf16 v[48:51], v[144:147], v[162:165], v[48:51]
	v_mfma_f32_16x16x32_bf16 v[36:39], v[64:67], v[176:179], v[36:39]
	v_mfma_f32_16x16x32_bf16 v[32:35], v[144:147], v[176:179], v[32:35]
	v_mfma_f32_16x16x32_bf16 v[20:23], v[64:67], v[200:203], v[20:23]
	v_mfma_f32_16x16x32_bf16 v[16:19], v[144:147], v[200:203], v[16:19]
	v_mfma_f32_16x16x32_bf16 v[76:79], v[68:71], v[156:159], v[76:79]
	v_mfma_f32_16x16x32_bf16 v[72:75], v[148:151], v[156:159], v[72:75]
	v_mfma_f32_16x16x32_bf16 v[52:55], v[68:71], v[172:175], v[52:55]
	v_mfma_f32_16x16x32_bf16 v[48:51], v[148:151], v[172:175], v[48:51]
	v_mfma_f32_16x16x32_bf16 v[36:39], v[68:71], v[196:199], v[36:39]
	v_mfma_f32_16x16x32_bf16 v[32:35], v[148:151], v[196:199], v[32:35]
	v_mfma_f32_16x16x32_bf16 v[20:23], v[68:71], v[204:207], v[20:23]
	v_mfma_f32_16x16x32_bf16 v[16:19], v[148:151], v[204:207], v[16:19]
	s_barrier
	s_mov_b32 m0, s65
	v_lshl_add_u64 v[64:65], v[166:167], 0, s[84:85]
	global_load_lds_dwordx4 v[64:65], off
	v_lshl_add_u64 v[64:65], v[166:167], 0, s[28:29]
	s_mov_b32 m0, s64
	s_nop 0
	global_load_lds_dwordx4 v[64:65], off
	s_waitcnt vmcnt(6)
	s_barrier
	v_mfma_f32_16x16x32_bf16 v[56:59], v[208:211], v[152:155], v[56:59]
	v_mfma_f32_16x16x32_bf16 v[68:71], v[212:215], v[156:159], v[56:59]
	v_mfma_f32_16x16x32_bf16 v[56:59], v[216:219], v[152:155], v[60:63]
	v_mfma_f32_16x16x32_bf16 v[44:47], v[208:211], v[162:165], v[44:47]
	v_mfma_f32_16x16x32_bf16 v[40:43], v[216:219], v[162:165], v[40:43]
	v_mfma_f32_16x16x32_bf16 v[28:31], v[208:211], v[176:179], v[28:31]
	v_mfma_f32_16x16x32_bf16 v[24:27], v[216:219], v[176:179], v[24:27]
	v_mfma_f32_16x16x32_bf16 v[12:15], v[208:211], v[200:203], v[12:15]
	v_mfma_f32_16x16x32_bf16 v[8:11], v[216:219], v[200:203], v[8:11]
	v_mfma_f32_16x16x32_bf16 v[64:67], v[220:223], v[156:159], v[56:59]
	v_mfma_f32_16x16x32_bf16 v[44:47], v[212:215], v[172:175], v[44:47]
	v_mfma_f32_16x16x32_bf16 v[40:43], v[220:223], v[172:175], v[40:43]
	v_mfma_f32_16x16x32_bf16 v[28:31], v[212:215], v[196:199], v[28:31]
	v_mfma_f32_16x16x32_bf16 v[24:27], v[220:223], v[196:199], v[24:27]
	v_mfma_f32_16x16x32_bf16 v[12:15], v[212:215], v[204:207], v[12:15]
	v_mfma_f32_16x16x32_bf16 v[8:11], v[220:223], v[204:207], v[8:11]
	s_andn2_b64 vcc, exec, s[24:25]
	s_mov_b64 s[26:27], -1
	s_mov_b64 s[24:25], 0
	s_mov_b64 s[30:31], 0x100
	s_cbranch_vccz .Ldb_SSM2_cont
	v_readfirstlane_b32 s101, v186
	s_cmpk_gt_u32 s101, 0xff
	s_cbranch_scc1 .Ldb_SSM2_exit
	s_barrier
	s_branch .Ldb_SSM2_exit

; #define G_STAGE(bufoff, gbase, o0, h64) do { \
;         __builtin_amdgcn_global_load_lds((const unsigned*)((const char*)(gbase) + (o0)), (LAS unsigned*)(lds + (bufoff) + ldsw), 16, 0, 0); \
;         __builtin_amdgcn_global_load_lds((const unsigned*)((const char*)(gbase) + (h64) + (o0)), (LAS unsigned*)(lds + (bufoff) + ldsw + 8192), 16, 0, 0); } while (0)
; #define G_LDA(dst, b, h) do { _Pragma("unroll") for (int m = 0; m < 4; ++m) _Pragma("unroll") for (int k = 0; k < 2; ++k) dst[m][k] = *(const LAS bf16x8*)(lds + G_SA(b, h) + aoff + m * 2048 + k * 1024); } while (0)
; #define G_LDB(dst, b, h) do { _Pragma("unroll") for (int n = 0; n < 2; ++n) _Pragma("unroll") for (int k = 0; k < 2; ++k) dst[n][k] = *(const LAS bf16x8*)(lds + G_SB(b, h) + boff + n * 2048 + k * 1024); } while (0)
; #define G_WAIT_L(n) asm volatile("s_waitcnt lgkmcnt(" #n ")" ::: "memory")
; #define G_BAR __builtin_amdgcn_s_barrier()
; #define G_SCHED __builtin_amdgcn_sched_barrier(0)
;     ...
;         for (int t = 0; t < nt; t += 2) {
;             const bool last = (t == nt - 2);
;             const char* a1 = cA + (size_t)(t + 1) * ckA;
;             const char* a2 = last ? nA : cA + (size_t)(t + 2) * ckA; const char* b2 = last ? nB : cB + (size_t)(t + 2) * kB;
;             const char* a3 = a2 + ckA; const char* b3 = b2 + kB;
;             G_LDB(B0, 0, 0); G_SCHED; G_LDA(At, 0, 0); G_STAGE(G_SA(1, 1), a1 + chA, cA0, qA);
;             G_WAIT_L(8); G_BAR; G_WAIT_L(0); G_MMA(0, 0, At, B0); G_BAR; G_SCHED;
;             G_LDB(B1, 0, 1); G_STAGE(G_SB(0, 0), b2, cB0, qB);
;             G_BAR; G_WAIT_L(0); G_MMA(0, 1, At, B1); G_BAR;
;             G_LDA(At, 0, 1); G_STAGE(G_SA(0, 0), a2, cA0, qA);
;             G_BAR; G_WAIT_L(0); G_MMA(1, 0, At, B0); G_BAR; G_SCHED;
.Ldbj_GLU_in:
.LBB0_804:
	s_add_i32 s40, 0, 0x10000
	v_add_u32_e32 v0, s40, v196
	ds_read_b128 v[112:115], v0
	ds_read_b128 v[124:127], v0 offset:1024
	ds_read_b128 v[136:139], v0 offset:2048
	ds_read_b128 v[148:151], v0 offset:3072
	s_cmp_eq_u32 s19, 4
	s_cselect_b32 s5, s15, s3
	s_cselect_b32 s4, s14, s2
	s_cselect_b32 s37, s17, s18
	s_cselect_b32 s36, s16, s13
	s_mov_b32 s38, 0xffc01000
	v_lshl_add_u64 v[184:185], s[2:3], 0, v[166:167]
	s_mov_b32 s39, -1
	v_lshl_add_u64 v[206:207], v[184:185], 0, s[38:39]
	s_mov_b32 s38, 0xffc01800
	s_add_i32 m0, s24, 0xc000
	s_mov_b32 s39, -1
	ds_read_b128 v[152:155], v197
	ds_read_b128 v[156:159], v197 offset:1024
	ds_read_b128 v[160:163], v197 offset:2048
	ds_read_b128 v[172:175], v197 offset:3072
	ds_read_b128 v[176:179], v197 offset:4096
	ds_read_b128 v[180:183], v197 offset:5120
	ds_read_b128 v[198:201], v197 offset:6144
	ds_read_b128 v[202:205], v197 offset:7168
	global_load_lds_dwordx4 v[206:207], off
	v_lshl_add_u64 v[184:185], v[184:185], 0, s[38:39]
	s_add_i32 m0, s24, 0xe000
	s_nop 0
	global_load_lds_dwordx4 v[184:185], off
	s_waitcnt lgkmcnt(8)
	s_barrier
	s_waitcnt lgkmcnt(0)
	v_mfma_f32_16x16x32_bf16 v[144:147], v[112:115], v[152:155], v[144:147]
	v_mfma_f32_16x16x32_bf16 v[140:143], v[136:139], v[152:155], v[140:143]
	v_mfma_f32_16x16x32_bf16 v[120:123], v[112:115], v[160:163], v[120:123]
	v_mfma_f32_16x16x32_bf16 v[116:119], v[136:139], v[160:163], v[116:119]
	v_mfma_f32_16x16x32_bf16 v[100:103], v[112:115], v[176:179], v[100:103]
	v_mfma_f32_16x16x32_bf16 v[96:99], v[136:139], v[176:179], v[96:99]
	v_mfma_f32_16x16x32_bf16 v[84:87], v[112:115], v[198:201], v[84:87]
	v_mfma_f32_16x16x32_bf16 v[80:83], v[136:139], v[198:201], v[80:83]
	v_mfma_f32_16x16x32_bf16 v[144:147], v[124:127], v[156:159], v[144:147]
	v_mfma_f32_16x16x32_bf16 v[140:143], v[148:151], v[156:159], v[140:143]
	v_mfma_f32_16x16x32_bf16 v[120:123], v[124:127], v[172:175], v[120:123]
	v_mfma_f32_16x16x32_bf16 v[116:119], v[148:151], v[172:175], v[116:119]
	v_mfma_f32_16x16x32_bf16 v[100:103], v[124:127], v[180:183], v[100:103]
	v_mfma_f32_16x16x32_bf16 v[96:99], v[148:151], v[180:183], v[96:99]
	v_mfma_f32_16x16x32_bf16 v[84:87], v[124:127], v[202:205], v[84:87]
	v_mfma_f32_16x16x32_bf16 v[80:83], v[148:151], v[202:205], v[80:83]
	s_barrier
	s_add_i32 s38, 0, 0x14000
	v_lshl_add_u64 v[184:185], s[36:37], 0, v[2:3]
	s_add_i32 s36, s40, s21
	v_add_u32_e32 v0, s38, v196
	s_mov_b32 m0, s36
	ds_read_b128 v[206:209], v0
	ds_read_b128 v[210:213], v0 offset:1024
	ds_read_b128 v[214:217], v0 offset:2048
	ds_read_b128 v[218:221], v0 offset:3072
	global_load_lds_dwordx4 v[184:185], off
	v_lshl_add_u64 v[222:223], v[184:185], 0, s[50:51]
	s_add_i32 m0, s36, 0x2000
	s_nop 0
	global_load_lds_dwordx4 v[222:223], off
	s_barrier
	s_waitcnt lgkmcnt(0)
	v_mfma_f32_16x16x32_bf16 v[132:135], v[206:209], v[152:155], v[132:135]
	v_mfma_f32_16x16x32_bf16 v[128:131], v[214:217], v[152:155], v[128:131]
	v_mfma_f32_16x16x32_bf16 v[108:111], v[206:209], v[160:163], v[108:111]
	v_mfma_f32_16x16x32_bf16 v[104:107], v[214:217], v[160:163], v[104:107]
	v_mfma_f32_16x16x32_bf16 v[92:95], v[206:209], v[176:179], v[92:95]
	v_mfma_f32_16x16x32_bf16 v[88:91], v[214:217], v[176:179], v[88:91]
	v_mfma_f32_16x16x32_bf16 v[76:79], v[206:209], v[198:201], v[76:79]
	v_mfma_f32_16x16x32_bf16 v[72:75], v[214:217], v[198:201], v[72:75]
	v_mfma_f32_16x16x32_bf16 v[132:135], v[210:213], v[156:159], v[132:135]
	v_mfma_f32_16x16x32_bf16 v[128:131], v[218:221], v[156:159], v[128:131]
	v_mfma_f32_16x16x32_bf16 v[108:111], v[210:213], v[172:175], v[108:111]
	v_mfma_f32_16x16x32_bf16 v[104:107], v[218:221], v[172:175], v[104:107]
	v_mfma_f32_16x16x32_bf16 v[92:95], v[210:213], v[180:183], v[92:95]
	v_mfma_f32_16x16x32_bf16 v[88:91], v[218:221], v[180:183], v[88:91]
	v_mfma_f32_16x16x32_bf16 v[76:79], v[210:213], v[202:205], v[76:79]
	v_mfma_f32_16x16x32_bf16 v[72:75], v[218:221], v[202:205], v[72:75]
	s_barrier
	s_mov_b32 m0, s24
	v_lshl_add_u64 v[222:223], s[4:5], 0, v[164:165]
	ds_read_b128 v[152:155], v197 offset:16384
	ds_read_b128 v[156:159], v197 offset:17408
	ds_read_b128 v[160:163], v197 offset:18432
	ds_read_b128 v[172:175], v197 offset:19456
	ds_read_b128 v[176:179], v197 offset:20480
	ds_read_b128 v[180:183], v197 offset:21504
	ds_read_b128 v[198:201], v197 offset:22528
	ds_read_b128 v[202:205], v197 offset:23552
	global_load_lds_dwordx4 v[222:223], off
	v_lshl_add_u64 v[224:225], v[222:223], 0, s[70:71]
	s_mov_b32 m0, s25
	s_nop 0
	global_load_lds_dwordx4 v[224:225], off
	s_barrier
	s_waitcnt lgkmcnt(0)
	v_mfma_f32_16x16x32_bf16 v[68:71], v[112:115], v[152:155], v[68:71]
	v_mfma_f32_16x16x32_bf16 v[64:67], v[136:139], v[152:155], v[64:67]
	v_mfma_f32_16x16x32_bf16 v[52:55], v[112:115], v[160:163], v[52:55]
	v_mfma_f32_16x16x32_bf16 v[48:51], v[136:139], v[160:163], v[48:51]
	v_mfma_f32_16x16x32_bf16 v[36:39], v[112:115], v[176:179], v[36:39]
	v_mfma_f32_16x16x32_bf16 v[32:35], v[136:139], v[176:179], v[32:35]
	v_mfma_f32_16x16x32_bf16 v[20:23], v[112:115], v[198:201], v[20:23]
	v_mfma_f32_16x16x32_bf16 v[16:19], v[136:139], v[198:201], v[16:19]
	v_mfma_f32_16x16x32_bf16 v[68:71], v[124:127], v[156:159], v[68:71]
	v_mfma_f32_16x16x32_bf16 v[64:67], v[148:151], v[156:159], v[64:67]
	v_mfma_f32_16x16x32_bf16 v[52:55], v[124:127], v[172:175], v[52:55]
	v_mfma_f32_16x16x32_bf16 v[48:51], v[148:151], v[172:175], v[48:51]
	v_mfma_f32_16x16x32_bf16 v[36:39], v[124:127], v[180:183], v[36:39]
	v_mfma_f32_16x16x32_bf16 v[32:35], v[148:151], v[180:183], v[32:35]
	v_mfma_f32_16x16x32_bf16 v[20:23], v[124:127], v[202:205], v[20:23]
	v_mfma_f32_16x16x32_bf16 v[16:19], v[148:151], v[202:205], v[16:19]
	s_barrier
; #define G_STAGE(bufoff, gbase, o0, h64) do { \
;         __builtin_amdgcn_global_load_lds((const unsigned*)((const char*)(gbase) + (o0)), (LAS unsigned*)(lds + (bufoff) + ldsw), 16, 0, 0); \
;         __builtin_amdgcn_global_load_lds((const unsigned*)((const char*)(gbase) + (h64) + (o0)), (LAS unsigned*)(lds + (bufoff) + ldsw + 8192), 16, 0, 0); } while (0)
; #define G_LDA(dst, b, h) do { _Pragma("unroll") for (int m = 0; m < 4; ++m) _Pragma("unroll") for (int k = 0; k < 2; ++k) dst[m][k] = *(const LAS bf16x8*)(lds + G_SA(b, h) + aoff + m * 2048 + k * 1024); } while (0)
; #define G_LDB(dst, b, h) do { _Pragma("unroll") for (int n = 0; n < 2; ++n) _Pragma("unroll") for (int k = 0; k < 2; ++k) dst[n][k] = *(const LAS bf16x8*)(lds + G_SB(b, h) + boff + n * 2048 + k * 1024); } while (0)
; #define G_WAIT_V(n) asm volatile("s_waitcnt vmcnt(" #n ")" ::: "memory")
; #define G_WAIT_L(n) asm volatile("s_waitcnt lgkmcnt(" #n ")" ::: "memory")
; #define G_BAR __builtin_amdgcn_s_barrier()
; #define G_SCHED __builtin_amdgcn_sched_barrier(0)
;     ...
;             G_STAGE(G_SB(0, 1), b2 + chB, cB0, qB);
;             G_WAIT_V(6); G_BAR; G_MMA(1, 1, At, B1); G_BAR;
;             G_LDB(B0, 1, 0); G_SCHED; G_LDA(At, 1, 0); G_STAGE(G_SA(0, 1), a2 + chA, cA0, qA);
;             G_WAIT_L(8); G_BAR; G_WAIT_L(0); G_MMA(0, 0, At, B0); G_BAR; G_SCHED;
;             G_LDB(B1, 1, 1); G_STAGE(G_SB(1, 0), b3, cB0, qB);
	s_add_i32 s4, s38, s21
	v_lshl_add_u64 v[112:113], v[184:185], 0, s[0:1]
	s_mov_b32 m0, s4
	s_nop 0
	global_load_lds_dwordx4 v[112:113], off
	v_lshl_add_u64 v[112:113], v[184:185], 0, s[52:53]
	s_add_i32 m0, s4, 0x2000
	s_nop 0
	global_load_lds_dwordx4 v[112:113], off
	s_waitcnt vmcnt(6)
	s_barrier
	v_mfma_f32_16x16x32_bf16 v[60:63], v[206:209], v[152:155], v[60:63]
	v_mfma_f32_16x16x32_bf16 v[56:59], v[214:217], v[152:155], v[56:59]
	v_mfma_f32_16x16x32_bf16 v[44:47], v[206:209], v[160:163], v[44:47]
	v_mfma_f32_16x16x32_bf16 v[40:43], v[214:217], v[160:163], v[40:43]
	v_mfma_f32_16x16x32_bf16 v[28:31], v[206:209], v[176:179], v[28:31]
	v_mfma_f32_16x16x32_bf16 v[24:27], v[214:217], v[176:179], v[24:27]
	v_mfma_f32_16x16x32_bf16 v[12:15], v[206:209], v[198:201], v[12:15]
	v_mfma_f32_16x16x32_bf16 v[8:11], v[214:217], v[198:201], v[8:11]
	v_mfma_f32_16x16x32_bf16 v[60:63], v[210:213], v[156:159], v[60:63]
	v_mfma_f32_16x16x32_bf16 v[56:59], v[218:221], v[156:159], v[56:59]
	v_mfma_f32_16x16x32_bf16 v[44:47], v[210:213], v[172:175], v[44:47]
	v_mfma_f32_16x16x32_bf16 v[40:43], v[218:221], v[172:175], v[40:43]
	v_mfma_f32_16x16x32_bf16 v[28:31], v[210:213], v[180:183], v[28:31]
	v_mfma_f32_16x16x32_bf16 v[24:27], v[218:221], v[180:183], v[24:27]
	v_mfma_f32_16x16x32_bf16 v[12:15], v[210:213], v[202:205], v[12:15]
	v_mfma_f32_16x16x32_bf16 v[8:11], v[218:221], v[202:205], v[8:11]
	s_barrier
	s_add_i32 s4, 0, 0x18000
	v_add_u32_e32 v0, s4, v196
	ds_read_b128 v[112:115], v0
	ds_read_b128 v[124:127], v0 offset:1024
	ds_read_b128 v[136:139], v0 offset:2048
	ds_read_b128 v[148:151], v0 offset:3072
	s_mov_b32 m0, s26
	v_lshl_add_u64 v[206:207], v[222:223], 0, s[80:81]
	ds_read_b128 v[152:155], v197 offset:32768
	ds_read_b128 v[156:159], v197 offset:33792
	ds_read_b128 v[160:163], v197 offset:34816
	ds_read_b128 v[172:175], v197 offset:35840
	ds_read_b128 v[176:179], v197 offset:36864
	ds_read_b128 v[180:183], v197 offset:37888
	ds_read_b128 v[198:201], v197 offset:38912
	ds_read_b128 v[202:205], v197 offset:39936
	global_load_lds_dwordx4 v[206:207], off
	v_lshl_add_u64 v[206:207], v[222:223], 0, s[82:83]
	s_mov_b32 m0, s27
	s_nop 0
	global_load_lds_dwordx4 v[206:207], off
	s_waitcnt lgkmcnt(8)
	s_barrier
	s_waitcnt lgkmcnt(0)
	v_mfma_f32_16x16x32_bf16 v[144:147], v[112:115], v[152:155], v[144:147]
	v_mfma_f32_16x16x32_bf16 v[140:143], v[136:139], v[152:155], v[140:143]
	v_mfma_f32_16x16x32_bf16 v[120:123], v[112:115], v[160:163], v[120:123]
	v_mfma_f32_16x16x32_bf16 v[116:119], v[136:139], v[160:163], v[116:119]
	v_mfma_f32_16x16x32_bf16 v[100:103], v[112:115], v[176:179], v[100:103]
	v_mfma_f32_16x16x32_bf16 v[96:99], v[136:139], v[176:179], v[96:99]
	v_mfma_f32_16x16x32_bf16 v[84:87], v[112:115], v[198:201], v[84:87]
	v_mfma_f32_16x16x32_bf16 v[80:83], v[136:139], v[198:201], v[80:83]
	v_mfma_f32_16x16x32_bf16 v[144:147], v[124:127], v[156:159], v[144:147]
	v_mfma_f32_16x16x32_bf16 v[140:143], v[148:151], v[156:159], v[140:143]
	v_mfma_f32_16x16x32_bf16 v[120:123], v[124:127], v[172:175], v[120:123]
	v_mfma_f32_16x16x32_bf16 v[116:119], v[148:151], v[172:175], v[116:119]
	v_mfma_f32_16x16x32_bf16 v[100:103], v[124:127], v[180:183], v[100:103]
	v_mfma_f32_16x16x32_bf16 v[96:99], v[148:151], v[180:183], v[96:99]
	v_mfma_f32_16x16x32_bf16 v[84:87], v[124:127], v[202:205], v[84:87]
	v_mfma_f32_16x16x32_bf16 v[80:83], v[148:151], v[202:205], v[80:83]
	s_barrier
	s_add_i32 s5, 0, 0x1c000
	s_add_i32 s4, s4, s21
	v_add_u32_e32 v0, s5, v196
	v_lshl_add_u64 v[224:225], v[184:185], 0, s[46:47]
	s_mov_b32 m0, s4
	ds_read_b128 v[206:209], v0
	ds_read_b128 v[210:213], v0 offset:1024
	ds_read_b128 v[214:217], v0 offset:2048
	ds_read_b128 v[218:221], v0 offset:3072
	global_load_lds_dwordx4 v[224:225], off
	v_lshl_add_u64 v[224:225], v[184:185], 0, s[54:55]
	s_add_i32 m0, s4, 0x2000
	s_nop 0
	global_load_lds_dwordx4 v[224:225], off
	s_barrier
; #define G_STAGE(bufoff, gbase, o0, h64) do { \
;         __builtin_amdgcn_global_load_lds((const unsigned*)((const char*)(gbase) + (o0)), (LAS unsigned*)(lds + (bufoff) + ldsw), 16, 0, 0); \
;         __builtin_amdgcn_global_load_lds((const unsigned*)((const char*)(gbase) + (h64) + (o0)), (LAS unsigned*)(lds + (bufoff) + ldsw + 8192), 16, 0, 0); } while (0)
; #define G_LDA(dst, b, h) do { _Pragma("unroll") for (int m = 0; m < 4; ++m) _Pragma("unroll") for (int k = 0; k < 2; ++k) dst[m][k] = *(const LAS bf16x8*)(lds + G_SA(b, h) + aoff + m * 2048 + k * 1024); } while (0)
; #define G_LDB(dst, b, h) do { _Pragma("unroll") for (int n = 0; n < 2; ++n) _Pragma("unroll") for (int k = 0; k < 2; ++k) dst[n][k] = *(const LAS bf16x8*)(lds + G_SB(b, h) + boff + n * 2048 + k * 1024); } while (0)
; #define G_WAIT_V(n) asm volatile("s_waitcnt vmcnt(" #n ")" ::: "memory")
; #define G_WAIT_L(n) asm volatile("s_waitcnt lgkmcnt(" #n ")" ::: "memory")
; #define G_BAR __builtin_amdgcn_s_barrier()
; #define G_SCHED __builtin_amdgcn_sched_barrier(0)
;     ...
;             G_WAIT_L(8); G_BAR; G_WAIT_L(0); G_MMA(0, 0, At, B0); G_BAR; G_SCHED;
;             G_LDB(B1, 1, 1); G_STAGE(G_SB(1, 0), b3, cB0, qB);
;             G_BAR; G_WAIT_L(0); G_MMA(0, 1, At, B1); G_BAR;
;             G_LDA(At, 1, 1); G_STAGE(G_SA(1, 0), a3, cA0, qA);
;             G_BAR; G_WAIT_L(0); G_MMA(1, 0, At, B0); G_BAR; G_SCHED;
;             G_STAGE(G_SB(1, 1), b3 + chB, cB0, qB);
;             G_WAIT_V(6); G_BAR; G_MMA(1, 1, At, B1); G_BAR;
;         }
	s_waitcnt lgkmcnt(0)
	v_mfma_f32_16x16x32_bf16 v[132:135], v[206:209], v[152:155], v[132:135]
	v_mfma_f32_16x16x32_bf16 v[128:131], v[214:217], v[152:155], v[128:131]
	v_mfma_f32_16x16x32_bf16 v[108:111], v[206:209], v[160:163], v[108:111]
	v_mfma_f32_16x16x32_bf16 v[104:107], v[214:217], v[160:163], v[104:107]
	v_mfma_f32_16x16x32_bf16 v[92:95], v[206:209], v[176:179], v[92:95]
	v_mfma_f32_16x16x32_bf16 v[88:91], v[214:217], v[176:179], v[88:91]
	v_mfma_f32_16x16x32_bf16 v[76:79], v[206:209], v[198:201], v[76:79]
	v_mfma_f32_16x16x32_bf16 v[72:75], v[214:217], v[198:201], v[72:75]
	v_mfma_f32_16x16x32_bf16 v[132:135], v[210:213], v[156:159], v[132:135]
	v_mfma_f32_16x16x32_bf16 v[128:131], v[218:221], v[156:159], v[128:131]
	v_mfma_f32_16x16x32_bf16 v[108:111], v[210:213], v[172:175], v[108:111]
	v_mfma_f32_16x16x32_bf16 v[104:107], v[218:221], v[172:175], v[104:107]
	v_mfma_f32_16x16x32_bf16 v[92:95], v[210:213], v[180:183], v[92:95]
	v_mfma_f32_16x16x32_bf16 v[88:91], v[218:221], v[180:183], v[88:91]
	v_mfma_f32_16x16x32_bf16 v[76:79], v[210:213], v[202:205], v[76:79]
	v_mfma_f32_16x16x32_bf16 v[72:75], v[218:221], v[202:205], v[72:75]
	s_barrier
	s_mov_b32 m0, s29
	v_lshl_add_u64 v[224:225], v[222:223], 0, s[62:63]
	ds_read_b128 v[152:155], v197 offset:49152
	ds_read_b128 v[156:159], v197 offset:50176
	ds_read_b128 v[160:163], v197 offset:51200
	ds_read_b128 v[172:175], v197 offset:52224
	ds_read_b128 v[176:179], v197 offset:53248
	ds_read_b128 v[180:183], v197 offset:54272
	ds_read_b128 v[198:201], v197 offset:55296
	ds_read_b128 v[202:205], v197 offset:56320
	global_load_lds_dwordx4 v[224:225], off
	v_lshl_add_u64 v[222:223], v[222:223], 0, s[84:85]
	s_mov_b32 m0, s30
	s_nop 0
	global_load_lds_dwordx4 v[222:223], off
	s_barrier
	s_waitcnt lgkmcnt(0)
	v_mfma_f32_16x16x32_bf16 v[68:71], v[112:115], v[152:155], v[68:71]
	v_mfma_f32_16x16x32_bf16 v[64:67], v[136:139], v[152:155], v[64:67]
	v_mfma_f32_16x16x32_bf16 v[52:55], v[112:115], v[160:163], v[52:55]
	v_mfma_f32_16x16x32_bf16 v[48:51], v[136:139], v[160:163], v[48:51]
	v_mfma_f32_16x16x32_bf16 v[36:39], v[112:115], v[176:179], v[36:39]
	v_mfma_f32_16x16x32_bf16 v[32:35], v[136:139], v[176:179], v[32:35]
	v_mfma_f32_16x16x32_bf16 v[20:23], v[112:115], v[198:201], v[20:23]
	v_mfma_f32_16x16x32_bf16 v[16:19], v[136:139], v[198:201], v[16:19]
	v_mfma_f32_16x16x32_bf16 v[68:71], v[124:127], v[156:159], v[68:71]
	v_mfma_f32_16x16x32_bf16 v[64:67], v[148:151], v[156:159], v[64:67]
	v_mfma_f32_16x16x32_bf16 v[52:55], v[124:127], v[172:175], v[52:55]
	v_mfma_f32_16x16x32_bf16 v[48:51], v[148:151], v[172:175], v[48:51]
	v_mfma_f32_16x16x32_bf16 v[36:39], v[124:127], v[180:183], v[36:39]
	v_mfma_f32_16x16x32_bf16 v[32:35], v[148:151], v[180:183], v[32:35]
	v_mfma_f32_16x16x32_bf16 v[20:23], v[124:127], v[202:205], v[20:23]
	v_mfma_f32_16x16x32_bf16 v[16:19], v[148:151], v[202:205], v[16:19]
	s_barrier
	s_add_i32 s4, s5, s21
	v_lshl_add_u64 v[112:113], v[184:185], 0, s[42:43]
	s_mov_b32 m0, s4
	s_nop 0
	global_load_lds_dwordx4 v[112:113], off
	v_lshl_add_u64 v[112:113], v[184:185], 0, s[58:59]
	s_add_i32 m0, s4, 0x2000
	s_nop 0
	global_load_lds_dwordx4 v[112:113], off
	s_add_i32 s19, s19, 2
	s_add_u32 s13, s13, 0x100
	s_addc_u32 s18, s18, 0
	s_add_u32 s2, s2, 0x800000
	s_addc_u32 s3, s3, 0
	s_cmp_gt_u32 s19, 5
	s_waitcnt vmcnt(6)
	s_barrier
	v_mfma_f32_16x16x32_bf16 v[60:63], v[206:209], v[152:155], v[60:63]
	v_mfma_f32_16x16x32_bf16 v[56:59], v[214:217], v[152:155], v[56:59]
	v_mfma_f32_16x16x32_bf16 v[44:47], v[206:209], v[160:163], v[44:47]
	v_mfma_f32_16x16x32_bf16 v[40:43], v[214:217], v[160:163], v[40:43]
	v_mfma_f32_16x16x32_bf16 v[28:31], v[206:209], v[176:179], v[28:31]
	v_mfma_f32_16x16x32_bf16 v[24:27], v[214:217], v[176:179], v[24:27]
	v_mfma_f32_16x16x32_bf16 v[12:15], v[206:209], v[198:201], v[12:15]
	v_mfma_f32_16x16x32_bf16 v[8:11], v[214:217], v[198:201], v[8:11]
	v_mfma_f32_16x16x32_bf16 v[60:63], v[210:213], v[156:159], v[60:63]
	v_mfma_f32_16x16x32_bf16 v[56:59], v[218:221], v[156:159], v[56:59]
	v_mfma_f32_16x16x32_bf16 v[44:47], v[210:213], v[172:175], v[44:47]
	v_mfma_f32_16x16x32_bf16 v[40:43], v[218:221], v[172:175], v[40:43]
	v_mfma_f32_16x16x32_bf16 v[28:31], v[210:213], v[180:183], v[28:31]
	v_mfma_f32_16x16x32_bf16 v[24:27], v[218:221], v[180:183], v[24:27]
	v_mfma_f32_16x16x32_bf16 v[12:15], v[210:213], v[202:205], v[12:15]
	v_mfma_f32_16x16x32_bf16 v[8:11], v[218:221], v[202:205], v[8:11]
	s_cbranch_scc0 .Ldb_GLU_cont
	v_readfirstlane_b32 s101, v186
	s_cmpk_gt_u32 s101, 0xff
	s_cbranch_scc1 .Ldb_GLU_exit
	s_barrier
	s_branch .Ldb_GLU_exit

; #define G_STAGE(bufoff, gbase, o0, h64) do { \
;         __builtin_amdgcn_global_load_lds((const unsigned*)((const char*)(gbase) + (o0)), (LAS unsigned*)(lds + (bufoff) + ldsw), 16, 0, 0); \
;         __builtin_amdgcn_global_load_lds((const unsigned*)((const char*)(gbase) + (h64) + (o0)), (LAS unsigned*)(lds + (bufoff) + ldsw + 8192), 16, 0, 0); } while (0)
; #define G_LDA(dst, b, h) do { _Pragma("unroll") for (int m = 0; m < 4; ++m) _Pragma("unroll") for (int k = 0; k < 2; ++k) dst[m][k] = *(const LAS bf16x8*)(lds + G_SA(b, h) + aoff + m * 2048 + k * 1024); } while (0)
; #define G_LDB(dst, b, h) do { _Pragma("unroll") for (int n = 0; n < 2; ++n) _Pragma("unroll") for (int k = 0; k < 2; ++k) dst[n][k] = *(const LAS bf16x8*)(lds + G_SB(b, h) + boff + n * 2048 + k * 1024); } while (0)
; #define G_WAIT_V(n) asm volatile("s_waitcnt vmcnt(" #n ")" ::: "memory")
; #define G_WAIT_L(n) asm volatile("s_waitcnt lgkmcnt(" #n ")" ::: "memory")
; #define G_BAR __builtin_amdgcn_s_barrier()
; #define G_SCHED __builtin_amdgcn_sched_barrier(0)
;     ...
;         for (int t = 0; t < nt; t += 2) {
;             const bool last = (t == nt - 2);
;             const char* a1 = cA + (size_t)(t + 1) * ckA;
;             const char* a2 = last ? nA : cA + (size_t)(t + 2) * ckA; const char* b2 = last ? nB : cB + (size_t)(t + 2) * kB;
;             const char* a3 = a2 + ckA; const char* b3 = b2 + kB;
;             G_LDB(B0, 0, 0); G_SCHED; G_LDA(At, 0, 0); G_STAGE(G_SA(1, 1), a1 + chA, cA0, qA);
;             G_WAIT_L(8); G_BAR; G_WAIT_L(0); G_MMA(0, 0, At, B0); G_BAR; G_SCHED;
;             G_LDB(B1, 0, 1); G_STAGE(G_SB(0, 0), b2, cB0, qB);
;             G_BAR; G_WAIT_L(0); G_MMA(0, 1, At, B1); G_BAR;
;             G_LDA(At, 0, 1); G_STAGE(G_SA(0, 0), a2, cA0, qA);
;             G_BAR; G_WAIT_L(0); G_MMA(1, 0, At, B0); G_BAR; G_SCHED;
;             G_STAGE(G_SB(0, 1), b2 + chB, cB0, qB);
;             G_WAIT_V(6); G_BAR; G_MMA(1, 1, At, B1); G_BAR;
.Ldbj_MG0_in:
.LBB0_872:
	s_add_u32 s4, s2, 0xfff50080
	s_addc_u32 s5, s3, -1
	s_add_i32 s40, 0, 0x10000
	v_add_u32_e32 v140, s40, v159
	ds_read_b128 v[144:147], v140
	ds_read_b128 v[148:151], v140 offset:1024
	ds_read_b128 v[136:139], v140 offset:2048
	ds_read_b128 v[140:143], v140 offset:3072
	s_cmp_eq_u32 s39, 4
	s_cselect_b32 s13, s9, s5
	s_cselect_b32 s12, s8, s4
	s_cselect_b32 s15, s11, s38
	s_cselect_b32 s14, s10, s37
	v_lshl_add_u64 v[154:155], s[2:3], 0, v[152:153]
	s_add_i32 m0, s22, 0xc000
	ds_read_b128 v[160:163], v236
	ds_read_b128 v[164:167], v236 offset:1024
	ds_read_b128 v[176:179], v236 offset:2048
	ds_read_b128 v[180:183], v236 offset:3072
	ds_read_b128 v[196:199], v236 offset:4096
	ds_read_b128 v[200:203], v236 offset:5120
	ds_read_b128 v[204:207], v236 offset:6144
	ds_read_b128 v[208:211], v236 offset:7168
	global_load_lds_dwordx4 v[154:155], off
	v_lshl_add_u64 v[154:155], v[154:155], 0, s[86:87]
	s_add_i32 m0, s22, 0xe000
	s_nop 0
	global_load_lds_dwordx4 v[154:155], off
	s_waitcnt lgkmcnt(8)
	s_barrier
	s_waitcnt lgkmcnt(0)
	v_mfma_f32_16x16x128_f8f6f4 v[128:131], v[144:151], v[160:167], v[128:131]
	v_mfma_f32_16x16x128_f8f6f4 v[132:135], v[136:143], v[160:167], v[132:135]
	v_mfma_f32_16x16x128_f8f6f4 v[112:115], v[144:151], v[176:183], v[112:115]
	v_mfma_f32_16x16x128_f8f6f4 v[116:119], v[136:143], v[176:183], v[116:119]
	v_mfma_f32_16x16x128_f8f6f4 v[96:99], v[144:151], v[196:203], v[96:99]
	v_mfma_f32_16x16x128_f8f6f4 v[100:103], v[136:143], v[196:203], v[100:103]
	v_mfma_f32_16x16x128_f8f6f4 v[80:83], v[144:151], v[204:211], v[80:83]
	v_mfma_f32_16x16x128_f8f6f4 v[84:87], v[136:143], v[204:211], v[84:87]
	s_barrier
	s_add_i32 s4, 0, 0x14000
	v_add_u32_e32 v154, s4, v159
	s_add_i32 s5, s40, s17
	ds_read_b128 v[212:215], v154
	ds_read_b128 v[216:219], v154 offset:1024
	ds_read_b128 v[220:223], v154 offset:2048
	ds_read_b128 v[224:227], v154 offset:3072
	v_lshl_add_u64 v[154:155], s[14:15], 0, v[0:1]
	s_mov_b32 m0, s5
	v_lshl_add_u64 v[156:157], v[154:155], 0, s[50:51]
	global_load_lds_dwordx4 v[154:155], off
	s_add_i32 m0, s5, 0x2000
	s_nop 0
	global_load_lds_dwordx4 v[156:157], off
	s_barrier
	s_waitcnt lgkmcnt(0)
	v_mfma_f32_16x16x128_f8f6f4 v[124:127], v[212:219], v[160:167], v[124:127]
	v_mfma_f32_16x16x128_f8f6f4 v[120:123], v[220:227], v[160:167], v[120:123]
	v_mfma_f32_16x16x128_f8f6f4 v[108:111], v[212:219], v[176:183], v[108:111]
	v_mfma_f32_16x16x128_f8f6f4 v[104:107], v[220:227], v[176:183], v[104:107]
	v_mfma_f32_16x16x128_f8f6f4 v[92:95], v[212:219], v[196:203], v[92:95]
	v_mfma_f32_16x16x128_f8f6f4 v[88:91], v[220:227], v[196:203], v[88:91]
	v_mfma_f32_16x16x128_f8f6f4 v[76:79], v[212:219], v[204:211], v[76:79]
	v_mfma_f32_16x16x128_f8f6f4 v[72:75], v[220:227], v[204:211], v[72:75]
	s_barrier
	s_mov_b32 m0, s22
	v_lshl_add_u64 v[156:157], s[12:13], 0, v[2:3]
	ds_read_b128 v[160:163], v236 offset:16384
	ds_read_b128 v[164:167], v236 offset:17408
	ds_read_b128 v[176:179], v236 offset:18432
	ds_read_b128 v[180:183], v236 offset:19456
	ds_read_b128 v[196:199], v236 offset:20480
	ds_read_b128 v[200:203], v236 offset:21504
	ds_read_b128 v[204:207], v236 offset:22528
	ds_read_b128 v[208:211], v236 offset:23552
	global_load_lds_dwordx4 v[156:157], off
	v_lshl_add_u64 v[234:235], v[156:157], 0, s[86:87]
	s_mov_b32 m0, s23
	s_nop 0
	global_load_lds_dwordx4 v[234:235], off
	s_barrier
	s_waitcnt lgkmcnt(0)
	v_mfma_f32_16x16x128_f8f6f4 v[64:67], v[144:151], v[160:167], v[64:67]
	v_mfma_f32_16x16x128_f8f6f4 v[68:71], v[136:143], v[160:167], v[68:71]
	v_mfma_f32_16x16x128_f8f6f4 v[48:51], v[144:151], v[176:183], v[48:51]
	v_mfma_f32_16x16x128_f8f6f4 v[52:55], v[136:143], v[176:183], v[52:55]
	v_mfma_f32_16x16x128_f8f6f4 v[32:35], v[144:151], v[196:203], v[32:35]
	v_mfma_f32_16x16x128_f8f6f4 v[36:39], v[136:143], v[196:203], v[36:39]
	v_mfma_f32_16x16x128_f8f6f4 v[20:23], v[144:151], v[204:211], v[20:23]
	v_mfma_f32_16x16x128_f8f6f4 v[16:19], v[136:143], v[204:211], v[16:19]
	s_barrier
	s_add_i32 s4, s4, s17
	v_lshl_add_u64 v[140:141], v[154:155], 0, s[0:1]
	s_mov_b32 m0, s4
	s_nop 0
	global_load_lds_dwordx4 v[140:141], off
	v_lshl_add_u64 v[140:141], v[154:155], 0, s[52:53]
	s_add_i32 m0, s4, 0x2000
	s_nop 0
	global_load_lds_dwordx4 v[140:141], off
	s_waitcnt vmcnt(6)
	s_barrier
	v_mfma_f32_16x16x128_f8f6f4 v[60:63], v[212:219], v[160:167], v[60:63]
	v_mfma_f32_16x16x128_f8f6f4 v[56:59], v[220:227], v[160:167], v[56:59]
	v_mfma_f32_16x16x128_f8f6f4 v[44:47], v[212:219], v[176:183], v[44:47]
	v_mfma_f32_16x16x128_f8f6f4 v[40:43], v[220:227], v[176:183], v[40:43]
	v_mfma_f32_16x16x128_f8f6f4 v[28:31], v[212:219], v[196:203], v[28:31]
	v_mfma_f32_16x16x128_f8f6f4 v[24:27], v[220:227], v[196:203], v[24:27]
	v_mfma_f32_16x16x128_f8f6f4 v[12:15], v[212:219], v[204:211], v[12:15]
	v_mfma_f32_16x16x128_f8f6f4 v[8:11], v[220:227], v[204:211], v[8:11]
	s_barrier
; #define G_STAGE(bufoff, gbase, o0, h64) do { \
;         __builtin_amdgcn_global_load_lds((const unsigned*)((const char*)(gbase) + (o0)), (LAS unsigned*)(lds + (bufoff) + ldsw), 16, 0, 0); \
;         __builtin_amdgcn_global_load_lds((const unsigned*)((const char*)(gbase) + (h64) + (o0)), (LAS unsigned*)(lds + (bufoff) + ldsw + 8192), 16, 0, 0); } while (0)
; #define G_LDA(dst, b, h) do { _Pragma("unroll") for (int m = 0; m < 4; ++m) _Pragma("unroll") for (int k = 0; k < 2; ++k) dst[m][k] = *(const LAS bf16x8*)(lds + G_SA(b, h) + aoff + m * 2048 + k * 1024); } while (0)
; #define G_LDB(dst, b, h) do { _Pragma("unroll") for (int n = 0; n < 2; ++n) _Pragma("unroll") for (int k = 0; k < 2; ++k) dst[n][k] = *(const LAS bf16x8*)(lds + G_SB(b, h) + boff + n * 2048 + k * 1024); } while (0)
; #define G_WAIT_V(n) asm volatile("s_waitcnt vmcnt(" #n ")" ::: "memory")
; #define G_WAIT_L(n) asm volatile("s_waitcnt lgkmcnt(" #n ")" ::: "memory")
; #define G_BAR __builtin_amdgcn_s_barrier()
; #define G_SCHED __builtin_amdgcn_sched_barrier(0)
;     ...
;             G_LDB(B0, 1, 0); G_SCHED; G_LDA(At, 1, 0); G_STAGE(G_SA(0, 1), a2 + chA, cA0, qA);
;             G_WAIT_L(8); G_BAR; G_WAIT_L(0); G_MMA(0, 0, At, B0); G_BAR; G_SCHED;
;             G_LDB(B1, 1, 1); G_STAGE(G_SB(1, 0), b3, cB0, qB);
;             G_BAR; G_WAIT_L(0); G_MMA(0, 1, At, B1); G_BAR;
;             G_LDA(At, 1, 1); G_STAGE(G_SA(1, 0), a3, cA0, qA);
;             G_BAR; G_WAIT_L(0); G_MMA(1, 0, At, B0); G_BAR; G_SCHED;
;             G_STAGE(G_SB(1, 1), b3 + chB, cB0, qB);
;             G_WAIT_V(6); G_BAR; G_MMA(1, 1, At, B1); G_BAR;
;         }
	s_add_i32 s4, 0, 0x18000
	v_add_u32_e32 v140, s4, v159
	ds_read_b128 v[144:147], v140
	ds_read_b128 v[148:151], v140 offset:1024
	ds_read_b128 v[136:139], v140 offset:2048
	ds_read_b128 v[140:143], v140 offset:3072
	s_mov_b32 m0, s24
	v_lshl_add_u64 v[234:235], v[156:157], 0, s[88:89]
	ds_read_b128 v[160:163], v236 offset:32768
	ds_read_b128 v[164:167], v236 offset:33792
	ds_read_b128 v[176:179], v236 offset:34816
	ds_read_b128 v[180:183], v236 offset:35840
	ds_read_b128 v[196:199], v236 offset:36864
	ds_read_b128 v[200:203], v236 offset:37888
	ds_read_b128 v[204:207], v236 offset:38912
	ds_read_b128 v[208:211], v236 offset:39936
	global_load_lds_dwordx4 v[234:235], off
	v_lshl_add_u64 v[234:235], v[156:157], 0, s[64:65]
	s_mov_b32 m0, s25
	s_nop 0
	global_load_lds_dwordx4 v[234:235], off
	s_waitcnt lgkmcnt(8)
	s_barrier
	s_waitcnt lgkmcnt(0)
	v_mfma_f32_16x16x128_f8f6f4 v[128:131], v[144:151], v[160:167], v[128:131]
	v_mfma_f32_16x16x128_f8f6f4 v[132:135], v[136:143], v[160:167], v[132:135]
	v_mfma_f32_16x16x128_f8f6f4 v[112:115], v[144:151], v[176:183], v[112:115]
	v_mfma_f32_16x16x128_f8f6f4 v[116:119], v[136:143], v[176:183], v[116:119]
	v_mfma_f32_16x16x128_f8f6f4 v[96:99], v[144:151], v[196:203], v[96:99]
	v_mfma_f32_16x16x128_f8f6f4 v[100:103], v[136:143], v[196:203], v[100:103]
	v_mfma_f32_16x16x128_f8f6f4 v[80:83], v[144:151], v[204:211], v[80:83]
	v_mfma_f32_16x16x128_f8f6f4 v[84:87], v[136:143], v[204:211], v[84:87]
	s_barrier
	s_add_i32 s5, 0, 0x1c000
	s_add_i32 s4, s4, s17
	v_add_u32_e32 v237, s5, v159
	v_lshl_add_u64 v[234:235], v[154:155], 0, s[46:47]
	s_mov_b32 m0, s4
	ds_read_b128 v[212:215], v237
	ds_read_b128 v[216:219], v237 offset:1024
	ds_read_b128 v[220:223], v237 offset:2048
	ds_read_b128 v[224:227], v237 offset:3072
	global_load_lds_dwordx4 v[234:235], off
	v_lshl_add_u64 v[234:235], v[154:155], 0, s[54:55]
	s_add_i32 m0, s4, 0x2000
	s_nop 0
	global_load_lds_dwordx4 v[234:235], off
	s_barrier
	s_waitcnt lgkmcnt(0)
	v_mfma_f32_16x16x128_f8f6f4 v[124:127], v[212:219], v[160:167], v[124:127]
	v_mfma_f32_16x16x128_f8f6f4 v[120:123], v[220:227], v[160:167], v[120:123]
	v_mfma_f32_16x16x128_f8f6f4 v[108:111], v[212:219], v[176:183], v[108:111]
	v_mfma_f32_16x16x128_f8f6f4 v[104:107], v[220:227], v[176:183], v[104:107]
	v_mfma_f32_16x16x128_f8f6f4 v[92:95], v[212:219], v[196:203], v[92:95]
	v_mfma_f32_16x16x128_f8f6f4 v[88:91], v[220:227], v[196:203], v[88:91]
	v_mfma_f32_16x16x128_f8f6f4 v[76:79], v[212:219], v[204:211], v[76:79]
	v_mfma_f32_16x16x128_f8f6f4 v[72:75], v[220:227], v[204:211], v[72:75]
	s_barrier
	s_mov_b32 m0, s26
	v_lshl_add_u64 v[234:235], v[156:157], 0, s[46:47]
	ds_read_b128 v[160:163], v236 offset:49152
	ds_read_b128 v[164:167], v236 offset:50176
	ds_read_b128 v[176:179], v236 offset:51200
	ds_read_b128 v[180:183], v236 offset:52224
	ds_read_b128 v[196:199], v236 offset:53248
	ds_read_b128 v[200:203], v236 offset:54272
	ds_read_b128 v[204:207], v236 offset:55296
	ds_read_b128 v[208:211], v236 offset:56320
	global_load_lds_dwordx4 v[234:235], off
	v_lshl_add_u64 v[156:157], v[156:157], 0, s[66:67]
	s_mov_b32 m0, s27
	s_nop 0
	global_load_lds_dwordx4 v[156:157], off
	s_barrier
	s_waitcnt lgkmcnt(0)
	v_mfma_f32_16x16x128_f8f6f4 v[64:67], v[144:151], v[160:167], v[64:67]
	v_mfma_f32_16x16x128_f8f6f4 v[68:71], v[136:143], v[160:167], v[68:71]
	v_mfma_f32_16x16x128_f8f6f4 v[48:51], v[144:151], v[176:183], v[48:51]
	v_mfma_f32_16x16x128_f8f6f4 v[52:55], v[136:143], v[176:183], v[52:55]
	v_mfma_f32_16x16x128_f8f6f4 v[32:35], v[144:151], v[196:203], v[32:35]
	v_mfma_f32_16x16x128_f8f6f4 v[36:39], v[136:143], v[196:203], v[36:39]
	v_mfma_f32_16x16x128_f8f6f4 v[20:23], v[144:151], v[204:211], v[20:23]
	v_mfma_f32_16x16x128_f8f6f4 v[16:19], v[136:143], v[204:211], v[16:19]
	s_barrier
	s_add_i32 s4, s5, s17
	v_lshl_add_u64 v[140:141], v[154:155], 0, s[42:43]
	s_mov_b32 m0, s4
	s_nop 0
	global_load_lds_dwordx4 v[140:141], off
	v_lshl_add_u64 v[140:141], v[154:155], 0, s[58:59]
	s_add_i32 m0, s4, 0x2000
	s_nop 0
	global_load_lds_dwordx4 v[140:141], off
	s_add_i32 s39, s39, 2
	s_add_u32 s2, s2, 0x100
	s_addc_u32 s3, s3, 0
	s_add_u32 s37, s37, 0x100
	s_addc_u32 s38, s38, 0
	s_cmp_gt_u32 s39, 5
	s_waitcnt vmcnt(6)
	s_barrier
	v_mfma_f32_16x16x128_f8f6f4 v[60:63], v[212:219], v[160:167], v[60:63]
	v_mfma_f32_16x16x128_f8f6f4 v[56:59], v[220:227], v[160:167], v[56:59]
	v_mfma_f32_16x16x128_f8f6f4 v[44:47], v[212:219], v[176:183], v[44:47]
	v_mfma_f32_16x16x128_f8f6f4 v[40:43], v[220:227], v[176:183], v[40:43]
	v_mfma_f32_16x16x128_f8f6f4 v[28:31], v[212:219], v[196:203], v[28:31]
	v_mfma_f32_16x16x128_f8f6f4 v[24:27], v[220:227], v[196:203], v[24:27]
	v_mfma_f32_16x16x128_f8f6f4 v[12:15], v[212:219], v[204:211], v[12:15]
	v_mfma_f32_16x16x128_f8f6f4 v[8:11], v[220:227], v[204:211], v[8:11]
	s_cbranch_scc0 .Ldb_MG0_cont
	v_readfirstlane_b32 s101, v186
	s_cmpk_gt_u32 s101, 0xff
	s_cbranch_scc1 .Ldb_MG0_exit
	s_barrier
	s_branch .Ldb_MG0_exit

; #define G_STAGE(bufoff, gbase, o0, h64) do { \
;         __builtin_amdgcn_global_load_lds((const unsigned*)((const char*)(gbase) + (o0)), (LAS unsigned*)(lds + (bufoff) + ldsw), 16, 0, 0); \
;         __builtin_amdgcn_global_load_lds((const unsigned*)((const char*)(gbase) + (h64) + (o0)), (LAS unsigned*)(lds + (bufoff) + ldsw + 8192), 16, 0, 0); } while (0)
; #define G_LDA(dst, b, h) do { _Pragma("unroll") for (int m = 0; m < 4; ++m) _Pragma("unroll") for (int k = 0; k < 2; ++k) dst[m][k] = *(const LAS bf16x8*)(lds + G_SA(b, h) + aoff + m * 2048 + k * 1024); } while (0)
; #define G_LDB(dst, b, h) do { _Pragma("unroll") for (int n = 0; n < 2; ++n) _Pragma("unroll") for (int k = 0; k < 2; ++k) dst[n][k] = *(const LAS bf16x8*)(lds + G_SB(b, h) + boff + n * 2048 + k * 1024); } while (0)
; #define G_WAIT_L(n) asm volatile("s_waitcnt lgkmcnt(" #n ")" ::: "memory")
; #define G_BAR __builtin_amdgcn_s_barrier()
; #define G_SCHED __builtin_amdgcn_sched_barrier(0)
;     ...
;         for (int t = 0; t < nt; t += 2) {
;             const bool last = (t == nt - 2);
;             const char* a1 = cA + (size_t)(t + 1) * ckA;
;             const char* a2 = last ? nA : cA + (size_t)(t + 2) * ckA; const char* b2 = last ? nB : cB + (size_t)(t + 2) * kB;
;             const char* a3 = a2 + ckA; const char* b3 = b2 + kB;
;             G_LDB(B0, 0, 0); G_SCHED; G_LDA(At, 0, 0); G_STAGE(G_SA(1, 1), a1 + chA, cA0, qA);
;             G_WAIT_L(8); G_BAR; G_WAIT_L(0); G_MMA(0, 0, At, B0); G_BAR; G_SCHED;
;             G_LDB(B1, 0, 1); G_STAGE(G_SB(0, 0), b2, cB0, qB);
;             G_BAR; G_WAIT_L(0); G_MMA(0, 1, At, B1); G_BAR;
;             G_LDA(At, 0, 1); G_STAGE(G_SA(0, 0), a2, cA0, qA);
;             G_BAR; G_WAIT_L(0); G_MMA(1, 0, At, B0); G_BAR; G_SCHED;
.Ldbj_MG1_in:
.LBB0_890:
	s_add_u32 s4, s6, 0xfff50080
	s_addc_u32 s5, s7, -1
	s_add_i32 s19, 0, 0x10000
	v_add_u32_e32 v0, s19, v175
	ds_read_b128 v[136:139], v0
	ds_read_b128 v[140:143], v0 offset:1024
	ds_read_b128 v[144:147], v0 offset:2048
	ds_read_b128 v[148:151], v0 offset:3072
	s_cmp_eq_u32 s18, 4
	s_cselect_b32 s45, s15, s9
	s_cselect_b32 s44, s14, s8
	s_cselect_b32 s5, s13, s5
	s_cselect_b32 s4, s12, s4
	v_lshl_add_u64 v[2:3], s[6:7], 0, v[156:157]
	s_add_i32 m0, s22, 0xc000
	ds_read_b128 v[158:161], v176
	ds_read_b128 v[162:165], v176 offset:1024
	ds_read_b128 v[178:181], v176 offset:2048
	ds_read_b128 v[182:185], v176 offset:3072
	ds_read_b128 v[196:199], v176 offset:4096
	ds_read_b128 v[200:203], v176 offset:5120
	ds_read_b128 v[204:207], v176 offset:6144
	ds_read_b128 v[208:211], v176 offset:7168
	global_load_lds_dwordx4 v[2:3], off
	v_lshl_add_u64 v[2:3], v[2:3], 0, s[86:87]
	s_add_i32 m0, s22, 0xe000
	s_nop 0
	global_load_lds_dwordx4 v[2:3], off
	s_waitcnt lgkmcnt(8)
	s_barrier
	s_waitcnt lgkmcnt(0)
	v_mfma_f32_16x16x32_bf16 v[104:107], v[136:139], v[158:161], v[104:107]
	v_mfma_f32_16x16x32_bf16 v[108:111], v[144:147], v[158:161], v[108:111]
	v_mfma_f32_16x16x32_bf16 v[132:135], v[136:139], v[178:181], v[132:135]
	v_mfma_f32_16x16x32_bf16 v[128:131], v[144:147], v[178:181], v[128:131]
	v_mfma_f32_16x16x32_bf16 v[124:127], v[136:139], v[196:199], v[124:127]
	v_mfma_f32_16x16x32_bf16 v[120:123], v[144:147], v[196:199], v[120:123]
	v_mfma_f32_16x16x32_bf16 v[116:119], v[136:139], v[204:207], v[116:119]
	v_mfma_f32_16x16x32_bf16 v[112:115], v[144:147], v[204:207], v[112:115]
	v_mfma_f32_16x16x32_bf16 v[104:107], v[140:143], v[162:165], v[104:107]
	v_mfma_f32_16x16x32_bf16 v[108:111], v[148:151], v[162:165], v[108:111]
	v_mfma_f32_16x16x32_bf16 v[132:135], v[140:143], v[182:185], v[132:135]
	v_mfma_f32_16x16x32_bf16 v[128:131], v[148:151], v[182:185], v[128:131]
	v_mfma_f32_16x16x32_bf16 v[124:127], v[140:143], v[200:203], v[124:127]
	v_mfma_f32_16x16x32_bf16 v[120:123], v[148:151], v[200:203], v[120:123]
	v_mfma_f32_16x16x32_bf16 v[116:119], v[140:143], v[208:211], v[116:119]
	v_mfma_f32_16x16x32_bf16 v[112:115], v[148:151], v[208:211], v[112:115]
	s_barrier
	s_add_i32 s43, 0, 0x14000
	s_add_i32 s19, s19, s21
	v_add_u32_e32 v0, s43, v175
	v_lshl_add_u64 v[2:3], s[44:45], 0, v[154:155]
	s_mov_b64 s[44:45], 0x10000
	s_mov_b32 m0, s19
	ds_read_b128 v[212:215], v0
	ds_read_b128 v[216:219], v0 offset:1024
	ds_read_b128 v[220:223], v0 offset:2048
	ds_read_b128 v[224:227], v0 offset:3072
	global_load_lds_dwordx4 v[2:3], off
	v_lshl_add_u64 v[166:167], v[2:3], 0, s[44:45]
	s_add_i32 m0, s19, 0x2000
	s_nop 0
	global_load_lds_dwordx4 v[166:167], off
	s_barrier
	s_waitcnt lgkmcnt(0)
	v_mfma_f32_16x16x32_bf16 v[100:103], v[212:215], v[158:161], v[100:103]
	v_mfma_f32_16x16x32_bf16 v[96:99], v[220:223], v[158:161], v[96:99]
	v_mfma_f32_16x16x32_bf16 v[92:95], v[212:215], v[178:181], v[92:95]
	v_mfma_f32_16x16x32_bf16 v[88:91], v[220:223], v[178:181], v[88:91]
	v_mfma_f32_16x16x32_bf16 v[84:87], v[212:215], v[196:199], v[84:87]
	v_mfma_f32_16x16x32_bf16 v[80:83], v[220:223], v[196:199], v[80:83]
	v_mfma_f32_16x16x32_bf16 v[76:79], v[212:215], v[204:207], v[76:79]
	v_mfma_f32_16x16x32_bf16 v[72:75], v[220:223], v[204:207], v[72:75]
	v_mfma_f32_16x16x32_bf16 v[100:103], v[216:219], v[162:165], v[100:103]
	v_mfma_f32_16x16x32_bf16 v[96:99], v[224:227], v[162:165], v[96:99]
	v_mfma_f32_16x16x32_bf16 v[92:95], v[216:219], v[182:185], v[92:95]
	v_mfma_f32_16x16x32_bf16 v[88:91], v[224:227], v[182:185], v[88:91]
	v_mfma_f32_16x16x32_bf16 v[84:87], v[216:219], v[200:203], v[84:87]
	v_mfma_f32_16x16x32_bf16 v[80:83], v[224:227], v[200:203], v[80:83]
	v_mfma_f32_16x16x32_bf16 v[76:79], v[216:219], v[208:211], v[76:79]
	v_mfma_f32_16x16x32_bf16 v[72:75], v[224:227], v[208:211], v[72:75]
	s_barrier
	s_mov_b32 m0, s22
	v_lshl_add_u64 v[166:167], s[4:5], 0, v[152:153]
	ds_read_b128 v[158:161], v176 offset:16384
	ds_read_b128 v[162:165], v176 offset:17408
	ds_read_b128 v[178:181], v176 offset:18432
	ds_read_b128 v[182:185], v176 offset:19456
	ds_read_b128 v[196:199], v176 offset:20480
	ds_read_b128 v[200:203], v176 offset:21504
	ds_read_b128 v[204:207], v176 offset:22528
	ds_read_b128 v[208:211], v176 offset:23552
	global_load_lds_dwordx4 v[166:167], off
	v_lshl_add_u64 v[172:173], v[166:167], 0, s[86:87]
	s_mov_b32 m0, s23
	s_nop 0
	global_load_lds_dwordx4 v[172:173], off
	s_barrier
	s_waitcnt lgkmcnt(0)
	v_mfma_f32_16x16x32_bf16 v[68:71], v[136:139], v[158:161], v[68:71]
	v_mfma_f32_16x16x32_bf16 v[64:67], v[144:147], v[158:161], v[64:67]
	v_mfma_f32_16x16x32_bf16 v[60:63], v[136:139], v[178:181], v[60:63]
	v_mfma_f32_16x16x32_bf16 v[56:59], v[144:147], v[178:181], v[56:59]
	v_mfma_f32_16x16x32_bf16 v[52:55], v[136:139], v[196:199], v[52:55]
	v_mfma_f32_16x16x32_bf16 v[48:51], v[144:147], v[196:199], v[48:51]
	v_mfma_f32_16x16x32_bf16 v[44:47], v[136:139], v[204:207], v[44:47]
	v_mfma_f32_16x16x32_bf16 v[40:43], v[144:147], v[204:207], v[40:43]
	v_mfma_f32_16x16x32_bf16 v[68:71], v[140:143], v[162:165], v[68:71]
	v_mfma_f32_16x16x32_bf16 v[64:67], v[148:151], v[162:165], v[64:67]
	v_mfma_f32_16x16x32_bf16 v[60:63], v[140:143], v[182:185], v[60:63]
	v_mfma_f32_16x16x32_bf16 v[56:59], v[148:151], v[182:185], v[56:59]
	v_mfma_f32_16x16x32_bf16 v[52:55], v[140:143], v[200:203], v[52:55]
	v_mfma_f32_16x16x32_bf16 v[48:51], v[148:151], v[200:203], v[48:51]
	v_mfma_f32_16x16x32_bf16 v[44:47], v[140:143], v[208:211], v[44:47]
	v_mfma_f32_16x16x32_bf16 v[40:43], v[148:151], v[208:211], v[40:43]
	s_barrier
; #define G_STAGE(bufoff, gbase, o0, h64) do { \
;         __builtin_amdgcn_global_load_lds((const unsigned*)((const char*)(gbase) + (o0)), (LAS unsigned*)(lds + (bufoff) + ldsw), 16, 0, 0); \
;         __builtin_amdgcn_global_load_lds((const unsigned*)((const char*)(gbase) + (h64) + (o0)), (LAS unsigned*)(lds + (bufoff) + ldsw + 8192), 16, 0, 0); } while (0)
; #define G_LDA(dst, b, h) do { _Pragma("unroll") for (int m = 0; m < 4; ++m) _Pragma("unroll") for (int k = 0; k < 2; ++k) dst[m][k] = *(const LAS bf16x8*)(lds + G_SA(b, h) + aoff + m * 2048 + k * 1024); } while (0)
; #define G_LDB(dst, b, h) do { _Pragma("unroll") for (int n = 0; n < 2; ++n) _Pragma("unroll") for (int k = 0; k < 2; ++k) dst[n][k] = *(const LAS bf16x8*)(lds + G_SB(b, h) + boff + n * 2048 + k * 1024); } while (0)
; #define G_WAIT_V(n) asm volatile("s_waitcnt vmcnt(" #n ")" ::: "memory")
; #define G_WAIT_L(n) asm volatile("s_waitcnt lgkmcnt(" #n ")" ::: "memory")
; #define G_BAR __builtin_amdgcn_s_barrier()
; #define G_SCHED __builtin_amdgcn_sched_barrier(0)
;     ...
;             G_STAGE(G_SB(0, 1), b2 + chB, cB0, qB);
;             G_WAIT_V(6); G_BAR; G_MMA(1, 1, At, B1); G_BAR;
;             G_LDB(B0, 1, 0); G_SCHED; G_LDA(At, 1, 0); G_STAGE(G_SA(0, 1), a2 + chA, cA0, qA);
;             G_WAIT_L(8); G_BAR; G_WAIT_L(0); G_MMA(0, 0, At, B0); G_BAR; G_SCHED;
;             G_LDB(B1, 1, 1); G_STAGE(G_SB(1, 0), b3, cB0, qB);
	s_add_i32 s4, s43, s21
	v_lshl_add_u64 v[136:137], v[2:3], 0, s[0:1]
	s_mov_b32 m0, s4
	s_nop 0
	global_load_lds_dwordx4 v[136:137], off
	v_lshl_add_u64 v[136:137], v[2:3], 0, s[52:53]
	s_add_i32 m0, s4, 0x2000
	s_nop 0
	global_load_lds_dwordx4 v[136:137], off
	s_waitcnt vmcnt(6)
	s_barrier
	v_mfma_f32_16x16x32_bf16 v[36:39], v[212:215], v[158:161], v[36:39]
	v_mfma_f32_16x16x32_bf16 v[32:35], v[220:223], v[158:161], v[32:35]
	v_mfma_f32_16x16x32_bf16 v[28:31], v[212:215], v[178:181], v[28:31]
	v_mfma_f32_16x16x32_bf16 v[24:27], v[220:223], v[178:181], v[24:27]
	v_mfma_f32_16x16x32_bf16 v[20:23], v[212:215], v[196:199], v[20:23]
	v_mfma_f32_16x16x32_bf16 v[16:19], v[220:223], v[196:199], v[16:19]
	v_mfma_f32_16x16x32_bf16 v[12:15], v[212:215], v[204:207], v[12:15]
	v_mfma_f32_16x16x32_bf16 v[8:11], v[220:223], v[204:207], v[8:11]
	v_mfma_f32_16x16x32_bf16 v[36:39], v[216:219], v[162:165], v[36:39]
	v_mfma_f32_16x16x32_bf16 v[32:35], v[224:227], v[162:165], v[32:35]
	v_mfma_f32_16x16x32_bf16 v[28:31], v[216:219], v[182:185], v[28:31]
	v_mfma_f32_16x16x32_bf16 v[24:27], v[224:227], v[182:185], v[24:27]
	v_mfma_f32_16x16x32_bf16 v[20:23], v[216:219], v[200:203], v[20:23]
	v_mfma_f32_16x16x32_bf16 v[16:19], v[224:227], v[200:203], v[16:19]
	v_mfma_f32_16x16x32_bf16 v[12:15], v[216:219], v[208:211], v[12:15]
	v_mfma_f32_16x16x32_bf16 v[8:11], v[224:227], v[208:211], v[8:11]
	s_barrier
	s_add_i32 s4, 0, 0x18000
	v_add_u32_e32 v0, s4, v175
	ds_read_b128 v[136:139], v0
	ds_read_b128 v[140:143], v0 offset:1024
	ds_read_b128 v[144:147], v0 offset:2048
	ds_read_b128 v[148:151], v0 offset:3072
	s_mov_b32 m0, s24
	v_lshl_add_u64 v[172:173], v[166:167], 0, s[88:89]
	ds_read_b128 v[158:161], v176 offset:32768
	ds_read_b128 v[162:165], v176 offset:33792
	ds_read_b128 v[178:181], v176 offset:34816
	ds_read_b128 v[182:185], v176 offset:35840
	ds_read_b128 v[196:199], v176 offset:36864
	ds_read_b128 v[200:203], v176 offset:37888
	ds_read_b128 v[204:207], v176 offset:38912
	ds_read_b128 v[208:211], v176 offset:39936
	global_load_lds_dwordx4 v[172:173], off
	v_lshl_add_u64 v[172:173], v[166:167], 0, s[64:65]
	s_mov_b32 m0, s25
	s_nop 0
	global_load_lds_dwordx4 v[172:173], off
	s_waitcnt lgkmcnt(8)
	s_barrier
	s_waitcnt lgkmcnt(0)
	v_mfma_f32_16x16x32_bf16 v[104:107], v[136:139], v[158:161], v[104:107]
	v_mfma_f32_16x16x32_bf16 v[108:111], v[144:147], v[158:161], v[108:111]
	v_mfma_f32_16x16x32_bf16 v[132:135], v[136:139], v[178:181], v[132:135]
	v_mfma_f32_16x16x32_bf16 v[128:131], v[144:147], v[178:181], v[128:131]
	v_mfma_f32_16x16x32_bf16 v[124:127], v[136:139], v[196:199], v[124:127]
	v_mfma_f32_16x16x32_bf16 v[120:123], v[144:147], v[196:199], v[120:123]
	v_mfma_f32_16x16x32_bf16 v[116:119], v[136:139], v[204:207], v[116:119]
	v_mfma_f32_16x16x32_bf16 v[112:115], v[144:147], v[204:207], v[112:115]
	v_mfma_f32_16x16x32_bf16 v[104:107], v[140:143], v[162:165], v[104:107]
	v_mfma_f32_16x16x32_bf16 v[108:111], v[148:151], v[162:165], v[108:111]
	v_mfma_f32_16x16x32_bf16 v[132:135], v[140:143], v[182:185], v[132:135]
	v_mfma_f32_16x16x32_bf16 v[128:131], v[148:151], v[182:185], v[128:131]
	v_mfma_f32_16x16x32_bf16 v[124:127], v[140:143], v[200:203], v[124:127]
	v_mfma_f32_16x16x32_bf16 v[120:123], v[148:151], v[200:203], v[120:123]
	v_mfma_f32_16x16x32_bf16 v[116:119], v[140:143], v[208:211], v[116:119]
	v_mfma_f32_16x16x32_bf16 v[112:115], v[148:151], v[208:211], v[112:115]
	s_barrier
	s_add_i32 s5, 0, 0x1c000
	s_add_i32 s4, s4, s21
	v_add_u32_e32 v0, s5, v175
	v_lshl_add_u64 v[172:173], v[2:3], 0, s[46:47]
	s_mov_b32 m0, s4
	ds_read_b128 v[212:215], v0
	ds_read_b128 v[216:219], v0 offset:1024
	ds_read_b128 v[220:223], v0 offset:2048
	ds_read_b128 v[224:227], v0 offset:3072
	global_load_lds_dwordx4 v[172:173], off
	v_lshl_add_u64 v[172:173], v[2:3], 0, s[54:55]
	s_add_i32 m0, s4, 0x2000
	s_nop 0
	global_load_lds_dwordx4 v[172:173], off
	s_barrier
; #define G_STAGE(bufoff, gbase, o0, h64) do { \
;         __builtin_amdgcn_global_load_lds((const unsigned*)((const char*)(gbase) + (o0)), (LAS unsigned*)(lds + (bufoff) + ldsw), 16, 0, 0); \
;         __builtin_amdgcn_global_load_lds((const unsigned*)((const char*)(gbase) + (h64) + (o0)), (LAS unsigned*)(lds + (bufoff) + ldsw + 8192), 16, 0, 0); } while (0)
; #define G_LDA(dst, b, h) do { _Pragma("unroll") for (int m = 0; m < 4; ++m) _Pragma("unroll") for (int k = 0; k < 2; ++k) dst[m][k] = *(const LAS bf16x8*)(lds + G_SA(b, h) + aoff + m * 2048 + k * 1024); } while (0)
; #define G_LDB(dst, b, h) do { _Pragma("unroll") for (int n = 0; n < 2; ++n) _Pragma("unroll") for (int k = 0; k < 2; ++k) dst[n][k] = *(const LAS bf16x8*)(lds + G_SB(b, h) + boff + n * 2048 + k * 1024); } while (0)
; #define G_WAIT_V(n) asm volatile("s_waitcnt vmcnt(" #n ")" ::: "memory")
; #define G_WAIT_L(n) asm volatile("s_waitcnt lgkmcnt(" #n ")" ::: "memory")
; #define G_BAR __builtin_amdgcn_s_barrier()
; #define G_SCHED __builtin_amdgcn_sched_barrier(0)
;     ...
;             G_WAIT_L(8); G_BAR; G_WAIT_L(0); G_MMA(0, 0, At, B0); G_BAR; G_SCHED;
;             G_LDB(B1, 1, 1); G_STAGE(G_SB(1, 0), b3, cB0, qB);
;             G_BAR; G_WAIT_L(0); G_MMA(0, 1, At, B1); G_BAR;
;             G_LDA(At, 1, 1); G_STAGE(G_SA(1, 0), a3, cA0, qA);
;             G_BAR; G_WAIT_L(0); G_MMA(1, 0, At, B0); G_BAR; G_SCHED;
;             G_STAGE(G_SB(1, 1), b3 + chB, cB0, qB);
;             G_WAIT_V(6); G_BAR; G_MMA(1, 1, At, B1); G_BAR;
;         }
	s_waitcnt lgkmcnt(0)
	v_mfma_f32_16x16x32_bf16 v[100:103], v[212:215], v[158:161], v[100:103]
	v_mfma_f32_16x16x32_bf16 v[96:99], v[220:223], v[158:161], v[96:99]
	v_mfma_f32_16x16x32_bf16 v[92:95], v[212:215], v[178:181], v[92:95]
	v_mfma_f32_16x16x32_bf16 v[88:91], v[220:223], v[178:181], v[88:91]
	v_mfma_f32_16x16x32_bf16 v[84:87], v[212:215], v[196:199], v[84:87]
	v_mfma_f32_16x16x32_bf16 v[80:83], v[220:223], v[196:199], v[80:83]
	v_mfma_f32_16x16x32_bf16 v[76:79], v[212:215], v[204:207], v[76:79]
	v_mfma_f32_16x16x32_bf16 v[72:75], v[220:223], v[204:207], v[72:75]
	v_mfma_f32_16x16x32_bf16 v[100:103], v[216:219], v[162:165], v[100:103]
	v_mfma_f32_16x16x32_bf16 v[96:99], v[224:227], v[162:165], v[96:99]
	v_mfma_f32_16x16x32_bf16 v[92:95], v[216:219], v[182:185], v[92:95]
	v_mfma_f32_16x16x32_bf16 v[88:91], v[224:227], v[182:185], v[88:91]
	v_mfma_f32_16x16x32_bf16 v[84:87], v[216:219], v[200:203], v[84:87]
	v_mfma_f32_16x16x32_bf16 v[80:83], v[224:227], v[200:203], v[80:83]
	v_mfma_f32_16x16x32_bf16 v[76:79], v[216:219], v[208:211], v[76:79]
	v_mfma_f32_16x16x32_bf16 v[72:75], v[224:227], v[208:211], v[72:75]
	s_barrier
	s_mov_b32 m0, s26
	v_lshl_add_u64 v[172:173], v[166:167], 0, s[46:47]
	ds_read_b128 v[158:161], v176 offset:49152
	ds_read_b128 v[162:165], v176 offset:50176
	ds_read_b128 v[178:181], v176 offset:51200
	ds_read_b128 v[182:185], v176 offset:52224
	ds_read_b128 v[196:199], v176 offset:53248
	ds_read_b128 v[200:203], v176 offset:54272
	ds_read_b128 v[204:207], v176 offset:55296
	ds_read_b128 v[208:211], v176 offset:56320
	global_load_lds_dwordx4 v[172:173], off
	v_lshl_add_u64 v[166:167], v[166:167], 0, s[66:67]
	s_mov_b32 m0, s27
	s_nop 0
	global_load_lds_dwordx4 v[166:167], off
	s_barrier
	s_waitcnt lgkmcnt(0)
	v_mfma_f32_16x16x32_bf16 v[68:71], v[136:139], v[158:161], v[68:71]
	v_mfma_f32_16x16x32_bf16 v[64:67], v[144:147], v[158:161], v[64:67]
	v_mfma_f32_16x16x32_bf16 v[60:63], v[136:139], v[178:181], v[60:63]
	v_mfma_f32_16x16x32_bf16 v[56:59], v[144:147], v[178:181], v[56:59]
	v_mfma_f32_16x16x32_bf16 v[52:55], v[136:139], v[196:199], v[52:55]
	v_mfma_f32_16x16x32_bf16 v[48:51], v[144:147], v[196:199], v[48:51]
	v_mfma_f32_16x16x32_bf16 v[44:47], v[136:139], v[204:207], v[44:47]
	v_mfma_f32_16x16x32_bf16 v[40:43], v[144:147], v[204:207], v[40:43]
	v_mfma_f32_16x16x32_bf16 v[68:71], v[140:143], v[162:165], v[68:71]
	v_mfma_f32_16x16x32_bf16 v[64:67], v[148:151], v[162:165], v[64:67]
	v_mfma_f32_16x16x32_bf16 v[60:63], v[140:143], v[182:185], v[60:63]
	v_mfma_f32_16x16x32_bf16 v[56:59], v[148:151], v[182:185], v[56:59]
	v_mfma_f32_16x16x32_bf16 v[52:55], v[140:143], v[200:203], v[52:55]
	v_mfma_f32_16x16x32_bf16 v[48:51], v[148:151], v[200:203], v[48:51]
	v_mfma_f32_16x16x32_bf16 v[44:47], v[140:143], v[208:211], v[44:47]
	v_mfma_f32_16x16x32_bf16 v[40:43], v[148:151], v[208:211], v[40:43]
	s_barrier
	s_add_i32 s4, s5, s21
	v_lshl_add_u64 v[136:137], v[2:3], 0, s[50:51]
	s_mov_b32 m0, s4
	v_lshl_add_u64 v[2:3], v[2:3], 0, s[58:59]
	global_load_lds_dwordx4 v[136:137], off
	s_add_i32 m0, s4, 0x2000
	s_nop 0
	global_load_lds_dwordx4 v[2:3], off
	s_add_i32 s18, s18, 2
	s_add_u32 s6, s6, 0x100
	s_addc_u32 s7, s7, 0
	s_add_u32 s8, s8, 0x100
	s_addc_u32 s9, s9, 0
	s_cmp_gt_u32 s18, 5
	s_waitcnt vmcnt(6)
	s_barrier
	v_mfma_f32_16x16x32_bf16 v[36:39], v[212:215], v[158:161], v[36:39]
	v_mfma_f32_16x16x32_bf16 v[32:35], v[220:223], v[158:161], v[32:35]
	v_mfma_f32_16x16x32_bf16 v[28:31], v[212:215], v[178:181], v[28:31]
	v_mfma_f32_16x16x32_bf16 v[24:27], v[220:223], v[178:181], v[24:27]
	v_mfma_f32_16x16x32_bf16 v[20:23], v[212:215], v[196:199], v[20:23]
	v_mfma_f32_16x16x32_bf16 v[16:19], v[220:223], v[196:199], v[16:19]
	v_mfma_f32_16x16x32_bf16 v[12:15], v[212:215], v[204:207], v[12:15]
	v_mfma_f32_16x16x32_bf16 v[8:11], v[220:223], v[204:207], v[8:11]
	v_mfma_f32_16x16x32_bf16 v[36:39], v[216:219], v[162:165], v[36:39]
	v_mfma_f32_16x16x32_bf16 v[32:35], v[224:227], v[162:165], v[32:35]
	v_mfma_f32_16x16x32_bf16 v[28:31], v[216:219], v[182:185], v[28:31]
	v_mfma_f32_16x16x32_bf16 v[24:27], v[224:227], v[182:185], v[24:27]
	v_mfma_f32_16x16x32_bf16 v[20:23], v[216:219], v[200:203], v[20:23]
	v_mfma_f32_16x16x32_bf16 v[16:19], v[224:227], v[200:203], v[16:19]
	v_mfma_f32_16x16x32_bf16 v[12:15], v[216:219], v[208:211], v[12:15]
	v_mfma_f32_16x16x32_bf16 v[8:11], v[224:227], v[208:211], v[8:11]
	s_cbranch_scc0 .Ldb_MG1_cont
	v_readfirstlane_b32 s101, v186
	s_cmpk_gt_u32 s101, 0xff
	s_cbranch_scc1 .Ldb_MG1_exit
	s_barrier
	s_branch .Ldb_MG1_exit

; #define G_STAGE(bufoff, gbase, o0, h64) do { \
;         __builtin_amdgcn_global_load_lds((const unsigned*)((const char*)(gbase) + (o0)), (LAS unsigned*)(lds + (bufoff) + ldsw), 16, 0, 0); \
;         __builtin_amdgcn_global_load_lds((const unsigned*)((const char*)(gbase) + (h64) + (o0)), (LAS unsigned*)(lds + (bufoff) + ldsw + 8192), 16, 0, 0); } while (0)
; #define G_LDA(dst, b, h) do { _Pragma("unroll") for (int m = 0; m < 4; ++m) _Pragma("unroll") for (int k = 0; k < 2; ++k) dst[m][k] = *(const LAS bf16x8*)(lds + G_SA(b, h) + aoff + m * 2048 + k * 1024); } while (0)
; #define G_LDB(dst, b, h) do { _Pragma("unroll") for (int n = 0; n < 2; ++n) _Pragma("unroll") for (int k = 0; k < 2; ++k) dst[n][k] = *(const LAS bf16x8*)(lds + G_SB(b, h) + boff + n * 2048 + k * 1024); } while (0)
; #define G_WAIT_L(n) asm volatile("s_waitcnt lgkmcnt(" #n ")" ::: "memory")
; #define G_BAR __builtin_amdgcn_s_barrier()
; #define G_SCHED __builtin_amdgcn_sched_barrier(0)
;     ...
;         for (int t = 0; t < nt; t += 2) {
;             const bool last = (t == nt - 2);
;             const char* a1 = cA + (size_t)(t + 1) * ckA;
;             const char* a2 = last ? nA : cA + (size_t)(t + 2) * ckA; const char* b2 = last ? nB : cB + (size_t)(t + 2) * kB;
;             const char* a3 = a2 + ckA; const char* b3 = b2 + kB;
;             G_LDB(B0, 0, 0); G_SCHED; G_LDA(At, 0, 0); G_STAGE(G_SA(1, 1), a1 + chA, cA0, qA);
;             G_WAIT_L(8); G_BAR; G_WAIT_L(0); G_MMA(0, 0, At, B0); G_BAR; G_SCHED;
;             G_LDB(B1, 0, 1); G_STAGE(G_SB(0, 0), b2, cB0, qB);
;             G_BAR; G_WAIT_L(0); G_MMA(0, 1, At, B1); G_BAR;
;             G_LDA(At, 0, 1); G_STAGE(G_SA(0, 0), a2, cA0, qA);
;             G_BAR; G_WAIT_L(0); G_MMA(1, 0, At, B0); G_BAR; G_SCHED;
.Ldbj_WOUT_in:
.LBB0_1037:
	s_add_u32 s4, s2, 0xfffc0080
	s_addc_u32 s5, s3, -1
	s_add_i32 s33, 0, 0x10000
	v_add_u32_e32 v0, s33, v181
	ds_read_b128 v[136:139], v0
	ds_read_b128 v[140:143], v0 offset:1024
	ds_read_b128 v[144:147], v0 offset:2048
	ds_read_b128 v[148:151], v0 offset:3072
	s_cmp_eq_u32 s15, 12
	s_cselect_b32 s5, s17, s5
	s_cselect_b32 s4, s16, s4
	s_cselect_b32 s21, s19, s7
	s_cselect_b32 s20, s18, s6
	v_lshl_add_u64 v[184:185], s[2:3], 0, v[166:167]
	s_add_i32 m0, s24, 0xc000
	ds_read_b128 v[152:155], v182
	ds_read_b128 v[156:159], v182 offset:1024
	ds_read_b128 v[160:163], v182 offset:2048
	ds_read_b128 v[172:175], v182 offset:3072
	ds_read_b128 v[176:179], v182 offset:4096
	ds_read_b128 v[196:199], v182 offset:5120
	ds_read_b128 v[200:203], v182 offset:6144
	ds_read_b128 v[204:207], v182 offset:7168
	global_load_lds_dwordx4 v[184:185], off
	v_lshl_add_u64 v[184:185], v[184:185], 0, s[0:1]
	s_add_i32 m0, s24, 0xe000
	s_nop 0
	global_load_lds_dwordx4 v[184:185], off
	s_waitcnt lgkmcnt(8)
	s_barrier
	s_waitcnt lgkmcnt(0)
	v_mfma_f32_16x16x32_bf16 v[132:135], v[136:139], v[152:155], v[132:135]
	v_mfma_f32_16x16x32_bf16 v[128:131], v[144:147], v[152:155], v[128:131]
	v_mfma_f32_16x16x32_bf16 v[116:119], v[136:139], v[160:163], v[116:119]
	v_mfma_f32_16x16x32_bf16 v[112:115], v[144:147], v[160:163], v[112:115]
	v_mfma_f32_16x16x32_bf16 v[100:103], v[136:139], v[176:179], v[100:103]
	v_mfma_f32_16x16x32_bf16 v[96:99], v[144:147], v[176:179], v[96:99]
	v_mfma_f32_16x16x32_bf16 v[84:87], v[136:139], v[200:203], v[84:87]
	v_mfma_f32_16x16x32_bf16 v[80:83], v[144:147], v[200:203], v[80:83]
	v_mfma_f32_16x16x32_bf16 v[132:135], v[140:143], v[156:159], v[132:135]
	v_mfma_f32_16x16x32_bf16 v[128:131], v[148:151], v[156:159], v[128:131]
	v_mfma_f32_16x16x32_bf16 v[116:119], v[140:143], v[172:175], v[116:119]
	v_mfma_f32_16x16x32_bf16 v[112:115], v[148:151], v[172:175], v[112:115]
	v_mfma_f32_16x16x32_bf16 v[100:103], v[140:143], v[196:199], v[100:103]
	v_mfma_f32_16x16x32_bf16 v[96:99], v[148:151], v[196:199], v[96:99]
	v_mfma_f32_16x16x32_bf16 v[84:87], v[140:143], v[204:207], v[84:87]
	v_mfma_f32_16x16x32_bf16 v[80:83], v[148:151], v[204:207], v[80:83]
	s_barrier
	s_add_i32 s41, 0, 0x14000
	v_lshl_add_u64 v[184:185], s[20:21], 0, v[164:165]
	s_add_i32 s20, s33, s23
	v_add_u32_e32 v0, s41, v181
	s_mov_b32 m0, s20
	ds_read_b128 v[208:211], v0
	ds_read_b128 v[212:215], v0 offset:1024
	ds_read_b128 v[216:219], v0 offset:2048
	ds_read_b128 v[220:223], v0 offset:3072
	global_load_lds_dwordx4 v[184:185], off
	v_lshl_add_u64 v[224:225], v[184:185], 0, s[0:1]
	s_add_i32 m0, s20, 0x2000
	s_nop 0
	global_load_lds_dwordx4 v[224:225], off
	s_barrier
	s_waitcnt lgkmcnt(0)
	v_mfma_f32_16x16x32_bf16 v[124:127], v[208:211], v[152:155], v[124:127]
	v_mfma_f32_16x16x32_bf16 v[120:123], v[216:219], v[152:155], v[120:123]
	v_mfma_f32_16x16x32_bf16 v[108:111], v[208:211], v[160:163], v[108:111]
	v_mfma_f32_16x16x32_bf16 v[104:107], v[216:219], v[160:163], v[104:107]
	v_mfma_f32_16x16x32_bf16 v[92:95], v[208:211], v[176:179], v[92:95]
	v_mfma_f32_16x16x32_bf16 v[88:91], v[216:219], v[176:179], v[88:91]
	v_mfma_f32_16x16x32_bf16 v[76:79], v[208:211], v[200:203], v[76:79]
	v_mfma_f32_16x16x32_bf16 v[72:75], v[216:219], v[200:203], v[72:75]
	v_mfma_f32_16x16x32_bf16 v[124:127], v[212:215], v[156:159], v[124:127]
	v_mfma_f32_16x16x32_bf16 v[120:123], v[220:223], v[156:159], v[120:123]
	v_mfma_f32_16x16x32_bf16 v[108:111], v[212:215], v[172:175], v[108:111]
	v_mfma_f32_16x16x32_bf16 v[104:107], v[220:223], v[172:175], v[104:107]
	v_mfma_f32_16x16x32_bf16 v[92:95], v[212:215], v[196:199], v[92:95]
	v_mfma_f32_16x16x32_bf16 v[88:91], v[220:223], v[196:199], v[88:91]
	v_mfma_f32_16x16x32_bf16 v[76:79], v[212:215], v[204:207], v[76:79]
	v_mfma_f32_16x16x32_bf16 v[72:75], v[220:223], v[204:207], v[72:75]
	s_barrier
	s_mov_b32 m0, s24
	v_lshl_add_u64 v[224:225], s[4:5], 0, v[2:3]
	ds_read_b128 v[152:155], v182 offset:16384
	ds_read_b128 v[156:159], v182 offset:17408
	ds_read_b128 v[160:163], v182 offset:18432
	ds_read_b128 v[172:175], v182 offset:19456
	ds_read_b128 v[176:179], v182 offset:20480
	ds_read_b128 v[196:199], v182 offset:21504
	ds_read_b128 v[200:203], v182 offset:22528
	ds_read_b128 v[204:207], v182 offset:23552
	global_load_lds_dwordx4 v[224:225], off
	v_lshl_add_u64 v[226:227], v[224:225], 0, s[0:1]
	s_mov_b32 m0, s25
	s_nop 0
	global_load_lds_dwordx4 v[226:227], off
	s_barrier
	s_waitcnt lgkmcnt(0)
	v_mfma_f32_16x16x32_bf16 v[68:71], v[136:139], v[152:155], v[68:71]
	v_mfma_f32_16x16x32_bf16 v[64:67], v[144:147], v[152:155], v[64:67]
	v_mfma_f32_16x16x32_bf16 v[52:55], v[136:139], v[160:163], v[52:55]
	v_mfma_f32_16x16x32_bf16 v[48:51], v[144:147], v[160:163], v[48:51]
	v_mfma_f32_16x16x32_bf16 v[36:39], v[136:139], v[176:179], v[36:39]
	v_mfma_f32_16x16x32_bf16 v[32:35], v[144:147], v[176:179], v[32:35]
	v_mfma_f32_16x16x32_bf16 v[20:23], v[136:139], v[200:203], v[20:23]
	v_mfma_f32_16x16x32_bf16 v[16:19], v[144:147], v[200:203], v[16:19]
	v_mfma_f32_16x16x32_bf16 v[68:71], v[140:143], v[156:159], v[68:71]
	v_mfma_f32_16x16x32_bf16 v[64:67], v[148:151], v[156:159], v[64:67]
	v_mfma_f32_16x16x32_bf16 v[52:55], v[140:143], v[172:175], v[52:55]
	v_mfma_f32_16x16x32_bf16 v[48:51], v[148:151], v[172:175], v[48:51]
	v_mfma_f32_16x16x32_bf16 v[36:39], v[140:143], v[196:199], v[36:39]
	v_mfma_f32_16x16x32_bf16 v[32:35], v[148:151], v[196:199], v[32:35]
	v_mfma_f32_16x16x32_bf16 v[20:23], v[140:143], v[204:207], v[20:23]
	v_mfma_f32_16x16x32_bf16 v[16:19], v[148:151], v[204:207], v[16:19]
	s_barrier
; #define G_STAGE(bufoff, gbase, o0, h64) do { \
;         __builtin_amdgcn_global_load_lds((const unsigned*)((const char*)(gbase) + (o0)), (LAS unsigned*)(lds + (bufoff) + ldsw), 16, 0, 0); \
;         __builtin_amdgcn_global_load_lds((const unsigned*)((const char*)(gbase) + (h64) + (o0)), (LAS unsigned*)(lds + (bufoff) + ldsw + 8192), 16, 0, 0); } while (0)
; #define G_LDA(dst, b, h) do { _Pragma("unroll") for (int m = 0; m < 4; ++m) _Pragma("unroll") for (int k = 0; k < 2; ++k) dst[m][k] = *(const LAS bf16x8*)(lds + G_SA(b, h) + aoff + m * 2048 + k * 1024); } while (0)
; #define G_LDB(dst, b, h) do { _Pragma("unroll") for (int n = 0; n < 2; ++n) _Pragma("unroll") for (int k = 0; k < 2; ++k) dst[n][k] = *(const LAS bf16x8*)(lds + G_SB(b, h) + boff + n * 2048 + k * 1024); } while (0)
; #define G_WAIT_V(n) asm volatile("s_waitcnt vmcnt(" #n ")" ::: "memory")
; #define G_WAIT_L(n) asm volatile("s_waitcnt lgkmcnt(" #n ")" ::: "memory")
; #define G_BAR __builtin_amdgcn_s_barrier()
; #define G_SCHED __builtin_amdgcn_sched_barrier(0)
;     ...
;             G_STAGE(G_SB(0, 1), b2 + chB, cB0, qB);
;             G_WAIT_V(6); G_BAR; G_MMA(1, 1, At, B1); G_BAR;
;             G_LDB(B0, 1, 0); G_SCHED; G_LDA(At, 1, 0); G_STAGE(G_SA(0, 1), a2 + chA, cA0, qA);
;             G_WAIT_L(8); G_BAR; G_WAIT_L(0); G_MMA(0, 0, At, B0); G_BAR; G_SCHED;
;             G_LDB(B1, 1, 1); G_STAGE(G_SB(1, 0), b3, cB0, qB);
	s_add_i32 s4, s41, s23
	v_lshl_add_u64 v[136:137], v[184:185], 0, s[42:43]
	s_mov_b32 m0, s4
	s_nop 0
	global_load_lds_dwordx4 v[136:137], off
	v_lshl_add_u64 v[136:137], v[184:185], 0, s[50:51]
	s_add_i32 m0, s4, 0x2000
	s_nop 0
	global_load_lds_dwordx4 v[136:137], off
	s_waitcnt vmcnt(6)
	s_barrier
	v_mfma_f32_16x16x32_bf16 v[60:63], v[208:211], v[152:155], v[60:63]
	v_mfma_f32_16x16x32_bf16 v[56:59], v[216:219], v[152:155], v[56:59]
	v_mfma_f32_16x16x32_bf16 v[44:47], v[208:211], v[160:163], v[44:47]
	v_mfma_f32_16x16x32_bf16 v[40:43], v[216:219], v[160:163], v[40:43]
	v_mfma_f32_16x16x32_bf16 v[28:31], v[208:211], v[176:179], v[28:31]
	v_mfma_f32_16x16x32_bf16 v[24:27], v[216:219], v[176:179], v[24:27]
	v_mfma_f32_16x16x32_bf16 v[12:15], v[208:211], v[200:203], v[12:15]
	v_mfma_f32_16x16x32_bf16 v[8:11], v[216:219], v[200:203], v[8:11]
	v_mfma_f32_16x16x32_bf16 v[60:63], v[212:215], v[156:159], v[60:63]
	v_mfma_f32_16x16x32_bf16 v[56:59], v[220:223], v[156:159], v[56:59]
	v_mfma_f32_16x16x32_bf16 v[44:47], v[212:215], v[172:175], v[44:47]
	v_mfma_f32_16x16x32_bf16 v[40:43], v[220:223], v[172:175], v[40:43]
	v_mfma_f32_16x16x32_bf16 v[28:31], v[212:215], v[196:199], v[28:31]
	v_mfma_f32_16x16x32_bf16 v[24:27], v[220:223], v[196:199], v[24:27]
	v_mfma_f32_16x16x32_bf16 v[12:15], v[212:215], v[204:207], v[12:15]
	v_mfma_f32_16x16x32_bf16 v[8:11], v[220:223], v[204:207], v[8:11]
	s_barrier
	s_add_i32 s4, 0, 0x18000
	v_add_u32_e32 v0, s4, v181
	ds_read_b128 v[136:139], v0
	ds_read_b128 v[140:143], v0 offset:1024
	ds_read_b128 v[144:147], v0 offset:2048
	ds_read_b128 v[148:151], v0 offset:3072
	s_mov_b32 m0, s26
	v_lshl_add_u64 v[208:209], v[224:225], 0, s[42:43]
	ds_read_b128 v[152:155], v182 offset:32768
	ds_read_b128 v[156:159], v182 offset:33792
	ds_read_b128 v[160:163], v182 offset:34816
	ds_read_b128 v[172:175], v182 offset:35840
	ds_read_b128 v[176:179], v182 offset:36864
	ds_read_b128 v[196:199], v182 offset:37888
	ds_read_b128 v[200:203], v182 offset:38912
	ds_read_b128 v[204:207], v182 offset:39936
	global_load_lds_dwordx4 v[208:209], off
	v_lshl_add_u64 v[208:209], v[224:225], 0, s[50:51]
	s_mov_b32 m0, s27
	s_nop 0
	global_load_lds_dwordx4 v[208:209], off
	s_waitcnt lgkmcnt(8)
	s_barrier
	s_waitcnt lgkmcnt(0)
	v_mfma_f32_16x16x32_bf16 v[132:135], v[136:139], v[152:155], v[132:135]
	v_mfma_f32_16x16x32_bf16 v[128:131], v[144:147], v[152:155], v[128:131]
	v_mfma_f32_16x16x32_bf16 v[116:119], v[136:139], v[160:163], v[116:119]
	v_mfma_f32_16x16x32_bf16 v[112:115], v[144:147], v[160:163], v[112:115]
	v_mfma_f32_16x16x32_bf16 v[100:103], v[136:139], v[176:179], v[100:103]
	v_mfma_f32_16x16x32_bf16 v[96:99], v[144:147], v[176:179], v[96:99]
	v_mfma_f32_16x16x32_bf16 v[84:87], v[136:139], v[200:203], v[84:87]
	v_mfma_f32_16x16x32_bf16 v[80:83], v[144:147], v[200:203], v[80:83]
	v_mfma_f32_16x16x32_bf16 v[132:135], v[140:143], v[156:159], v[132:135]
	v_mfma_f32_16x16x32_bf16 v[128:131], v[148:151], v[156:159], v[128:131]
	v_mfma_f32_16x16x32_bf16 v[116:119], v[140:143], v[172:175], v[116:119]
	v_mfma_f32_16x16x32_bf16 v[112:115], v[148:151], v[172:175], v[112:115]
	v_mfma_f32_16x16x32_bf16 v[100:103], v[140:143], v[196:199], v[100:103]
	v_mfma_f32_16x16x32_bf16 v[96:99], v[148:151], v[196:199], v[96:99]
	v_mfma_f32_16x16x32_bf16 v[84:87], v[140:143], v[204:207], v[84:87]
	v_mfma_f32_16x16x32_bf16 v[80:83], v[148:151], v[204:207], v[80:83]
	s_barrier
	s_add_i32 s5, 0, 0x1c000
	s_add_i32 s4, s4, s23
	v_add_u32_e32 v0, s5, v181
	v_lshl_add_u64 v[226:227], v[184:185], 0, s[46:47]
	s_mov_b32 m0, s4
	ds_read_b128 v[208:211], v0
	ds_read_b128 v[212:215], v0 offset:1024
	ds_read_b128 v[216:219], v0 offset:2048
	ds_read_b128 v[220:223], v0 offset:3072
	global_load_lds_dwordx4 v[226:227], off
	v_lshl_add_u64 v[226:227], v[184:185], 0, s[52:53]
	s_add_i32 m0, s4, 0x2000
	s_nop 0
	global_load_lds_dwordx4 v[226:227], off
	s_barrier
; #define G_STAGE(bufoff, gbase, o0, h64) do { \
;         __builtin_amdgcn_global_load_lds((const unsigned*)((const char*)(gbase) + (o0)), (LAS unsigned*)(lds + (bufoff) + ldsw), 16, 0, 0); \
;         __builtin_amdgcn_global_load_lds((const unsigned*)((const char*)(gbase) + (h64) + (o0)), (LAS unsigned*)(lds + (bufoff) + ldsw + 8192), 16, 0, 0); } while (0)
; #define G_LDA(dst, b, h) do { _Pragma("unroll") for (int m = 0; m < 4; ++m) _Pragma("unroll") for (int k = 0; k < 2; ++k) dst[m][k] = *(const LAS bf16x8*)(lds + G_SA(b, h) + aoff + m * 2048 + k * 1024); } while (0)
; #define G_LDB(dst, b, h) do { _Pragma("unroll") for (int n = 0; n < 2; ++n) _Pragma("unroll") for (int k = 0; k < 2; ++k) dst[n][k] = *(const LAS bf16x8*)(lds + G_SB(b, h) + boff + n * 2048 + k * 1024); } while (0)
; #define G_WAIT_V(n) asm volatile("s_waitcnt vmcnt(" #n ")" ::: "memory")
; #define G_WAIT_L(n) asm volatile("s_waitcnt lgkmcnt(" #n ")" ::: "memory")
; #define G_BAR __builtin_amdgcn_s_barrier()
; #define G_SCHED __builtin_amdgcn_sched_barrier(0)
;     ...
;             G_WAIT_L(8); G_BAR; G_WAIT_L(0); G_MMA(0, 0, At, B0); G_BAR; G_SCHED;
;             G_LDB(B1, 1, 1); G_STAGE(G_SB(1, 0), b3, cB0, qB);
;             G_BAR; G_WAIT_L(0); G_MMA(0, 1, At, B1); G_BAR;
;             G_LDA(At, 1, 1); G_STAGE(G_SA(1, 0), a3, cA0, qA);
;             G_BAR; G_WAIT_L(0); G_MMA(1, 0, At, B0); G_BAR; G_SCHED;
;             G_STAGE(G_SB(1, 1), b3 + chB, cB0, qB);
;             G_WAIT_V(6); G_BAR; G_MMA(1, 1, At, B1); G_BAR;
;         }
	s_waitcnt lgkmcnt(0)
	v_mfma_f32_16x16x32_bf16 v[124:127], v[208:211], v[152:155], v[124:127]
	v_mfma_f32_16x16x32_bf16 v[120:123], v[216:219], v[152:155], v[120:123]
	v_mfma_f32_16x16x32_bf16 v[108:111], v[208:211], v[160:163], v[108:111]
	v_mfma_f32_16x16x32_bf16 v[104:107], v[216:219], v[160:163], v[104:107]
	v_mfma_f32_16x16x32_bf16 v[92:95], v[208:211], v[176:179], v[92:95]
	v_mfma_f32_16x16x32_bf16 v[88:91], v[216:219], v[176:179], v[88:91]
	v_mfma_f32_16x16x32_bf16 v[76:79], v[208:211], v[200:203], v[76:79]
	v_mfma_f32_16x16x32_bf16 v[72:75], v[216:219], v[200:203], v[72:75]
	v_mfma_f32_16x16x32_bf16 v[124:127], v[212:215], v[156:159], v[124:127]
	v_mfma_f32_16x16x32_bf16 v[120:123], v[220:223], v[156:159], v[120:123]
	v_mfma_f32_16x16x32_bf16 v[108:111], v[212:215], v[172:175], v[108:111]
	v_mfma_f32_16x16x32_bf16 v[104:107], v[220:223], v[172:175], v[104:107]
	v_mfma_f32_16x16x32_bf16 v[92:95], v[212:215], v[196:199], v[92:95]
	v_mfma_f32_16x16x32_bf16 v[88:91], v[220:223], v[196:199], v[88:91]
	v_mfma_f32_16x16x32_bf16 v[76:79], v[212:215], v[204:207], v[76:79]
	v_mfma_f32_16x16x32_bf16 v[72:75], v[220:223], v[204:207], v[72:75]
	s_barrier
	s_mov_b32 m0, s29
	v_lshl_add_u64 v[226:227], v[224:225], 0, s[46:47]
	ds_read_b128 v[152:155], v182 offset:49152
	ds_read_b128 v[156:159], v182 offset:50176
	ds_read_b128 v[160:163], v182 offset:51200
	ds_read_b128 v[172:175], v182 offset:52224
	ds_read_b128 v[176:179], v182 offset:53248
	ds_read_b128 v[196:199], v182 offset:54272
	ds_read_b128 v[200:203], v182 offset:55296
	ds_read_b128 v[204:207], v182 offset:56320
	global_load_lds_dwordx4 v[226:227], off
	v_lshl_add_u64 v[224:225], v[224:225], 0, s[52:53]
	s_mov_b32 m0, s30
	s_nop 0
	global_load_lds_dwordx4 v[224:225], off
	s_barrier
	s_waitcnt lgkmcnt(0)
	v_mfma_f32_16x16x32_bf16 v[68:71], v[136:139], v[152:155], v[68:71]
	v_mfma_f32_16x16x32_bf16 v[64:67], v[144:147], v[152:155], v[64:67]
	v_mfma_f32_16x16x32_bf16 v[52:55], v[136:139], v[160:163], v[52:55]
	v_mfma_f32_16x16x32_bf16 v[48:51], v[144:147], v[160:163], v[48:51]
	v_mfma_f32_16x16x32_bf16 v[36:39], v[136:139], v[176:179], v[36:39]
	v_mfma_f32_16x16x32_bf16 v[32:35], v[144:147], v[176:179], v[32:35]
	v_mfma_f32_16x16x32_bf16 v[20:23], v[136:139], v[200:203], v[20:23]
	v_mfma_f32_16x16x32_bf16 v[16:19], v[144:147], v[200:203], v[16:19]
	v_mfma_f32_16x16x32_bf16 v[68:71], v[140:143], v[156:159], v[68:71]
	v_mfma_f32_16x16x32_bf16 v[64:67], v[148:151], v[156:159], v[64:67]
	v_mfma_f32_16x16x32_bf16 v[52:55], v[140:143], v[172:175], v[52:55]
	v_mfma_f32_16x16x32_bf16 v[48:51], v[148:151], v[172:175], v[48:51]
	v_mfma_f32_16x16x32_bf16 v[36:39], v[140:143], v[196:199], v[36:39]
	v_mfma_f32_16x16x32_bf16 v[32:35], v[148:151], v[196:199], v[32:35]
	v_mfma_f32_16x16x32_bf16 v[20:23], v[140:143], v[204:207], v[20:23]
	v_mfma_f32_16x16x32_bf16 v[16:19], v[148:151], v[204:207], v[16:19]
	s_barrier
	s_add_i32 s4, s5, s23
	v_lshl_add_u64 v[136:137], v[184:185], 0, s[54:55]
	s_mov_b32 m0, s4
	s_nop 0
	global_load_lds_dwordx4 v[136:137], off
	v_lshl_add_u64 v[136:137], v[184:185], 0, s[58:59]
	s_add_i32 m0, s4, 0x2000
	s_nop 0
	global_load_lds_dwordx4 v[136:137], off
	s_add_i32 s15, s15, 2
	s_add_u32 s2, s2, 0x100
	s_addc_u32 s3, s3, 0
	s_add_u32 s6, s6, 0x100
	s_addc_u32 s7, s7, 0
	s_cmp_gt_u32 s15, 13
	s_waitcnt vmcnt(6)
	s_barrier
	v_mfma_f32_16x16x32_bf16 v[60:63], v[208:211], v[152:155], v[60:63]
	v_mfma_f32_16x16x32_bf16 v[56:59], v[216:219], v[152:155], v[56:59]
	v_mfma_f32_16x16x32_bf16 v[44:47], v[208:211], v[160:163], v[44:47]
	v_mfma_f32_16x16x32_bf16 v[40:43], v[216:219], v[160:163], v[40:43]
	v_mfma_f32_16x16x32_bf16 v[28:31], v[208:211], v[176:179], v[28:31]
	v_mfma_f32_16x16x32_bf16 v[24:27], v[216:219], v[176:179], v[24:27]
	v_mfma_f32_16x16x32_bf16 v[12:15], v[208:211], v[200:203], v[12:15]
	v_mfma_f32_16x16x32_bf16 v[8:11], v[216:219], v[200:203], v[8:11]
	v_mfma_f32_16x16x32_bf16 v[60:63], v[212:215], v[156:159], v[60:63]
	v_mfma_f32_16x16x32_bf16 v[56:59], v[220:223], v[156:159], v[56:59]
	v_mfma_f32_16x16x32_bf16 v[44:47], v[212:215], v[172:175], v[44:47]
	v_mfma_f32_16x16x32_bf16 v[40:43], v[220:223], v[172:175], v[40:43]
	v_mfma_f32_16x16x32_bf16 v[28:31], v[212:215], v[196:199], v[28:31]
	v_mfma_f32_16x16x32_bf16 v[24:27], v[220:223], v[196:199], v[24:27]
	v_mfma_f32_16x16x32_bf16 v[12:15], v[212:215], v[204:207], v[12:15]
	v_mfma_f32_16x16x32_bf16 v[8:11], v[220:223], v[204:207], v[8:11]
	s_cbranch_scc0 .Ldb_WOUT_cont
	v_readfirstlane_b32 s101, v186
	s_cmpk_gt_u32 s101, 0xff
	s_cbranch_scc1 .Ldb_WOUT_exit
	s_barrier
	s_branch .Ldb_WOUT_exit

; #define G_STAGE(bufoff, gbase, o0, h64) do { \
;         __builtin_amdgcn_global_load_lds((const unsigned*)((const char*)(gbase) + (o0)), (LAS unsigned*)(lds + (bufoff) + ldsw), 16, 0, 0); \
;         __builtin_amdgcn_global_load_lds((const unsigned*)((const char*)(gbase) + (h64) + (o0)), (LAS unsigned*)(lds + (bufoff) + ldsw + 8192), 16, 0, 0); } while (0)
; #define G_LDA(dst, b, h) do { _Pragma("unroll") for (int m = 0; m < 4; ++m) _Pragma("unroll") for (int k = 0; k < 2; ++k) dst[m][k] = *(const LAS bf16x8*)(lds + G_SA(b, h) + aoff + m * 2048 + k * 1024); } while (0)
; #define G_LDB(dst, b, h) do { _Pragma("unroll") for (int n = 0; n < 2; ++n) _Pragma("unroll") for (int k = 0; k < 2; ++k) dst[n][k] = *(const LAS bf16x8*)(lds + G_SB(b, h) + boff + n * 2048 + k * 1024); } while (0)
; #define G_WAIT_L(n) asm volatile("s_waitcnt lgkmcnt(" #n ")" ::: "memory")
; #define G_BAR __builtin_amdgcn_s_barrier()
; #define G_SCHED __builtin_amdgcn_sched_barrier(0)
;     ...
;         for (int t = 0; t < nt; t += 2) {
;             const bool last = (t == nt - 2);
;             const char* a1 = cA + (size_t)(t + 1) * ckA;
;             const char* a2 = last ? nA : cA + (size_t)(t + 2) * ckA; const char* b2 = last ? nB : cB + (size_t)(t + 2) * kB;
;             const char* a3 = a2 + ckA; const char* b3 = b2 + kB;
;             G_LDB(B0, 0, 0); G_SCHED; G_LDA(At, 0, 0); G_STAGE(G_SA(1, 1), a1 + chA, cA0, qA);
;             G_WAIT_L(8); G_BAR; G_WAIT_L(0); G_MMA(0, 0, At, B0); G_BAR; G_SCHED;
;             G_LDB(B1, 0, 1); G_STAGE(G_SB(0, 0), b2, cB0, qB);
;             G_BAR; G_WAIT_L(0); G_MMA(0, 1, At, B1); G_BAR;
;             G_LDA(At, 0, 1); G_STAGE(G_SA(0, 0), a2, cA0, qA);
;             G_BAR; G_WAIT_L(0); G_MMA(1, 0, At, B0); G_BAR; G_SCHED;
.Ldbj_FFI_in:
.LBB0_1120:
	s_add_u32 s4, s2, 0xfffc0080
	s_addc_u32 s5, s3, -1
	s_add_i32 s19, 0, 0x10000
	v_add_u32_e32 v0, s19, v149
	ds_read_b128 v[140:143], v0
	ds_read_b128 v[144:147], v0 offset:1024
	ds_read_b128 v[152:155], v0 offset:2048
	ds_read_b128 v[156:159], v0 offset:3072
	s_cmp_eq_u32 s18, 12
	s_cselect_b32 s5, s13, s5
	s_cselect_b32 s4, s12, s4
	s_cselect_b32 s41, s15, s17
	s_cselect_b32 s40, s14, s16
	v_lshl_add_u64 v[184:185], s[2:3], 0, v[138:139]
	s_add_i32 m0, s26, 0xc000
	ds_read_b128 v[160:163], v150
	ds_read_b128 v[164:167], v150 offset:1024
	ds_read_b128 v[172:175], v150 offset:2048
	ds_read_b128 v[176:179], v150 offset:3072
	ds_read_b128 v[180:183], v150 offset:4096
	ds_read_b128 v[196:199], v150 offset:5120
	ds_read_b128 v[200:203], v150 offset:6144
	ds_read_b128 v[204:207], v150 offset:7168
	global_load_lds_dwordx4 v[184:185], off
	v_lshl_add_u64 v[184:185], v[184:185], 0, s[0:1]
	s_add_i32 m0, s26, 0xe000
	s_nop 0
	global_load_lds_dwordx4 v[184:185], off
	s_waitcnt lgkmcnt(8)
	s_barrier
	s_waitcnt lgkmcnt(0)
	v_mfma_f32_16x16x32_bf16 v[132:135], v[140:143], v[160:163], v[132:135]
	v_mfma_f32_16x16x32_bf16 v[124:127], v[152:155], v[160:163], v[124:127]
	v_mfma_f32_16x16x32_bf16 v[116:119], v[140:143], v[172:175], v[116:119]
	v_mfma_f32_16x16x32_bf16 v[108:111], v[152:155], v[172:175], v[108:111]
	v_mfma_f32_16x16x32_bf16 v[100:103], v[140:143], v[180:183], v[100:103]
	v_mfma_f32_16x16x32_bf16 v[92:95], v[152:155], v[180:183], v[92:95]
	v_mfma_f32_16x16x32_bf16 v[84:87], v[140:143], v[200:203], v[84:87]
	v_mfma_f32_16x16x32_bf16 v[76:79], v[152:155], v[200:203], v[76:79]
	v_mfma_f32_16x16x32_bf16 v[132:135], v[144:147], v[164:167], v[132:135]
	v_mfma_f32_16x16x32_bf16 v[124:127], v[156:159], v[164:167], v[124:127]
	v_mfma_f32_16x16x32_bf16 v[116:119], v[144:147], v[176:179], v[116:119]
	v_mfma_f32_16x16x32_bf16 v[108:111], v[156:159], v[176:179], v[108:111]
	v_mfma_f32_16x16x32_bf16 v[100:103], v[144:147], v[196:199], v[100:103]
	v_mfma_f32_16x16x32_bf16 v[92:95], v[156:159], v[196:199], v[92:95]
	v_mfma_f32_16x16x32_bf16 v[84:87], v[144:147], v[204:207], v[84:87]
	v_mfma_f32_16x16x32_bf16 v[76:79], v[156:159], v[204:207], v[76:79]
	s_barrier
	s_add_i32 s39, 0, 0x14000
	s_add_i32 s19, s19, s21
	v_add_u32_e32 v0, s39, v149
	v_lshl_add_u64 v[184:185], s[40:41], 0, v[2:3]
	s_mov_b32 m0, s19
	ds_read_b128 v[208:211], v0
	ds_read_b128 v[212:215], v0 offset:1024
	ds_read_b128 v[216:219], v0 offset:2048
	ds_read_b128 v[220:223], v0 offset:3072
	global_load_lds_dwordx4 v[184:185], off
	v_lshl_add_u64 v[224:225], v[184:185], 0, s[0:1]
	s_add_i32 m0, s19, 0x2000
	s_nop 0
	global_load_lds_dwordx4 v[224:225], off
	s_barrier
	s_waitcnt lgkmcnt(0)
	v_mfma_f32_16x16x32_bf16 v[128:131], v[208:211], v[160:163], v[128:131]
	v_mfma_f32_16x16x32_bf16 v[120:123], v[216:219], v[160:163], v[120:123]
	v_mfma_f32_16x16x32_bf16 v[112:115], v[208:211], v[172:175], v[112:115]
	v_mfma_f32_16x16x32_bf16 v[104:107], v[216:219], v[172:175], v[104:107]
	v_mfma_f32_16x16x32_bf16 v[96:99], v[208:211], v[180:183], v[96:99]
	v_mfma_f32_16x16x32_bf16 v[88:91], v[216:219], v[180:183], v[88:91]
	v_mfma_f32_16x16x32_bf16 v[80:83], v[208:211], v[200:203], v[80:83]
	v_mfma_f32_16x16x32_bf16 v[72:75], v[216:219], v[200:203], v[72:75]
	v_mfma_f32_16x16x32_bf16 v[128:131], v[212:215], v[164:167], v[128:131]
	v_mfma_f32_16x16x32_bf16 v[120:123], v[220:223], v[164:167], v[120:123]
	v_mfma_f32_16x16x32_bf16 v[112:115], v[212:215], v[176:179], v[112:115]
	v_mfma_f32_16x16x32_bf16 v[104:107], v[220:223], v[176:179], v[104:107]
	v_mfma_f32_16x16x32_bf16 v[96:99], v[212:215], v[196:199], v[96:99]
	v_mfma_f32_16x16x32_bf16 v[88:91], v[220:223], v[196:199], v[88:91]
	v_mfma_f32_16x16x32_bf16 v[80:83], v[212:215], v[204:207], v[80:83]
	v_mfma_f32_16x16x32_bf16 v[72:75], v[220:223], v[204:207], v[72:75]
	s_barrier
	s_mov_b32 m0, s26
	v_lshl_add_u64 v[224:225], s[4:5], 0, v[136:137]
	ds_read_b128 v[160:163], v150 offset:16384
	ds_read_b128 v[164:167], v150 offset:17408
	ds_read_b128 v[172:175], v150 offset:18432
	ds_read_b128 v[176:179], v150 offset:19456
	ds_read_b128 v[180:183], v150 offset:20480
	ds_read_b128 v[196:199], v150 offset:21504
	ds_read_b128 v[200:203], v150 offset:22528
	ds_read_b128 v[204:207], v150 offset:23552
	global_load_lds_dwordx4 v[224:225], off
	v_lshl_add_u64 v[226:227], v[224:225], 0, s[0:1]
	s_mov_b32 m0, s27
	s_nop 0
	global_load_lds_dwordx4 v[226:227], off
	s_barrier
	s_waitcnt lgkmcnt(0)
	v_mfma_f32_16x16x32_bf16 v[68:71], v[140:143], v[160:163], v[68:71]
	v_mfma_f32_16x16x32_bf16 v[60:63], v[152:155], v[160:163], v[60:63]
	v_mfma_f32_16x16x32_bf16 v[52:55], v[140:143], v[172:175], v[52:55]
	v_mfma_f32_16x16x32_bf16 v[44:47], v[152:155], v[172:175], v[44:47]
	v_mfma_f32_16x16x32_bf16 v[36:39], v[140:143], v[180:183], v[36:39]
	v_mfma_f32_16x16x32_bf16 v[28:31], v[152:155], v[180:183], v[28:31]
	v_mfma_f32_16x16x32_bf16 v[20:23], v[140:143], v[200:203], v[20:23]
	v_mfma_f32_16x16x32_bf16 v[12:15], v[152:155], v[200:203], v[12:15]
	v_mfma_f32_16x16x32_bf16 v[68:71], v[144:147], v[164:167], v[68:71]
	v_mfma_f32_16x16x32_bf16 v[60:63], v[156:159], v[164:167], v[60:63]
	v_mfma_f32_16x16x32_bf16 v[52:55], v[144:147], v[176:179], v[52:55]
	v_mfma_f32_16x16x32_bf16 v[44:47], v[156:159], v[176:179], v[44:47]
	v_mfma_f32_16x16x32_bf16 v[36:39], v[144:147], v[196:199], v[36:39]
	v_mfma_f32_16x16x32_bf16 v[28:31], v[156:159], v[196:199], v[28:31]
	v_mfma_f32_16x16x32_bf16 v[20:23], v[144:147], v[204:207], v[20:23]
	v_mfma_f32_16x16x32_bf16 v[12:15], v[156:159], v[204:207], v[12:15]
	s_barrier
; #define G_STAGE(bufoff, gbase, o0, h64) do { \
;         __builtin_amdgcn_global_load_lds((const unsigned*)((const char*)(gbase) + (o0)), (LAS unsigned*)(lds + (bufoff) + ldsw), 16, 0, 0); \
;         __builtin_amdgcn_global_load_lds((const unsigned*)((const char*)(gbase) + (h64) + (o0)), (LAS unsigned*)(lds + (bufoff) + ldsw + 8192), 16, 0, 0); } while (0)
; #define G_LDA(dst, b, h) do { _Pragma("unroll") for (int m = 0; m < 4; ++m) _Pragma("unroll") for (int k = 0; k < 2; ++k) dst[m][k] = *(const LAS bf16x8*)(lds + G_SA(b, h) + aoff + m * 2048 + k * 1024); } while (0)
; #define G_LDB(dst, b, h) do { _Pragma("unroll") for (int n = 0; n < 2; ++n) _Pragma("unroll") for (int k = 0; k < 2; ++k) dst[n][k] = *(const LAS bf16x8*)(lds + G_SB(b, h) + boff + n * 2048 + k * 1024); } while (0)
; #define G_WAIT_V(n) asm volatile("s_waitcnt vmcnt(" #n ")" ::: "memory")
; #define G_WAIT_L(n) asm volatile("s_waitcnt lgkmcnt(" #n ")" ::: "memory")
; #define G_BAR __builtin_amdgcn_s_barrier()
; #define G_SCHED __builtin_amdgcn_sched_barrier(0)
;     ...
;             G_STAGE(G_SB(0, 1), b2 + chB, cB0, qB);
;             G_WAIT_V(6); G_BAR; G_MMA(1, 1, At, B1); G_BAR;
;             G_LDB(B0, 1, 0); G_SCHED; G_LDA(At, 1, 0); G_STAGE(G_SA(0, 1), a2 + chA, cA0, qA);
;             G_WAIT_L(8); G_BAR; G_WAIT_L(0); G_MMA(0, 0, At, B0); G_BAR; G_SCHED;
;             G_LDB(B1, 1, 1); G_STAGE(G_SB(1, 0), b3, cB0, qB);
	s_add_i32 s4, s39, s21
	v_lshl_add_u64 v[140:141], v[184:185], 0, s[42:43]
	s_mov_b32 m0, s4
	s_nop 0
	global_load_lds_dwordx4 v[140:141], off
	v_lshl_add_u64 v[140:141], v[184:185], 0, s[50:51]
	s_add_i32 m0, s4, 0x2000
	s_nop 0
	global_load_lds_dwordx4 v[140:141], off
	s_waitcnt vmcnt(6)
	s_barrier
	v_mfma_f32_16x16x32_bf16 v[64:67], v[208:211], v[160:163], v[64:67]
	v_mfma_f32_16x16x32_bf16 v[56:59], v[216:219], v[160:163], v[56:59]
	v_mfma_f32_16x16x32_bf16 v[48:51], v[208:211], v[172:175], v[48:51]
	v_mfma_f32_16x16x32_bf16 v[40:43], v[216:219], v[172:175], v[40:43]
	v_mfma_f32_16x16x32_bf16 v[32:35], v[208:211], v[180:183], v[32:35]
	v_mfma_f32_16x16x32_bf16 v[24:27], v[216:219], v[180:183], v[24:27]
	v_mfma_f32_16x16x32_bf16 v[16:19], v[208:211], v[200:203], v[16:19]
	v_mfma_f32_16x16x32_bf16 v[8:11], v[216:219], v[200:203], v[8:11]
	v_mfma_f32_16x16x32_bf16 v[64:67], v[212:215], v[164:167], v[64:67]
	v_mfma_f32_16x16x32_bf16 v[56:59], v[220:223], v[164:167], v[56:59]
	v_mfma_f32_16x16x32_bf16 v[48:51], v[212:215], v[176:179], v[48:51]
	v_mfma_f32_16x16x32_bf16 v[40:43], v[220:223], v[176:179], v[40:43]
	v_mfma_f32_16x16x32_bf16 v[32:35], v[212:215], v[196:199], v[32:35]
	v_mfma_f32_16x16x32_bf16 v[24:27], v[220:223], v[196:199], v[24:27]
	v_mfma_f32_16x16x32_bf16 v[16:19], v[212:215], v[204:207], v[16:19]
	v_mfma_f32_16x16x32_bf16 v[8:11], v[220:223], v[204:207], v[8:11]
	s_barrier
	s_add_i32 s4, 0, 0x18000
	v_add_u32_e32 v0, s4, v149
	ds_read_b128 v[140:143], v0
	ds_read_b128 v[144:147], v0 offset:1024
	ds_read_b128 v[152:155], v0 offset:2048
	ds_read_b128 v[156:159], v0 offset:3072
	s_mov_b32 m0, s29
	v_lshl_add_u64 v[208:209], v[224:225], 0, s[42:43]
	ds_read_b128 v[160:163], v150 offset:32768
	ds_read_b128 v[164:167], v150 offset:33792
	ds_read_b128 v[172:175], v150 offset:34816
	ds_read_b128 v[176:179], v150 offset:35840
	ds_read_b128 v[180:183], v150 offset:36864
	ds_read_b128 v[196:199], v150 offset:37888
	ds_read_b128 v[200:203], v150 offset:38912
	ds_read_b128 v[204:207], v150 offset:39936
	global_load_lds_dwordx4 v[208:209], off
	v_lshl_add_u64 v[208:209], v[224:225], 0, s[50:51]
	s_mov_b32 m0, s30
	s_nop 0
	global_load_lds_dwordx4 v[208:209], off
	s_waitcnt lgkmcnt(8)
	s_barrier
	s_waitcnt lgkmcnt(0)
	v_mfma_f32_16x16x32_bf16 v[132:135], v[140:143], v[160:163], v[132:135]
	v_mfma_f32_16x16x32_bf16 v[124:127], v[152:155], v[160:163], v[124:127]
	v_mfma_f32_16x16x32_bf16 v[116:119], v[140:143], v[172:175], v[116:119]
	v_mfma_f32_16x16x32_bf16 v[108:111], v[152:155], v[172:175], v[108:111]
	v_mfma_f32_16x16x32_bf16 v[100:103], v[140:143], v[180:183], v[100:103]
	v_mfma_f32_16x16x32_bf16 v[92:95], v[152:155], v[180:183], v[92:95]
	v_mfma_f32_16x16x32_bf16 v[84:87], v[140:143], v[200:203], v[84:87]
	v_mfma_f32_16x16x32_bf16 v[76:79], v[152:155], v[200:203], v[76:79]
	v_mfma_f32_16x16x32_bf16 v[132:135], v[144:147], v[164:167], v[132:135]
	v_mfma_f32_16x16x32_bf16 v[124:127], v[156:159], v[164:167], v[124:127]
	v_mfma_f32_16x16x32_bf16 v[116:119], v[144:147], v[176:179], v[116:119]
	v_mfma_f32_16x16x32_bf16 v[108:111], v[156:159], v[176:179], v[108:111]
	v_mfma_f32_16x16x32_bf16 v[100:103], v[144:147], v[196:199], v[100:103]
	v_mfma_f32_16x16x32_bf16 v[92:95], v[156:159], v[196:199], v[92:95]
	v_mfma_f32_16x16x32_bf16 v[84:87], v[144:147], v[204:207], v[84:87]
	v_mfma_f32_16x16x32_bf16 v[76:79], v[156:159], v[204:207], v[76:79]
	s_barrier
	s_add_i32 s5, 0, 0x1c000
	s_add_i32 s4, s4, s21
	v_add_u32_e32 v0, s5, v149
	v_lshl_add_u64 v[226:227], v[184:185], 0, s[46:47]
	s_mov_b32 m0, s4
	ds_read_b128 v[208:211], v0
	ds_read_b128 v[212:215], v0 offset:1024
	ds_read_b128 v[216:219], v0 offset:2048
	ds_read_b128 v[220:223], v0 offset:3072
	global_load_lds_dwordx4 v[226:227], off
	v_lshl_add_u64 v[226:227], v[184:185], 0, s[52:53]
	s_add_i32 m0, s4, 0x2000
	s_nop 0
	global_load_lds_dwordx4 v[226:227], off
	s_barrier
; #define G_STAGE(bufoff, gbase, o0, h64) do { \
;         __builtin_amdgcn_global_load_lds((const unsigned*)((const char*)(gbase) + (o0)), (LAS unsigned*)(lds + (bufoff) + ldsw), 16, 0, 0); \
;         __builtin_amdgcn_global_load_lds((const unsigned*)((const char*)(gbase) + (h64) + (o0)), (LAS unsigned*)(lds + (bufoff) + ldsw + 8192), 16, 0, 0); } while (0)
; #define G_LDA(dst, b, h) do { _Pragma("unroll") for (int m = 0; m < 4; ++m) _Pragma("unroll") for (int k = 0; k < 2; ++k) dst[m][k] = *(const LAS bf16x8*)(lds + G_SA(b, h) + aoff + m * 2048 + k * 1024); } while (0)
; #define G_LDB(dst, b, h) do { _Pragma("unroll") for (int n = 0; n < 2; ++n) _Pragma("unroll") for (int k = 0; k < 2; ++k) dst[n][k] = *(const LAS bf16x8*)(lds + G_SB(b, h) + boff + n * 2048 + k * 1024); } while (0)
; #define G_WAIT_V(n) asm volatile("s_waitcnt vmcnt(" #n ")" ::: "memory")
; #define G_WAIT_L(n) asm volatile("s_waitcnt lgkmcnt(" #n ")" ::: "memory")
; #define G_BAR __builtin_amdgcn_s_barrier()
; #define G_SCHED __builtin_amdgcn_sched_barrier(0)
;     ...
;             G_WAIT_L(8); G_BAR; G_WAIT_L(0); G_MMA(0, 0, At, B0); G_BAR; G_SCHED;
;             G_LDB(B1, 1, 1); G_STAGE(G_SB(1, 0), b3, cB0, qB);
;             G_BAR; G_WAIT_L(0); G_MMA(0, 1, At, B1); G_BAR;
;             G_LDA(At, 1, 1); G_STAGE(G_SA(1, 0), a3, cA0, qA);
;             G_BAR; G_WAIT_L(0); G_MMA(1, 0, At, B0); G_BAR; G_SCHED;
;             G_STAGE(G_SB(1, 1), b3 + chB, cB0, qB);
;             G_WAIT_V(6); G_BAR; G_MMA(1, 1, At, B1); G_BAR;
;         }
	s_waitcnt lgkmcnt(0)
	v_mfma_f32_16x16x32_bf16 v[128:131], v[208:211], v[160:163], v[128:131]
	v_mfma_f32_16x16x32_bf16 v[120:123], v[216:219], v[160:163], v[120:123]
	v_mfma_f32_16x16x32_bf16 v[112:115], v[208:211], v[172:175], v[112:115]
	v_mfma_f32_16x16x32_bf16 v[104:107], v[216:219], v[172:175], v[104:107]
	v_mfma_f32_16x16x32_bf16 v[96:99], v[208:211], v[180:183], v[96:99]
	v_mfma_f32_16x16x32_bf16 v[88:91], v[216:219], v[180:183], v[88:91]
	v_mfma_f32_16x16x32_bf16 v[80:83], v[208:211], v[200:203], v[80:83]
	v_mfma_f32_16x16x32_bf16 v[72:75], v[216:219], v[200:203], v[72:75]
	v_mfma_f32_16x16x32_bf16 v[128:131], v[212:215], v[164:167], v[128:131]
	v_mfma_f32_16x16x32_bf16 v[120:123], v[220:223], v[164:167], v[120:123]
	v_mfma_f32_16x16x32_bf16 v[112:115], v[212:215], v[176:179], v[112:115]
	v_mfma_f32_16x16x32_bf16 v[104:107], v[220:223], v[176:179], v[104:107]
	v_mfma_f32_16x16x32_bf16 v[96:99], v[212:215], v[196:199], v[96:99]
	v_mfma_f32_16x16x32_bf16 v[88:91], v[220:223], v[196:199], v[88:91]
	v_mfma_f32_16x16x32_bf16 v[80:83], v[212:215], v[204:207], v[80:83]
	v_mfma_f32_16x16x32_bf16 v[72:75], v[220:223], v[204:207], v[72:75]
	s_barrier
	s_mov_b32 m0, s31
	v_lshl_add_u64 v[226:227], v[224:225], 0, s[46:47]
	ds_read_b128 v[160:163], v150 offset:49152
	ds_read_b128 v[164:167], v150 offset:50176
	ds_read_b128 v[172:175], v150 offset:51200
	ds_read_b128 v[176:179], v150 offset:52224
	ds_read_b128 v[180:183], v150 offset:53248
	ds_read_b128 v[196:199], v150 offset:54272
	ds_read_b128 v[200:203], v150 offset:55296
	ds_read_b128 v[204:207], v150 offset:56320
	global_load_lds_dwordx4 v[226:227], off
	v_lshl_add_u64 v[224:225], v[224:225], 0, s[52:53]
	s_mov_b32 m0, s34
	s_nop 0
	global_load_lds_dwordx4 v[224:225], off
	s_barrier
	s_waitcnt lgkmcnt(0)
	v_mfma_f32_16x16x32_bf16 v[68:71], v[140:143], v[160:163], v[68:71]
	v_mfma_f32_16x16x32_bf16 v[60:63], v[152:155], v[160:163], v[60:63]
	v_mfma_f32_16x16x32_bf16 v[52:55], v[140:143], v[172:175], v[52:55]
	v_mfma_f32_16x16x32_bf16 v[44:47], v[152:155], v[172:175], v[44:47]
	v_mfma_f32_16x16x32_bf16 v[36:39], v[140:143], v[180:183], v[36:39]
	v_mfma_f32_16x16x32_bf16 v[28:31], v[152:155], v[180:183], v[28:31]
	v_mfma_f32_16x16x32_bf16 v[20:23], v[140:143], v[200:203], v[20:23]
	v_mfma_f32_16x16x32_bf16 v[12:15], v[152:155], v[200:203], v[12:15]
	v_mfma_f32_16x16x32_bf16 v[68:71], v[144:147], v[164:167], v[68:71]
	v_mfma_f32_16x16x32_bf16 v[60:63], v[156:159], v[164:167], v[60:63]
	v_mfma_f32_16x16x32_bf16 v[52:55], v[144:147], v[176:179], v[52:55]
	v_mfma_f32_16x16x32_bf16 v[44:47], v[156:159], v[176:179], v[44:47]
	v_mfma_f32_16x16x32_bf16 v[36:39], v[144:147], v[196:199], v[36:39]
	v_mfma_f32_16x16x32_bf16 v[28:31], v[156:159], v[196:199], v[28:31]
	v_mfma_f32_16x16x32_bf16 v[20:23], v[144:147], v[204:207], v[20:23]
	v_mfma_f32_16x16x32_bf16 v[12:15], v[156:159], v[204:207], v[12:15]
	s_barrier
	s_add_i32 s4, s5, s21
	v_lshl_add_u64 v[140:141], v[184:185], 0, s[54:55]
	s_mov_b32 m0, s4
	s_nop 0
	global_load_lds_dwordx4 v[140:141], off
	v_lshl_add_u64 v[140:141], v[184:185], 0, s[58:59]
	s_add_i32 m0, s4, 0x2000
	s_nop 0
	global_load_lds_dwordx4 v[140:141], off
	s_add_i32 s18, s18, 2
	s_add_u32 s2, s2, 0x100
	s_addc_u32 s3, s3, 0
	s_add_u32 s16, s16, 0x100
	s_addc_u32 s17, s17, 0
	s_cmp_gt_u32 s18, 13
	s_waitcnt vmcnt(6)
	s_barrier
	v_mfma_f32_16x16x32_bf16 v[64:67], v[208:211], v[160:163], v[64:67]
	v_mfma_f32_16x16x32_bf16 v[56:59], v[216:219], v[160:163], v[56:59]
	v_mfma_f32_16x16x32_bf16 v[48:51], v[208:211], v[172:175], v[48:51]
	v_mfma_f32_16x16x32_bf16 v[40:43], v[216:219], v[172:175], v[40:43]
	v_mfma_f32_16x16x32_bf16 v[32:35], v[208:211], v[180:183], v[32:35]
	v_mfma_f32_16x16x32_bf16 v[24:27], v[216:219], v[180:183], v[24:27]
	v_mfma_f32_16x16x32_bf16 v[16:19], v[208:211], v[200:203], v[16:19]
	v_mfma_f32_16x16x32_bf16 v[8:11], v[216:219], v[200:203], v[8:11]
	v_mfma_f32_16x16x32_bf16 v[64:67], v[212:215], v[164:167], v[64:67]
	v_mfma_f32_16x16x32_bf16 v[56:59], v[220:223], v[164:167], v[56:59]
	v_mfma_f32_16x16x32_bf16 v[48:51], v[212:215], v[176:179], v[48:51]
	v_mfma_f32_16x16x32_bf16 v[40:43], v[220:223], v[176:179], v[40:43]
	v_mfma_f32_16x16x32_bf16 v[32:35], v[212:215], v[196:199], v[32:35]
	v_mfma_f32_16x16x32_bf16 v[24:27], v[220:223], v[196:199], v[24:27]
	v_mfma_f32_16x16x32_bf16 v[16:19], v[212:215], v[204:207], v[16:19]
	v_mfma_f32_16x16x32_bf16 v[8:11], v[220:223], v[204:207], v[8:11]
	s_cbranch_scc0 .Ldb_FFI_cont
	v_readfirstlane_b32 s101, v186
	s_cmpk_gt_u32 s101, 0xff
	s_cbranch_scc1 .Ldb_FFI_exit
	s_barrier
	s_branch .Ldb_FFI_exit

; #define G_STAGE(bufoff, gbase, o0, h64) do { \
;         __builtin_amdgcn_global_load_lds((const unsigned*)((const char*)(gbase) + (o0)), (LAS unsigned*)(lds + (bufoff) + ldsw), 16, 0, 0); \
;         __builtin_amdgcn_global_load_lds((const unsigned*)((const char*)(gbase) + (h64) + (o0)), (LAS unsigned*)(lds + (bufoff) + ldsw + 8192), 16, 0, 0); } while (0)
; #define G_LDA(dst, b, h) do { _Pragma("unroll") for (int m = 0; m < 4; ++m) _Pragma("unroll") for (int k = 0; k < 2; ++k) dst[m][k] = *(const LAS bf16x8*)(lds + G_SA(b, h) + aoff + m * 2048 + k * 1024); } while (0)
; #define G_LDB(dst, b, h) do { _Pragma("unroll") for (int n = 0; n < 2; ++n) _Pragma("unroll") for (int k = 0; k < 2; ++k) dst[n][k] = *(const LAS bf16x8*)(lds + G_SB(b, h) + boff + n * 2048 + k * 1024); } while (0)
; #define G_WAIT_L(n) asm volatile("s_waitcnt lgkmcnt(" #n ")" ::: "memory")
; #define G_BAR __builtin_amdgcn_s_barrier()
; #define G_SCHED __builtin_amdgcn_sched_barrier(0)
;     ...
;         for (int t = 0; t < nt; t += 2) {
;             const bool last = (t == nt - 2);
;             const char* a1 = cA + (size_t)(t + 1) * ckA;
;             const char* a2 = last ? nA : cA + (size_t)(t + 2) * ckA; const char* b2 = last ? nB : cB + (size_t)(t + 2) * kB;
;             const char* a3 = a2 + ckA; const char* b3 = b2 + kB;
;             G_LDB(B0, 0, 0); G_SCHED; G_LDA(At, 0, 0); G_STAGE(G_SA(1, 1), a1 + chA, cA0, qA);
;             G_WAIT_L(8); G_BAR; G_WAIT_L(0); G_MMA(0, 0, At, B0); G_BAR; G_SCHED;
;             G_LDB(B1, 0, 1); G_STAGE(G_SB(0, 0), b2, cB0, qB);
;             G_BAR; G_WAIT_L(0); G_MMA(0, 1, At, B1); G_BAR;
;             G_LDA(At, 0, 1); G_STAGE(G_SA(0, 0), a2, cA0, qA);
;             G_BAR; G_WAIT_L(0); G_MMA(1, 0, At, B0); G_BAR; G_SCHED;
.Ldbj_FFO_in:
.LBB0_1185:
	s_add_u32 s4, s2, 0xfff50080
	s_addc_u32 s5, s3, -1
	s_add_i32 s33, 0, 0x10000
	v_add_u32_e32 v0, s33, v185
	ds_read_b128 v[136:139], v0
	ds_read_b128 v[140:143], v0 offset:1024
	ds_read_b128 v[144:147], v0 offset:2048
	ds_read_b128 v[148:151], v0 offset:3072
	s_cmp_eq_u32 s21, 40
	s_cselect_b32 s5, s17, s5
	s_cselect_b32 s4, s16, s4
	s_cselect_b32 s23, s19, s7
	s_cselect_b32 s22, s18, s6
	v_lshl_add_u64 v[204:205], s[2:3], 0, v[174:175]
	s_add_i32 m0, s26, 0xc000
	ds_read_b128 v[152:155], v195
	ds_read_b128 v[156:159], v195 offset:1024
	ds_read_b128 v[160:163], v195 offset:2048
	ds_read_b128 v[164:167], v195 offset:3072
	ds_read_b128 v[176:179], v195 offset:4096
	ds_read_b128 v[180:183], v195 offset:5120
	ds_read_b128 v[196:199], v195 offset:6144
	ds_read_b128 v[200:203], v195 offset:7168
	global_load_lds_dwordx4 v[204:205], off
	v_lshl_add_u64 v[204:205], v[204:205], 0, s[86:87]
	s_add_i32 m0, s26, 0xe000
	s_nop 0
	global_load_lds_dwordx4 v[204:205], off
	s_waitcnt lgkmcnt(8)
	s_barrier
	s_waitcnt lgkmcnt(0)
	v_mfma_f32_16x16x32_bf16 v[132:135], v[136:139], v[152:155], v[132:135]
	v_mfma_f32_16x16x32_bf16 v[128:131], v[144:147], v[152:155], v[128:131]
	v_mfma_f32_16x16x32_bf16 v[116:119], v[136:139], v[160:163], v[116:119]
	v_mfma_f32_16x16x32_bf16 v[112:115], v[144:147], v[160:163], v[112:115]
	v_mfma_f32_16x16x32_bf16 v[100:103], v[136:139], v[176:179], v[100:103]
	v_mfma_f32_16x16x32_bf16 v[96:99], v[144:147], v[176:179], v[96:99]
	v_mfma_f32_16x16x32_bf16 v[84:87], v[136:139], v[196:199], v[84:87]
	v_mfma_f32_16x16x32_bf16 v[80:83], v[144:147], v[196:199], v[80:83]
	v_mfma_f32_16x16x32_bf16 v[132:135], v[140:143], v[156:159], v[132:135]
	v_mfma_f32_16x16x32_bf16 v[128:131], v[148:151], v[156:159], v[128:131]
	v_mfma_f32_16x16x32_bf16 v[116:119], v[140:143], v[164:167], v[116:119]
	v_mfma_f32_16x16x32_bf16 v[112:115], v[148:151], v[164:167], v[112:115]
	v_mfma_f32_16x16x32_bf16 v[100:103], v[140:143], v[180:183], v[100:103]
	v_mfma_f32_16x16x32_bf16 v[96:99], v[148:151], v[180:183], v[96:99]
	v_mfma_f32_16x16x32_bf16 v[84:87], v[140:143], v[200:203], v[84:87]
	v_mfma_f32_16x16x32_bf16 v[80:83], v[148:151], v[200:203], v[80:83]
	s_barrier
	s_add_i32 s44, 0, 0x14000
	v_lshl_add_u64 v[220:221], s[22:23], 0, v[172:173]
	s_add_i32 s22, s33, s25
	v_add_u32_e32 v0, s44, v185
	s_mov_b32 m0, s22
	ds_read_b128 v[204:207], v0
	ds_read_b128 v[208:211], v0 offset:1024
	ds_read_b128 v[212:215], v0 offset:2048
	ds_read_b128 v[216:219], v0 offset:3072
	global_load_lds_dwordx4 v[220:221], off
	v_lshl_add_u64 v[222:223], v[220:221], 0, s[86:87]
	s_add_i32 m0, s22, 0x2000
	s_nop 0
	global_load_lds_dwordx4 v[222:223], off
	s_barrier
	s_waitcnt lgkmcnt(0)
	v_mfma_f32_16x16x32_bf16 v[124:127], v[204:207], v[152:155], v[124:127]
	v_mfma_f32_16x16x32_bf16 v[120:123], v[212:215], v[152:155], v[120:123]
	v_mfma_f32_16x16x32_bf16 v[108:111], v[204:207], v[160:163], v[108:111]
	v_mfma_f32_16x16x32_bf16 v[104:107], v[212:215], v[160:163], v[104:107]
	v_mfma_f32_16x16x32_bf16 v[92:95], v[204:207], v[176:179], v[92:95]
	v_mfma_f32_16x16x32_bf16 v[88:91], v[212:215], v[176:179], v[88:91]
	v_mfma_f32_16x16x32_bf16 v[76:79], v[204:207], v[196:199], v[76:79]
	v_mfma_f32_16x16x32_bf16 v[72:75], v[212:215], v[196:199], v[72:75]
	v_mfma_f32_16x16x32_bf16 v[124:127], v[208:211], v[156:159], v[124:127]
	v_mfma_f32_16x16x32_bf16 v[120:123], v[216:219], v[156:159], v[120:123]
	v_mfma_f32_16x16x32_bf16 v[108:111], v[208:211], v[164:167], v[108:111]
	v_mfma_f32_16x16x32_bf16 v[104:107], v[216:219], v[164:167], v[104:107]
	v_mfma_f32_16x16x32_bf16 v[92:95], v[208:211], v[180:183], v[92:95]
	v_mfma_f32_16x16x32_bf16 v[88:91], v[216:219], v[180:183], v[88:91]
	v_mfma_f32_16x16x32_bf16 v[76:79], v[208:211], v[200:203], v[76:79]
	v_mfma_f32_16x16x32_bf16 v[72:75], v[216:219], v[200:203], v[72:75]
	s_barrier
	s_mov_b32 m0, s26
	v_lshl_add_u64 v[222:223], s[4:5], 0, v[2:3]
	ds_read_b128 v[152:155], v195 offset:16384
	ds_read_b128 v[156:159], v195 offset:17408
	ds_read_b128 v[160:163], v195 offset:18432
	ds_read_b128 v[164:167], v195 offset:19456
	ds_read_b128 v[176:179], v195 offset:20480
	ds_read_b128 v[180:183], v195 offset:21504
	ds_read_b128 v[196:199], v195 offset:22528
	ds_read_b128 v[200:203], v195 offset:23552
	global_load_lds_dwordx4 v[222:223], off
	v_lshl_add_u64 v[224:225], v[222:223], 0, s[86:87]
	s_mov_b32 m0, s27
	s_nop 0
	global_load_lds_dwordx4 v[224:225], off
	s_barrier
	s_waitcnt lgkmcnt(0)
	v_mfma_f32_16x16x32_bf16 v[68:71], v[136:139], v[152:155], v[68:71]
	v_mfma_f32_16x16x32_bf16 v[64:67], v[144:147], v[152:155], v[64:67]
	v_mfma_f32_16x16x32_bf16 v[52:55], v[136:139], v[160:163], v[52:55]
	v_mfma_f32_16x16x32_bf16 v[48:51], v[144:147], v[160:163], v[48:51]
	v_mfma_f32_16x16x32_bf16 v[36:39], v[136:139], v[176:179], v[36:39]
	v_mfma_f32_16x16x32_bf16 v[32:35], v[144:147], v[176:179], v[32:35]
	v_mfma_f32_16x16x32_bf16 v[20:23], v[136:139], v[196:199], v[20:23]
	v_mfma_f32_16x16x32_bf16 v[16:19], v[144:147], v[196:199], v[16:19]
	v_mfma_f32_16x16x32_bf16 v[68:71], v[140:143], v[156:159], v[68:71]
	v_mfma_f32_16x16x32_bf16 v[64:67], v[148:151], v[156:159], v[64:67]
	v_mfma_f32_16x16x32_bf16 v[52:55], v[140:143], v[164:167], v[52:55]
	v_mfma_f32_16x16x32_bf16 v[48:51], v[148:151], v[164:167], v[48:51]
	v_mfma_f32_16x16x32_bf16 v[36:39], v[140:143], v[180:183], v[36:39]
	v_mfma_f32_16x16x32_bf16 v[32:35], v[148:151], v[180:183], v[32:35]
	v_mfma_f32_16x16x32_bf16 v[20:23], v[140:143], v[200:203], v[20:23]
	v_mfma_f32_16x16x32_bf16 v[16:19], v[148:151], v[200:203], v[16:19]
	s_barrier
; #define G_STAGE(bufoff, gbase, o0, h64) do { \
;         __builtin_amdgcn_global_load_lds((const unsigned*)((const char*)(gbase) + (o0)), (LAS unsigned*)(lds + (bufoff) + ldsw), 16, 0, 0); \
;         __builtin_amdgcn_global_load_lds((const unsigned*)((const char*)(gbase) + (h64) + (o0)), (LAS unsigned*)(lds + (bufoff) + ldsw + 8192), 16, 0, 0); } while (0)
; #define G_LDA(dst, b, h) do { _Pragma("unroll") for (int m = 0; m < 4; ++m) _Pragma("unroll") for (int k = 0; k < 2; ++k) dst[m][k] = *(const LAS bf16x8*)(lds + G_SA(b, h) + aoff + m * 2048 + k * 1024); } while (0)
; #define G_LDB(dst, b, h) do { _Pragma("unroll") for (int n = 0; n < 2; ++n) _Pragma("unroll") for (int k = 0; k < 2; ++k) dst[n][k] = *(const LAS bf16x8*)(lds + G_SB(b, h) + boff + n * 2048 + k * 1024); } while (0)
; #define G_WAIT_V(n) asm volatile("s_waitcnt vmcnt(" #n ")" ::: "memory")
; #define G_WAIT_L(n) asm volatile("s_waitcnt lgkmcnt(" #n ")" ::: "memory")
; #define G_BAR __builtin_amdgcn_s_barrier()
; #define G_SCHED __builtin_amdgcn_sched_barrier(0)
;     ...
;             G_STAGE(G_SB(0, 1), b2 + chB, cB0, qB);
;             G_WAIT_V(6); G_BAR; G_MMA(1, 1, At, B1); G_BAR;
;             G_LDB(B0, 1, 0); G_SCHED; G_LDA(At, 1, 0); G_STAGE(G_SA(0, 1), a2 + chA, cA0, qA);
;             G_WAIT_L(8); G_BAR; G_WAIT_L(0); G_MMA(0, 0, At, B0); G_BAR; G_SCHED;
;             G_LDB(B1, 1, 1); G_STAGE(G_SB(1, 0), b3, cB0, qB);
	s_add_i32 s4, s44, s25
	v_lshl_add_u64 v[136:137], v[220:221], 0, s[88:89]
	s_mov_b32 m0, s4
	s_nop 0
	global_load_lds_dwordx4 v[136:137], off
	v_lshl_add_u64 v[136:137], v[220:221], 0, s[64:65]
	s_add_i32 m0, s4, 0x2000
	s_nop 0
	global_load_lds_dwordx4 v[136:137], off
	s_waitcnt vmcnt(6)
	s_barrier
	v_mfma_f32_16x16x32_bf16 v[60:63], v[204:207], v[152:155], v[60:63]
	v_mfma_f32_16x16x32_bf16 v[56:59], v[212:215], v[152:155], v[56:59]
	v_mfma_f32_16x16x32_bf16 v[44:47], v[204:207], v[160:163], v[44:47]
	v_mfma_f32_16x16x32_bf16 v[40:43], v[212:215], v[160:163], v[40:43]
	v_mfma_f32_16x16x32_bf16 v[28:31], v[204:207], v[176:179], v[28:31]
	v_mfma_f32_16x16x32_bf16 v[24:27], v[212:215], v[176:179], v[24:27]
	v_mfma_f32_16x16x32_bf16 v[12:15], v[204:207], v[196:199], v[12:15]
	v_mfma_f32_16x16x32_bf16 v[8:11], v[212:215], v[196:199], v[8:11]
	v_mfma_f32_16x16x32_bf16 v[60:63], v[208:211], v[156:159], v[60:63]
	v_mfma_f32_16x16x32_bf16 v[56:59], v[216:219], v[156:159], v[56:59]
	v_mfma_f32_16x16x32_bf16 v[44:47], v[208:211], v[164:167], v[44:47]
	v_mfma_f32_16x16x32_bf16 v[40:43], v[216:219], v[164:167], v[40:43]
	v_mfma_f32_16x16x32_bf16 v[28:31], v[208:211], v[180:183], v[28:31]
	v_mfma_f32_16x16x32_bf16 v[24:27], v[216:219], v[180:183], v[24:27]
	v_mfma_f32_16x16x32_bf16 v[12:15], v[208:211], v[200:203], v[12:15]
	v_mfma_f32_16x16x32_bf16 v[8:11], v[216:219], v[200:203], v[8:11]
	s_barrier
	s_add_i32 s4, 0, 0x18000
	v_add_u32_e32 v0, s4, v185
	ds_read_b128 v[136:139], v0
	ds_read_b128 v[140:143], v0 offset:1024
	ds_read_b128 v[144:147], v0 offset:2048
	ds_read_b128 v[148:151], v0 offset:3072
	s_mov_b32 m0, s29
	v_lshl_add_u64 v[204:205], v[222:223], 0, s[88:89]
	ds_read_b128 v[152:155], v195 offset:32768
	ds_read_b128 v[156:159], v195 offset:33792
	ds_read_b128 v[160:163], v195 offset:34816
	ds_read_b128 v[164:167], v195 offset:35840
	ds_read_b128 v[176:179], v195 offset:36864
	ds_read_b128 v[180:183], v195 offset:37888
	ds_read_b128 v[196:199], v195 offset:38912
	ds_read_b128 v[200:203], v195 offset:39936
	global_load_lds_dwordx4 v[204:205], off
	v_lshl_add_u64 v[204:205], v[222:223], 0, s[64:65]
	s_mov_b32 m0, s30
	s_nop 0
	global_load_lds_dwordx4 v[204:205], off
	s_waitcnt lgkmcnt(8)
	s_barrier
	s_waitcnt lgkmcnt(0)
	v_mfma_f32_16x16x32_bf16 v[132:135], v[136:139], v[152:155], v[132:135]
	v_mfma_f32_16x16x32_bf16 v[128:131], v[144:147], v[152:155], v[128:131]
	v_mfma_f32_16x16x32_bf16 v[116:119], v[136:139], v[160:163], v[116:119]
	v_mfma_f32_16x16x32_bf16 v[112:115], v[144:147], v[160:163], v[112:115]
	v_mfma_f32_16x16x32_bf16 v[100:103], v[136:139], v[176:179], v[100:103]
	v_mfma_f32_16x16x32_bf16 v[96:99], v[144:147], v[176:179], v[96:99]
	v_mfma_f32_16x16x32_bf16 v[84:87], v[136:139], v[196:199], v[84:87]
	v_mfma_f32_16x16x32_bf16 v[80:83], v[144:147], v[196:199], v[80:83]
	v_mfma_f32_16x16x32_bf16 v[132:135], v[140:143], v[156:159], v[132:135]
	v_mfma_f32_16x16x32_bf16 v[128:131], v[148:151], v[156:159], v[128:131]
	v_mfma_f32_16x16x32_bf16 v[116:119], v[140:143], v[164:167], v[116:119]
	v_mfma_f32_16x16x32_bf16 v[112:115], v[148:151], v[164:167], v[112:115]
	v_mfma_f32_16x16x32_bf16 v[100:103], v[140:143], v[180:183], v[100:103]
	v_mfma_f32_16x16x32_bf16 v[96:99], v[148:151], v[180:183], v[96:99]
	v_mfma_f32_16x16x32_bf16 v[84:87], v[140:143], v[200:203], v[84:87]
	v_mfma_f32_16x16x32_bf16 v[80:83], v[148:151], v[200:203], v[80:83]
	s_barrier
	s_add_i32 s5, 0, 0x1c000
	s_add_i32 s4, s4, s25
	v_add_u32_e32 v0, s5, v185
	v_lshl_add_u64 v[224:225], v[220:221], 0, s[46:47]
	s_mov_b32 m0, s4
	ds_read_b128 v[204:207], v0
	ds_read_b128 v[208:211], v0 offset:1024
	ds_read_b128 v[212:215], v0 offset:2048
	ds_read_b128 v[216:219], v0 offset:3072
	global_load_lds_dwordx4 v[224:225], off
	v_lshl_add_u64 v[224:225], v[220:221], 0, s[66:67]
	s_add_i32 m0, s4, 0x2000
	s_nop 0
	global_load_lds_dwordx4 v[224:225], off
	s_barrier
; #define G_STAGE(bufoff, gbase, o0, h64) do { \
;         __builtin_amdgcn_global_load_lds((const unsigned*)((const char*)(gbase) + (o0)), (LAS unsigned*)(lds + (bufoff) + ldsw), 16, 0, 0); \
;         __builtin_amdgcn_global_load_lds((const unsigned*)((const char*)(gbase) + (h64) + (o0)), (LAS unsigned*)(lds + (bufoff) + ldsw + 8192), 16, 0, 0); } while (0)
; #define G_LDA(dst, b, h) do { _Pragma("unroll") for (int m = 0; m < 4; ++m) _Pragma("unroll") for (int k = 0; k < 2; ++k) dst[m][k] = *(const LAS bf16x8*)(lds + G_SA(b, h) + aoff + m * 2048 + k * 1024); } while (0)
; #define G_LDB(dst, b, h) do { _Pragma("unroll") for (int n = 0; n < 2; ++n) _Pragma("unroll") for (int k = 0; k < 2; ++k) dst[n][k] = *(const LAS bf16x8*)(lds + G_SB(b, h) + boff + n * 2048 + k * 1024); } while (0)
; #define G_WAIT_V(n) asm volatile("s_waitcnt vmcnt(" #n ")" ::: "memory")
; #define G_WAIT_L(n) asm volatile("s_waitcnt lgkmcnt(" #n ")" ::: "memory")
; #define G_BAR __builtin_amdgcn_s_barrier()
; #define G_SCHED __builtin_amdgcn_sched_barrier(0)
;     ...
;             G_LDB(B0, 1, 0); G_SCHED; G_LDA(At, 1, 0); G_STAGE(G_SA(0, 1), a2 + chA, cA0, qA);
;             G_WAIT_L(8); G_BAR; G_WAIT_L(0); G_MMA(0, 0, At, B0); G_BAR; G_SCHED;
;             G_LDB(B1, 1, 1); G_STAGE(G_SB(1, 0), b3, cB0, qB);
;             G_BAR; G_WAIT_L(0); G_MMA(0, 1, At, B1); G_BAR;
;             G_LDA(At, 1, 1); G_STAGE(G_SA(1, 0), a3, cA0, qA);
;             G_BAR; G_WAIT_L(0); G_MMA(1, 0, At, B0); G_BAR; G_SCHED;
;             G_STAGE(G_SB(1, 1), b3 + chB, cB0, qB);
;             G_WAIT_V(6); G_BAR; G_MMA(1, 1, At, B1); G_BAR;
;         }
	s_waitcnt lgkmcnt(0)
	v_mfma_f32_16x16x32_bf16 v[124:127], v[204:207], v[152:155], v[124:127]
	v_mfma_f32_16x16x32_bf16 v[120:123], v[212:215], v[152:155], v[120:123]
	v_mfma_f32_16x16x32_bf16 v[108:111], v[204:207], v[160:163], v[108:111]
	v_mfma_f32_16x16x32_bf16 v[104:107], v[212:215], v[160:163], v[104:107]
	v_mfma_f32_16x16x32_bf16 v[92:95], v[204:207], v[176:179], v[92:95]
	v_mfma_f32_16x16x32_bf16 v[88:91], v[212:215], v[176:179], v[88:91]
	v_mfma_f32_16x16x32_bf16 v[76:79], v[204:207], v[196:199], v[76:79]
	v_mfma_f32_16x16x32_bf16 v[72:75], v[212:215], v[196:199], v[72:75]
	v_mfma_f32_16x16x32_bf16 v[124:127], v[208:211], v[156:159], v[124:127]
	v_mfma_f32_16x16x32_bf16 v[120:123], v[216:219], v[156:159], v[120:123]
	v_mfma_f32_16x16x32_bf16 v[108:111], v[208:211], v[164:167], v[108:111]
	v_mfma_f32_16x16x32_bf16 v[104:107], v[216:219], v[164:167], v[104:107]
	v_mfma_f32_16x16x32_bf16 v[92:95], v[208:211], v[180:183], v[92:95]
	v_mfma_f32_16x16x32_bf16 v[88:91], v[216:219], v[180:183], v[88:91]
	v_mfma_f32_16x16x32_bf16 v[76:79], v[208:211], v[200:203], v[76:79]
	v_mfma_f32_16x16x32_bf16 v[72:75], v[216:219], v[200:203], v[72:75]
	s_barrier
	s_mov_b32 m0, s31
	v_lshl_add_u64 v[224:225], v[222:223], 0, s[46:47]
	ds_read_b128 v[152:155], v195 offset:49152
	ds_read_b128 v[156:159], v195 offset:50176
	ds_read_b128 v[160:163], v195 offset:51200
	ds_read_b128 v[164:167], v195 offset:52224
	ds_read_b128 v[176:179], v195 offset:53248
	ds_read_b128 v[180:183], v195 offset:54272
	ds_read_b128 v[196:199], v195 offset:55296
	ds_read_b128 v[200:203], v195 offset:56320
	global_load_lds_dwordx4 v[224:225], off
	v_lshl_add_u64 v[222:223], v[222:223], 0, s[66:67]
	s_mov_b32 m0, s34
	s_nop 0
	global_load_lds_dwordx4 v[222:223], off
	s_barrier
	s_waitcnt lgkmcnt(0)
	v_mfma_f32_16x16x32_bf16 v[68:71], v[136:139], v[152:155], v[68:71]
	v_mfma_f32_16x16x32_bf16 v[64:67], v[144:147], v[152:155], v[64:67]
	v_mfma_f32_16x16x32_bf16 v[52:55], v[136:139], v[160:163], v[52:55]
	v_mfma_f32_16x16x32_bf16 v[48:51], v[144:147], v[160:163], v[48:51]
	v_mfma_f32_16x16x32_bf16 v[36:39], v[136:139], v[176:179], v[36:39]
	v_mfma_f32_16x16x32_bf16 v[32:35], v[144:147], v[176:179], v[32:35]
	v_mfma_f32_16x16x32_bf16 v[20:23], v[136:139], v[196:199], v[20:23]
	v_mfma_f32_16x16x32_bf16 v[16:19], v[144:147], v[196:199], v[16:19]
	v_mfma_f32_16x16x32_bf16 v[68:71], v[140:143], v[156:159], v[68:71]
	v_mfma_f32_16x16x32_bf16 v[64:67], v[148:151], v[156:159], v[64:67]
	v_mfma_f32_16x16x32_bf16 v[52:55], v[140:143], v[164:167], v[52:55]
	v_mfma_f32_16x16x32_bf16 v[48:51], v[148:151], v[164:167], v[48:51]
	v_mfma_f32_16x16x32_bf16 v[36:39], v[140:143], v[180:183], v[36:39]
	v_mfma_f32_16x16x32_bf16 v[32:35], v[148:151], v[180:183], v[32:35]
	v_mfma_f32_16x16x32_bf16 v[20:23], v[140:143], v[200:203], v[20:23]
	v_mfma_f32_16x16x32_bf16 v[16:19], v[148:151], v[200:203], v[16:19]
	s_barrier
	s_add_i32 s4, s5, s25
	v_lshl_add_u64 v[136:137], v[220:221], 0, s[52:53]
	s_mov_b32 m0, s4
	s_nop 0
	global_load_lds_dwordx4 v[136:137], off
	v_lshl_add_u64 v[136:137], v[220:221], 0, s[54:55]
	s_add_i32 m0, s4, 0x2000
	s_nop 0
	global_load_lds_dwordx4 v[136:137], off
	s_add_i32 s21, s21, 2
	s_add_u32 s2, s2, 0x100
	s_addc_u32 s3, s3, 0
	s_add_u32 s6, s6, 0x100
	s_addc_u32 s7, s7, 0
	s_cmp_gt_u32 s21, 41
	s_waitcnt vmcnt(6)
	s_barrier
	v_mfma_f32_16x16x32_bf16 v[60:63], v[204:207], v[152:155], v[60:63]
	v_mfma_f32_16x16x32_bf16 v[56:59], v[212:215], v[152:155], v[56:59]
	v_mfma_f32_16x16x32_bf16 v[44:47], v[204:207], v[160:163], v[44:47]
	v_mfma_f32_16x16x32_bf16 v[40:43], v[212:215], v[160:163], v[40:43]
	v_mfma_f32_16x16x32_bf16 v[28:31], v[204:207], v[176:179], v[28:31]
	v_mfma_f32_16x16x32_bf16 v[24:27], v[212:215], v[176:179], v[24:27]
	v_mfma_f32_16x16x32_bf16 v[12:15], v[204:207], v[196:199], v[12:15]
	v_mfma_f32_16x16x32_bf16 v[8:11], v[212:215], v[196:199], v[8:11]
	v_mfma_f32_16x16x32_bf16 v[60:63], v[208:211], v[156:159], v[60:63]
	v_mfma_f32_16x16x32_bf16 v[56:59], v[216:219], v[156:159], v[56:59]
	v_mfma_f32_16x16x32_bf16 v[44:47], v[208:211], v[164:167], v[44:47]
	v_mfma_f32_16x16x32_bf16 v[40:43], v[216:219], v[164:167], v[40:43]
	v_mfma_f32_16x16x32_bf16 v[28:31], v[208:211], v[180:183], v[28:31]
	v_mfma_f32_16x16x32_bf16 v[24:27], v[216:219], v[180:183], v[24:27]
	v_mfma_f32_16x16x32_bf16 v[12:15], v[208:211], v[200:203], v[12:15]
	v_mfma_f32_16x16x32_bf16 v[8:11], v[216:219], v[200:203], v[8:11]
	s_cbranch_scc0 .Ldb_FFO_cont
	v_readfirstlane_b32 s101, v186
	s_cmpk_gt_u32 s101, 0xff
	s_cbranch_scc1 .Ldb_FFO_exit
	s_barrier
	s_branch .Ldb_FFO_exit

; #define G_STAGE(bufoff, gbase, o0, h64) do { \
;         __builtin_amdgcn_global_load_lds((const unsigned*)((const char*)(gbase) + (o0)), (LAS unsigned*)(lds + (bufoff) + ldsw), 16, 0, 0); \
;         __builtin_amdgcn_global_load_lds((const unsigned*)((const char*)(gbase) + (h64) + (o0)), (LAS unsigned*)(lds + (bufoff) + ldsw + 8192), 16, 0, 0); } while (0)
; #define G_LDA(dst, b, h) do { _Pragma("unroll") for (int m = 0; m < 4; ++m) _Pragma("unroll") for (int k = 0; k < 2; ++k) dst[m][k] = *(const LAS bf16x8*)(lds + G_SA(b, h) + aoff + m * 2048 + k * 1024); } while (0)
; #define G_LDB(dst, b, h) do { _Pragma("unroll") for (int n = 0; n < 2; ++n) _Pragma("unroll") for (int k = 0; k < 2; ++k) dst[n][k] = *(const LAS bf16x8*)(lds + G_SB(b, h) + boff + n * 2048 + k * 1024); } while (0)
; #define G_WAIT_L(n) asm volatile("s_waitcnt lgkmcnt(" #n ")" ::: "memory")
; #define G_BAR __builtin_amdgcn_s_barrier()
; #define G_SCHED __builtin_amdgcn_sched_barrier(0)
;     ...
;         for (int t = 0; t < nt; t += 2) {
;             const bool last = (t == nt - 2);
;             const char* a1 = cA + (size_t)(t + 1) * ckA;
;             const char* a2 = last ? nA : cA + (size_t)(t + 2) * ckA; const char* b2 = last ? nB : cB + (size_t)(t + 2) * kB;
;             const char* a3 = a2 + ckA; const char* b3 = b2 + kB;
;             G_LDB(B0, 0, 0); G_SCHED; G_LDA(At, 0, 0); G_STAGE(G_SA(1, 1), a1 + chA, cA0, qA);
;             G_WAIT_L(8); G_BAR; G_WAIT_L(0); G_MMA(0, 0, At, B0); G_BAR; G_SCHED;
;             G_LDB(B1, 0, 1); G_STAGE(G_SB(0, 0), b2, cB0, qB);
;             G_BAR; G_WAIT_L(0); G_MMA(0, 1, At, B1); G_BAR;
;             G_LDA(At, 0, 1); G_STAGE(G_SA(0, 0), a2, cA0, qA);
;             G_BAR; G_WAIT_L(0); G_MMA(1, 0, At, B0); G_BAR; G_SCHED;
.Ldbj_PLE0_in:
.LBB0_1260:
	s_add_u32 s22, s10, s18
	s_addc_u32 s23, s11, s19
	s_add_u32 s20, s22, 0x100
	s_addc_u32 s21, s23, 0
	s_and_b64 s[4:5], s[16:17], exec
	s_cselect_b32 s20, s6, s20
	s_cselect_b32 s21, s7, s21
	s_add_u32 s4, s12, s18
	s_addc_u32 s5, s13, s19
	s_add_u32 s18, s4, 0x100
	s_addc_u32 s19, s5, 0
	s_add_i32 s44, 0, 0x10000
	v_add_u32_e32 v139, s44, v137
	ds_read_b128 v[140:143], v139
	ds_read_b128 v[144:147], v139 offset:1024
	ds_read_b128 v[148:151], v139 offset:2048
	ds_read_b128 v[152:155], v139 offset:3072
	s_and_b64 s[4:5], s[16:17], exec
	s_cselect_b32 s16, s8, s18
	s_cselect_b32 s17, s9, s19
	s_add_i32 s5, 0, 0x14000
	s_add_i32 s43, 0, 0x18000
	s_add_i32 s18, 0, 0x1c000
	s_add_i32 s45, s44, s25
	s_add_i32 s51, s5, s25
	s_add_i32 s19, s43, s25
	s_add_i32 s53, s18, s25
	s_mov_b64 s[64:65], 0x8000
	s_mov_b64 s[62:63], 0x10080
	s_add_i32 m0, s31, 0xc000
	s_add_i32 s4, s31, 0xe000
	s_add_i32 s54, s45, 0x2000
	s_add_i32 s50, s51, 0x2000
	s_add_i32 s44, s19, 0x2000
	s_add_i32 s52, s53, 0x2000
	v_lshl_add_u64 v[184:185], s[22:23], 0, v[2:3]
	v_lshl_add_u64 v[204:205], v[184:185], 0, s[62:63]
	ds_read_b128 v[156:159], v138
	ds_read_b128 v[160:163], v138 offset:1024
	ds_read_b128 v[164:167], v138 offset:2048
	ds_read_b128 v[172:175], v138 offset:3072
	ds_read_b128 v[176:179], v138 offset:4096
	ds_read_b128 v[180:183], v138 offset:5120
	ds_read_b128 v[196:199], v138 offset:6144
	ds_read_b128 v[200:203], v138 offset:7168
	global_load_lds_dwordx4 v[204:205], off
	v_lshl_add_u64 v[184:185], v[184:185], 0, s[68:69]
	s_mov_b32 m0, s4
	s_nop 0
	global_load_lds_dwordx4 v[184:185], off
	s_waitcnt lgkmcnt(8)
	s_barrier
	s_waitcnt lgkmcnt(0)
	v_mfma_f32_16x16x32_bf16 v[132:135], v[140:143], v[156:159], v[132:135]
	v_mfma_f32_16x16x32_bf16 v[128:131], v[148:151], v[156:159], v[128:131]
	v_mfma_f32_16x16x32_bf16 v[124:127], v[140:143], v[164:167], v[124:127]
	v_mfma_f32_16x16x32_bf16 v[116:119], v[148:151], v[164:167], v[116:119]
	v_mfma_f32_16x16x32_bf16 v[108:111], v[140:143], v[176:179], v[108:111]
	v_mfma_f32_16x16x32_bf16 v[100:103], v[148:151], v[176:179], v[100:103]
	v_mfma_f32_16x16x32_bf16 v[92:95], v[140:143], v[196:199], v[92:95]
	v_mfma_f32_16x16x32_bf16 v[84:87], v[148:151], v[196:199], v[84:87]
	v_mfma_f32_16x16x32_bf16 v[132:135], v[144:147], v[160:163], v[132:135]
	v_mfma_f32_16x16x32_bf16 v[128:131], v[152:155], v[160:163], v[128:131]
	v_mfma_f32_16x16x32_bf16 v[124:127], v[144:147], v[172:175], v[124:127]
	v_mfma_f32_16x16x32_bf16 v[116:119], v[152:155], v[172:175], v[116:119]
	v_mfma_f32_16x16x32_bf16 v[108:111], v[144:147], v[180:183], v[108:111]
	v_mfma_f32_16x16x32_bf16 v[100:103], v[152:155], v[180:183], v[100:103]
	v_mfma_f32_16x16x32_bf16 v[92:95], v[144:147], v[200:203], v[92:95]
	v_mfma_f32_16x16x32_bf16 v[84:87], v[152:155], v[200:203], v[84:87]
	s_barrier
	s_mov_b32 m0, s45
	v_add_u32_e32 v139, s5, v137
	v_lshl_add_u64 v[184:185], s[16:17], 0, v[0:1]
	ds_read_b128 v[204:207], v139
	ds_read_b128 v[208:211], v139 offset:1024
	ds_read_b128 v[212:215], v139 offset:2048
	ds_read_b128 v[216:219], v139 offset:3072
	global_load_lds_dwordx4 v[184:185], off
	v_lshl_add_u64 v[220:221], v[184:185], 0, s[64:65]
	s_mov_b32 m0, s54
	s_nop 0
	global_load_lds_dwordx4 v[220:221], off
	s_barrier
	s_waitcnt lgkmcnt(0)
	v_mfma_f32_16x16x32_bf16 v[120:123], v[204:207], v[156:159], v[120:123]
	v_mfma_f32_16x16x32_bf16 v[112:115], v[212:215], v[156:159], v[112:115]
	v_mfma_f32_16x16x32_bf16 v[104:107], v[204:207], v[164:167], v[104:107]
	v_mfma_f32_16x16x32_bf16 v[96:99], v[212:215], v[164:167], v[96:99]
	v_mfma_f32_16x16x32_bf16 v[88:91], v[204:207], v[176:179], v[88:91]
	v_mfma_f32_16x16x32_bf16 v[80:83], v[212:215], v[176:179], v[80:83]
	v_mfma_f32_16x16x32_bf16 v[76:79], v[204:207], v[196:199], v[76:79]
	v_mfma_f32_16x16x32_bf16 v[72:75], v[212:215], v[196:199], v[72:75]
	v_mfma_f32_16x16x32_bf16 v[120:123], v[208:211], v[160:163], v[120:123]
	v_mfma_f32_16x16x32_bf16 v[112:115], v[216:219], v[160:163], v[112:115]
	v_mfma_f32_16x16x32_bf16 v[104:107], v[208:211], v[172:175], v[104:107]
	v_mfma_f32_16x16x32_bf16 v[96:99], v[216:219], v[172:175], v[96:99]
	v_mfma_f32_16x16x32_bf16 v[88:91], v[208:211], v[180:183], v[88:91]
	v_mfma_f32_16x16x32_bf16 v[80:83], v[216:219], v[180:183], v[80:83]
	v_mfma_f32_16x16x32_bf16 v[76:79], v[208:211], v[200:203], v[76:79]
	v_mfma_f32_16x16x32_bf16 v[72:75], v[216:219], v[200:203], v[72:75]
	s_barrier
	s_mov_b32 m0, s31
	v_lshl_add_u64 v[220:221], s[20:21], 0, v[2:3]
	s_mov_b64 s[4:5], 0x8000
	ds_read_b128 v[156:159], v138 offset:16384
	ds_read_b128 v[160:163], v138 offset:17408
	ds_read_b128 v[164:167], v138 offset:18432
	ds_read_b128 v[172:175], v138 offset:19456
	ds_read_b128 v[176:179], v138 offset:20480
	ds_read_b128 v[180:183], v138 offset:21504
	ds_read_b128 v[196:199], v138 offset:22528
	ds_read_b128 v[200:203], v138 offset:23552
	global_load_lds_dwordx4 v[220:221], off
	v_lshl_add_u64 v[222:223], v[220:221], 0, s[4:5]
	s_mov_b32 m0, s33
	s_mov_b64 s[16:17], 0x18000
	global_load_lds_dwordx4 v[222:223], off
	s_barrier
; #define G_STAGE(bufoff, gbase, o0, h64) do { \
;         __builtin_amdgcn_global_load_lds((const unsigned*)((const char*)(gbase) + (o0)), (LAS unsigned*)(lds + (bufoff) + ldsw), 16, 0, 0); \
;         __builtin_amdgcn_global_load_lds((const unsigned*)((const char*)(gbase) + (h64) + (o0)), (LAS unsigned*)(lds + (bufoff) + ldsw + 8192), 16, 0, 0); } while (0)
; #define G_LDA(dst, b, h) do { _Pragma("unroll") for (int m = 0; m < 4; ++m) _Pragma("unroll") for (int k = 0; k < 2; ++k) dst[m][k] = *(const LAS bf16x8*)(lds + G_SA(b, h) + aoff + m * 2048 + k * 1024); } while (0)
; #define G_LDB(dst, b, h) do { _Pragma("unroll") for (int n = 0; n < 2; ++n) _Pragma("unroll") for (int k = 0; k < 2; ++k) dst[n][k] = *(const LAS bf16x8*)(lds + G_SB(b, h) + boff + n * 2048 + k * 1024); } while (0)
; #define G_WAIT_V(n) asm volatile("s_waitcnt vmcnt(" #n ")" ::: "memory")
; #define G_WAIT_L(n) asm volatile("s_waitcnt lgkmcnt(" #n ")" ::: "memory")
; #define G_BAR __builtin_amdgcn_s_barrier()
; #define G_SCHED __builtin_amdgcn_sched_barrier(0)
;     ...
;             G_LDA(At, 0, 1); G_STAGE(G_SA(0, 0), a2, cA0, qA);
;             G_BAR; G_WAIT_L(0); G_MMA(1, 0, At, B0); G_BAR; G_SCHED;
;             G_STAGE(G_SB(0, 1), b2 + chB, cB0, qB);
;             G_WAIT_V(6); G_BAR; G_MMA(1, 1, At, B1); G_BAR;
;             G_LDB(B0, 1, 0); G_SCHED; G_LDA(At, 1, 0); G_STAGE(G_SA(0, 1), a2 + chA, cA0, qA);
;             G_WAIT_L(8); G_BAR; G_WAIT_L(0); G_MMA(0, 0, At, B0); G_BAR; G_SCHED;
	s_waitcnt lgkmcnt(0)
	s_mov_b64 s[20:21], 0x8080
	s_waitcnt lgkmcnt(0)
	v_mfma_f32_16x16x32_bf16 v[68:71], v[140:143], v[156:159], v[68:71]
	v_mfma_f32_16x16x32_bf16 v[64:67], v[148:151], v[156:159], v[64:67]
	v_mfma_f32_16x16x32_bf16 v[60:63], v[140:143], v[164:167], v[60:63]
	v_mfma_f32_16x16x32_bf16 v[52:55], v[148:151], v[164:167], v[52:55]
	v_mfma_f32_16x16x32_bf16 v[44:47], v[140:143], v[176:179], v[44:47]
	v_mfma_f32_16x16x32_bf16 v[36:39], v[148:151], v[176:179], v[36:39]
	v_mfma_f32_16x16x32_bf16 v[28:31], v[140:143], v[196:199], v[28:31]
	v_mfma_f32_16x16x32_bf16 v[20:23], v[148:151], v[196:199], v[20:23]
	v_mfma_f32_16x16x32_bf16 v[68:71], v[144:147], v[160:163], v[68:71]
	v_mfma_f32_16x16x32_bf16 v[64:67], v[152:155], v[160:163], v[64:67]
	v_mfma_f32_16x16x32_bf16 v[60:63], v[144:147], v[172:175], v[60:63]
	v_mfma_f32_16x16x32_bf16 v[52:55], v[152:155], v[172:175], v[52:55]
	v_mfma_f32_16x16x32_bf16 v[44:47], v[144:147], v[180:183], v[44:47]
	v_mfma_f32_16x16x32_bf16 v[36:39], v[152:155], v[180:183], v[36:39]
	v_mfma_f32_16x16x32_bf16 v[28:31], v[144:147], v[200:203], v[28:31]
	v_mfma_f32_16x16x32_bf16 v[20:23], v[152:155], v[200:203], v[20:23]
	s_barrier
	s_mov_b32 m0, s51
	v_lshl_add_u64 v[140:141], v[184:185], 0, s[58:59]
	global_load_lds_dwordx4 v[140:141], off
	v_lshl_add_u64 v[140:141], v[184:185], 0, s[16:17]
	s_mov_b32 m0, s50
	s_nop 0
	global_load_lds_dwordx4 v[140:141], off
	s_waitcnt vmcnt(6)
	s_barrier
	v_mfma_f32_16x16x32_bf16 v[56:59], v[204:207], v[156:159], v[56:59]
	v_mfma_f32_16x16x32_bf16 v[48:51], v[212:215], v[156:159], v[48:51]
	v_mfma_f32_16x16x32_bf16 v[40:43], v[204:207], v[164:167], v[40:43]
	v_mfma_f32_16x16x32_bf16 v[32:35], v[212:215], v[164:167], v[32:35]
	v_mfma_f32_16x16x32_bf16 v[24:27], v[204:207], v[176:179], v[24:27]
	v_mfma_f32_16x16x32_bf16 v[16:19], v[212:215], v[176:179], v[16:19]
	v_mfma_f32_16x16x32_bf16 v[12:15], v[204:207], v[196:199], v[12:15]
	v_mfma_f32_16x16x32_bf16 v[8:11], v[212:215], v[196:199], v[8:11]
	v_mfma_f32_16x16x32_bf16 v[56:59], v[208:211], v[160:163], v[56:59]
	v_mfma_f32_16x16x32_bf16 v[48:51], v[216:219], v[160:163], v[48:51]
	v_mfma_f32_16x16x32_bf16 v[40:43], v[208:211], v[172:175], v[40:43]
	v_mfma_f32_16x16x32_bf16 v[32:35], v[216:219], v[172:175], v[32:35]
	v_mfma_f32_16x16x32_bf16 v[24:27], v[208:211], v[180:183], v[24:27]
	v_mfma_f32_16x16x32_bf16 v[16:19], v[216:219], v[180:183], v[16:19]
	v_mfma_f32_16x16x32_bf16 v[12:15], v[208:211], v[200:203], v[12:15]
	v_mfma_f32_16x16x32_bf16 v[8:11], v[216:219], v[200:203], v[8:11]
	s_barrier
	v_add_u32_e32 v139, s43, v137
	ds_read_b128 v[140:143], v139
	ds_read_b128 v[144:147], v139 offset:1024
	ds_read_b128 v[148:151], v139 offset:2048
	ds_read_b128 v[152:155], v139 offset:3072
	s_mov_b32 m0, s34
	v_lshl_add_u64 v[204:205], v[220:221], 0, s[58:59]
	ds_read_b128 v[156:159], v138 offset:32768
	ds_read_b128 v[160:163], v138 offset:33792
	ds_read_b128 v[164:167], v138 offset:34816
	ds_read_b128 v[172:175], v138 offset:35840
	ds_read_b128 v[176:179], v138 offset:36864
	ds_read_b128 v[180:183], v138 offset:37888
	ds_read_b128 v[196:199], v138 offset:38912
	ds_read_b128 v[200:203], v138 offset:39936
	global_load_lds_dwordx4 v[204:205], off
	v_lshl_add_u64 v[204:205], v[220:221], 0, s[16:17]
	s_mov_b32 m0, s35
	s_nop 0
	global_load_lds_dwordx4 v[204:205], off
	s_waitcnt lgkmcnt(8)
	s_barrier
	s_waitcnt lgkmcnt(0)
	v_mfma_f32_16x16x32_bf16 v[132:135], v[140:143], v[156:159], v[132:135]
	v_mfma_f32_16x16x32_bf16 v[128:131], v[148:151], v[156:159], v[128:131]
	v_mfma_f32_16x16x32_bf16 v[124:127], v[140:143], v[164:167], v[124:127]
	v_mfma_f32_16x16x32_bf16 v[116:119], v[148:151], v[164:167], v[116:119]
	v_mfma_f32_16x16x32_bf16 v[108:111], v[140:143], v[176:179], v[108:111]
	v_mfma_f32_16x16x32_bf16 v[100:103], v[148:151], v[176:179], v[100:103]
	v_mfma_f32_16x16x32_bf16 v[92:95], v[140:143], v[196:199], v[92:95]
	v_mfma_f32_16x16x32_bf16 v[84:87], v[148:151], v[196:199], v[84:87]
	v_mfma_f32_16x16x32_bf16 v[132:135], v[144:147], v[160:163], v[132:135]
	v_mfma_f32_16x16x32_bf16 v[128:131], v[152:155], v[160:163], v[128:131]
	v_mfma_f32_16x16x32_bf16 v[124:127], v[144:147], v[172:175], v[124:127]
	v_mfma_f32_16x16x32_bf16 v[116:119], v[152:155], v[172:175], v[116:119]
	v_mfma_f32_16x16x32_bf16 v[108:111], v[144:147], v[180:183], v[108:111]
	v_mfma_f32_16x16x32_bf16 v[100:103], v[152:155], v[180:183], v[100:103]
	v_mfma_f32_16x16x32_bf16 v[92:95], v[144:147], v[200:203], v[92:95]
	v_mfma_f32_16x16x32_bf16 v[84:87], v[152:155], v[200:203], v[84:87]
	s_barrier
; #define G_STAGE(bufoff, gbase, o0, h64) do { \
;         __builtin_amdgcn_global_load_lds((const unsigned*)((const char*)(gbase) + (o0)), (LAS unsigned*)(lds + (bufoff) + ldsw), 16, 0, 0); \
;         __builtin_amdgcn_global_load_lds((const unsigned*)((const char*)(gbase) + (h64) + (o0)), (LAS unsigned*)(lds + (bufoff) + ldsw + 8192), 16, 0, 0); } while (0)
; #define G_LDA(dst, b, h) do { _Pragma("unroll") for (int m = 0; m < 4; ++m) _Pragma("unroll") for (int k = 0; k < 2; ++k) dst[m][k] = *(const LAS bf16x8*)(lds + G_SA(b, h) + aoff + m * 2048 + k * 1024); } while (0)
; #define G_LDB(dst, b, h) do { _Pragma("unroll") for (int n = 0; n < 2; ++n) _Pragma("unroll") for (int k = 0; k < 2; ++k) dst[n][k] = *(const LAS bf16x8*)(lds + G_SB(b, h) + boff + n * 2048 + k * 1024); } while (0)
; #define G_WAIT_V(n) asm volatile("s_waitcnt vmcnt(" #n ")" ::: "memory")
; #define G_WAIT_L(n) asm volatile("s_waitcnt lgkmcnt(" #n ")" ::: "memory")
; #define G_BAR __builtin_amdgcn_s_barrier()
; #define G_SCHED __builtin_amdgcn_sched_barrier(0)
;     ...
;             G_WAIT_L(8); G_BAR; G_WAIT_L(0); G_MMA(0, 0, At, B0); G_BAR; G_SCHED;
;             G_LDB(B1, 1, 1); G_STAGE(G_SB(1, 0), b3, cB0, qB);
;             G_BAR; G_WAIT_L(0); G_MMA(0, 1, At, B1); G_BAR;
;             G_LDA(At, 1, 1); G_STAGE(G_SA(1, 0), a3, cA0, qA);
;             G_BAR; G_WAIT_L(0); G_MMA(1, 0, At, B0); G_BAR; G_SCHED;
;             G_STAGE(G_SB(1, 1), b3 + chB, cB0, qB);
;             G_WAIT_V(6); G_BAR; G_MMA(1, 1, At, B1); G_BAR;
;         }
	s_mov_b32 m0, s19
	v_add_u32_e32 v139, s18, v137
	v_lshl_add_u64 v[222:223], v[184:185], 0, s[46:47]
	ds_read_b128 v[204:207], v139
	ds_read_b128 v[208:211], v139 offset:1024
	ds_read_b128 v[212:215], v139 offset:2048
	ds_read_b128 v[216:219], v139 offset:3072
	global_load_lds_dwordx4 v[222:223], off
	v_lshl_add_u64 v[222:223], v[184:185], 0, s[20:21]
	s_mov_b32 m0, s44
	s_mov_b64 s[4:5], 0x10080
	global_load_lds_dwordx4 v[222:223], off
	s_barrier
	s_waitcnt lgkmcnt(0)
	v_mfma_f32_16x16x32_bf16 v[120:123], v[204:207], v[156:159], v[120:123]
	v_mfma_f32_16x16x32_bf16 v[112:115], v[212:215], v[156:159], v[112:115]
	v_mfma_f32_16x16x32_bf16 v[104:107], v[204:207], v[164:167], v[104:107]
	v_mfma_f32_16x16x32_bf16 v[96:99], v[212:215], v[164:167], v[96:99]
	v_mfma_f32_16x16x32_bf16 v[88:91], v[204:207], v[176:179], v[88:91]
	v_mfma_f32_16x16x32_bf16 v[80:83], v[212:215], v[176:179], v[80:83]
	v_mfma_f32_16x16x32_bf16 v[76:79], v[204:207], v[196:199], v[76:79]
	v_mfma_f32_16x16x32_bf16 v[72:75], v[212:215], v[196:199], v[72:75]
	v_mfma_f32_16x16x32_bf16 v[120:123], v[208:211], v[160:163], v[120:123]
	v_mfma_f32_16x16x32_bf16 v[112:115], v[216:219], v[160:163], v[112:115]
	v_mfma_f32_16x16x32_bf16 v[104:107], v[208:211], v[172:175], v[104:107]
	v_mfma_f32_16x16x32_bf16 v[96:99], v[216:219], v[172:175], v[96:99]
	v_mfma_f32_16x16x32_bf16 v[88:91], v[208:211], v[180:183], v[88:91]
	v_mfma_f32_16x16x32_bf16 v[80:83], v[216:219], v[180:183], v[80:83]
	v_mfma_f32_16x16x32_bf16 v[76:79], v[208:211], v[200:203], v[76:79]
	v_mfma_f32_16x16x32_bf16 v[72:75], v[216:219], v[200:203], v[72:75]
	s_barrier
	s_mov_b32 m0, s36
	v_lshl_add_u64 v[222:223], v[220:221], 0, s[46:47]
	ds_read_b128 v[156:159], v138 offset:49152
	ds_read_b128 v[160:163], v138 offset:50176
	ds_read_b128 v[164:167], v138 offset:51200
	ds_read_b128 v[172:175], v138 offset:52224
	ds_read_b128 v[176:179], v138 offset:53248
	ds_read_b128 v[180:183], v138 offset:54272
	ds_read_b128 v[196:199], v138 offset:55296
	ds_read_b128 v[200:203], v138 offset:56320
	global_load_lds_dwordx4 v[222:223], off
	v_lshl_add_u64 v[220:221], v[220:221], 0, s[20:21]
	s_mov_b32 m0, s37
	s_nop 0
	global_load_lds_dwordx4 v[220:221], off
	s_barrier
	s_waitcnt lgkmcnt(0)
	v_mfma_f32_16x16x32_bf16 v[68:71], v[140:143], v[156:159], v[68:71]
	v_mfma_f32_16x16x32_bf16 v[64:67], v[148:151], v[156:159], v[64:67]
	v_mfma_f32_16x16x32_bf16 v[60:63], v[140:143], v[164:167], v[60:63]
	v_mfma_f32_16x16x32_bf16 v[52:55], v[148:151], v[164:167], v[52:55]
	v_mfma_f32_16x16x32_bf16 v[44:47], v[140:143], v[176:179], v[44:47]
	v_mfma_f32_16x16x32_bf16 v[36:39], v[148:151], v[176:179], v[36:39]
	v_mfma_f32_16x16x32_bf16 v[28:31], v[140:143], v[196:199], v[28:31]
	v_mfma_f32_16x16x32_bf16 v[20:23], v[148:151], v[196:199], v[20:23]
	v_mfma_f32_16x16x32_bf16 v[68:71], v[144:147], v[160:163], v[68:71]
	v_mfma_f32_16x16x32_bf16 v[64:67], v[152:155], v[160:163], v[64:67]
	v_mfma_f32_16x16x32_bf16 v[60:63], v[144:147], v[172:175], v[60:63]
	v_mfma_f32_16x16x32_bf16 v[52:55], v[152:155], v[172:175], v[52:55]
	v_mfma_f32_16x16x32_bf16 v[44:47], v[144:147], v[180:183], v[44:47]
	v_mfma_f32_16x16x32_bf16 v[36:39], v[152:155], v[180:183], v[36:39]
	v_mfma_f32_16x16x32_bf16 v[28:31], v[144:147], v[200:203], v[28:31]
	v_mfma_f32_16x16x32_bf16 v[20:23], v[152:155], v[200:203], v[20:23]
	s_barrier
	s_mov_b32 m0, s53
	v_lshl_add_u64 v[140:141], v[184:185], 0, s[4:5]
	global_load_lds_dwordx4 v[140:141], off
	v_lshl_add_u64 v[140:141], v[184:185], 0, s[68:69]
	s_mov_b32 m0, s52
	s_nop 0
	global_load_lds_dwordx4 v[140:141], off
	s_waitcnt vmcnt(6)
	s_barrier
	v_mfma_f32_16x16x32_bf16 v[56:59], v[204:207], v[156:159], v[56:59]
	v_mfma_f32_16x16x32_bf16 v[48:51], v[212:215], v[156:159], v[48:51]
	v_mfma_f32_16x16x32_bf16 v[40:43], v[204:207], v[164:167], v[40:43]
	v_mfma_f32_16x16x32_bf16 v[32:35], v[212:215], v[164:167], v[32:35]
	v_mfma_f32_16x16x32_bf16 v[24:27], v[204:207], v[176:179], v[24:27]
	v_mfma_f32_16x16x32_bf16 v[16:19], v[212:215], v[176:179], v[16:19]
	v_mfma_f32_16x16x32_bf16 v[12:15], v[204:207], v[196:199], v[12:15]
	v_mfma_f32_16x16x32_bf16 v[8:11], v[212:215], v[196:199], v[8:11]
	v_mfma_f32_16x16x32_bf16 v[56:59], v[208:211], v[160:163], v[56:59]
	v_mfma_f32_16x16x32_bf16 v[48:51], v[216:219], v[160:163], v[48:51]
	v_mfma_f32_16x16x32_bf16 v[40:43], v[208:211], v[172:175], v[40:43]
	v_mfma_f32_16x16x32_bf16 v[32:35], v[216:219], v[172:175], v[32:35]
	v_mfma_f32_16x16x32_bf16 v[24:27], v[208:211], v[180:183], v[24:27]
	v_mfma_f32_16x16x32_bf16 v[16:19], v[216:219], v[180:183], v[16:19]
	v_mfma_f32_16x16x32_bf16 v[12:15], v[208:211], v[200:203], v[12:15]
	v_mfma_f32_16x16x32_bf16 v[8:11], v[216:219], v[200:203], v[8:11]
	s_andn2_b64 vcc, exec, s[14:15]
	s_mov_b64 s[16:17], -1
	s_mov_b64 s[14:15], 0
	s_mov_b64 s[18:19], 0x100
	s_cbranch_vccz .Ldb_PLE0_cont
	v_readfirstlane_b32 s101, v186
	s_cmpk_gt_u32 s101, 0xff
	s_cbranch_scc1 .Ldb_PLE0_exit
	s_barrier
	s_branch .Ldb_PLE0_exit

; #define G_STAGE(bufoff, gbase, o0, h64) do { \
;         __builtin_amdgcn_global_load_lds((const unsigned*)((const char*)(gbase) + (o0)), (LAS unsigned*)(lds + (bufoff) + ldsw), 16, 0, 0); \
;         __builtin_amdgcn_global_load_lds((const unsigned*)((const char*)(gbase) + (h64) + (o0)), (LAS unsigned*)(lds + (bufoff) + ldsw + 8192), 16, 0, 0); } while (0)
; #define G_LDA(dst, b, h) do { _Pragma("unroll") for (int m = 0; m < 4; ++m) _Pragma("unroll") for (int k = 0; k < 2; ++k) dst[m][k] = *(const LAS bf16x8*)(lds + G_SA(b, h) + aoff + m * 2048 + k * 1024); } while (0)
; #define G_LDB(dst, b, h) do { _Pragma("unroll") for (int n = 0; n < 2; ++n) _Pragma("unroll") for (int k = 0; k < 2; ++k) dst[n][k] = *(const LAS bf16x8*)(lds + G_SB(b, h) + boff + n * 2048 + k * 1024); } while (0)
; #define G_WAIT_L(n) asm volatile("s_waitcnt lgkmcnt(" #n ")" ::: "memory")
; #define G_BAR __builtin_amdgcn_s_barrier()
; #define G_SCHED __builtin_amdgcn_sched_barrier(0)
;     ...
;         for (int t = 0; t < nt; t += 2) {
;             const bool last = (t == nt - 2);
;             const char* a1 = cA + (size_t)(t + 1) * ckA;
;             const char* a2 = last ? nA : cA + (size_t)(t + 2) * ckA; const char* b2 = last ? nB : cB + (size_t)(t + 2) * kB;
;             const char* a3 = a2 + ckA; const char* b3 = b2 + kB;
;             G_LDB(B0, 0, 0); G_SCHED; G_LDA(At, 0, 0); G_STAGE(G_SA(1, 1), a1 + chA, cA0, qA);
;             G_WAIT_L(8); G_BAR; G_WAIT_L(0); G_MMA(0, 0, At, B0); G_BAR; G_SCHED;
;             G_LDB(B1, 0, 1); G_STAGE(G_SB(0, 0), b2, cB0, qB);
;             G_BAR; G_WAIT_L(0); G_MMA(0, 1, At, B1); G_BAR;
;             G_LDA(At, 0, 1); G_STAGE(G_SA(0, 0), a2, cA0, qA);
;             G_BAR; G_WAIT_L(0); G_MMA(1, 0, At, B0); G_BAR; G_SCHED;
.Ldbj_PLE1_in:
.LBB0_1283:
	s_add_u32 s4, s2, 0xfffc0080
	s_addc_u32 s5, s3, -1
	s_add_i32 s25, 0, 0x10000
	v_add_u32_e32 v0, s25, v181
	ds_read_b128 v[136:139], v0
	ds_read_b128 v[140:143], v0 offset:1024
	ds_read_b128 v[144:147], v0 offset:2048
	ds_read_b128 v[148:151], v0 offset:3072
	s_cmp_eq_u32 s24, 12
	s_cselect_b32 s5, s19, s5
	s_cselect_b32 s4, s18, s4
	s_cselect_b32 s41, s21, s23
	s_cselect_b32 s40, s20, s22
	v_lshl_add_u64 v[184:185], s[2:3], 0, v[158:159]
	s_add_i32 m0, s29, 0xc000
	ds_read_b128 v[152:155], v182
	ds_read_b128 v[160:163], v182 offset:1024
	ds_read_b128 v[164:167], v182 offset:2048
	ds_read_b128 v[172:175], v182 offset:3072
	ds_read_b128 v[176:179], v182 offset:4096
	ds_read_b128 v[196:199], v182 offset:5120
	ds_read_b128 v[200:203], v182 offset:6144
	ds_read_b128 v[204:207], v182 offset:7168
	global_load_lds_dwordx4 v[184:185], off
	v_lshl_add_u64 v[184:185], v[184:185], 0, s[0:1]
	s_add_i32 m0, s29, 0xe000
	s_nop 0
	global_load_lds_dwordx4 v[184:185], off
	s_waitcnt lgkmcnt(8)
	s_barrier
	s_waitcnt lgkmcnt(0)
	v_mfma_f32_16x16x32_bf16 v[132:135], v[136:139], v[152:155], v[132:135]
	v_mfma_f32_16x16x32_bf16 v[128:131], v[144:147], v[152:155], v[128:131]
	v_mfma_f32_16x16x32_bf16 v[116:119], v[136:139], v[164:167], v[116:119]
	v_mfma_f32_16x16x32_bf16 v[112:115], v[144:147], v[164:167], v[112:115]
	v_mfma_f32_16x16x32_bf16 v[100:103], v[136:139], v[176:179], v[100:103]
	v_mfma_f32_16x16x32_bf16 v[96:99], v[144:147], v[176:179], v[96:99]
	v_mfma_f32_16x16x32_bf16 v[84:87], v[136:139], v[200:203], v[84:87]
	v_mfma_f32_16x16x32_bf16 v[80:83], v[144:147], v[200:203], v[80:83]
	v_mfma_f32_16x16x32_bf16 v[132:135], v[140:143], v[160:163], v[132:135]
	v_mfma_f32_16x16x32_bf16 v[128:131], v[148:151], v[160:163], v[128:131]
	v_mfma_f32_16x16x32_bf16 v[116:119], v[140:143], v[172:175], v[116:119]
	v_mfma_f32_16x16x32_bf16 v[112:115], v[148:151], v[172:175], v[112:115]
	v_mfma_f32_16x16x32_bf16 v[100:103], v[140:143], v[196:199], v[100:103]
	v_mfma_f32_16x16x32_bf16 v[96:99], v[148:151], v[196:199], v[96:99]
	v_mfma_f32_16x16x32_bf16 v[84:87], v[140:143], v[204:207], v[84:87]
	v_mfma_f32_16x16x32_bf16 v[80:83], v[148:151], v[204:207], v[80:83]
	s_barrier
	s_add_i32 s44, 0, 0x14000
	s_add_i32 s25, s25, s27
	v_add_u32_e32 v0, s44, v181
	v_lshl_add_u64 v[184:185], s[40:41], 0, v[156:157]
	s_mov_b32 m0, s25
	ds_read_b128 v[208:211], v0
	ds_read_b128 v[212:215], v0 offset:1024
	ds_read_b128 v[216:219], v0 offset:2048
	ds_read_b128 v[220:223], v0 offset:3072
	global_load_lds_dwordx4 v[184:185], off
	v_lshl_add_u64 v[224:225], v[184:185], 0, s[0:1]
	s_add_i32 m0, s25, 0x2000
	s_nop 0
	global_load_lds_dwordx4 v[224:225], off
	s_barrier
	s_waitcnt lgkmcnt(0)
	v_mfma_f32_16x16x32_bf16 v[124:127], v[208:211], v[152:155], v[124:127]
	v_mfma_f32_16x16x32_bf16 v[120:123], v[216:219], v[152:155], v[120:123]
	v_mfma_f32_16x16x32_bf16 v[108:111], v[208:211], v[164:167], v[108:111]
	v_mfma_f32_16x16x32_bf16 v[104:107], v[216:219], v[164:167], v[104:107]
	v_mfma_f32_16x16x32_bf16 v[92:95], v[208:211], v[176:179], v[92:95]
	v_mfma_f32_16x16x32_bf16 v[88:91], v[216:219], v[176:179], v[88:91]
	v_mfma_f32_16x16x32_bf16 v[76:79], v[208:211], v[200:203], v[76:79]
	v_mfma_f32_16x16x32_bf16 v[72:75], v[216:219], v[200:203], v[72:75]
	v_mfma_f32_16x16x32_bf16 v[124:127], v[212:215], v[160:163], v[124:127]
	v_mfma_f32_16x16x32_bf16 v[120:123], v[220:223], v[160:163], v[120:123]
	v_mfma_f32_16x16x32_bf16 v[108:111], v[212:215], v[172:175], v[108:111]
	v_mfma_f32_16x16x32_bf16 v[104:107], v[220:223], v[172:175], v[104:107]
	v_mfma_f32_16x16x32_bf16 v[92:95], v[212:215], v[196:199], v[92:95]
	v_mfma_f32_16x16x32_bf16 v[88:91], v[220:223], v[196:199], v[88:91]
	v_mfma_f32_16x16x32_bf16 v[76:79], v[212:215], v[204:207], v[76:79]
	v_mfma_f32_16x16x32_bf16 v[72:75], v[220:223], v[204:207], v[72:75]
	s_barrier
	s_mov_b32 m0, s29
	v_lshl_add_u64 v[224:225], s[4:5], 0, v[2:3]
	ds_read_b128 v[152:155], v182 offset:16384
	ds_read_b128 v[160:163], v182 offset:17408
	ds_read_b128 v[164:167], v182 offset:18432
	ds_read_b128 v[172:175], v182 offset:19456
	ds_read_b128 v[176:179], v182 offset:20480
	ds_read_b128 v[196:199], v182 offset:21504
	ds_read_b128 v[200:203], v182 offset:22528
	ds_read_b128 v[204:207], v182 offset:23552
	global_load_lds_dwordx4 v[224:225], off
	v_lshl_add_u64 v[226:227], v[224:225], 0, s[0:1]
	s_mov_b32 m0, s30
	s_nop 0
	global_load_lds_dwordx4 v[226:227], off
	s_barrier
	s_waitcnt lgkmcnt(0)
	v_mfma_f32_16x16x32_bf16 v[68:71], v[136:139], v[152:155], v[68:71]
	v_mfma_f32_16x16x32_bf16 v[64:67], v[144:147], v[152:155], v[64:67]
	v_mfma_f32_16x16x32_bf16 v[52:55], v[136:139], v[164:167], v[52:55]
	v_mfma_f32_16x16x32_bf16 v[48:51], v[144:147], v[164:167], v[48:51]
	v_mfma_f32_16x16x32_bf16 v[36:39], v[136:139], v[176:179], v[36:39]
	v_mfma_f32_16x16x32_bf16 v[32:35], v[144:147], v[176:179], v[32:35]
	v_mfma_f32_16x16x32_bf16 v[20:23], v[136:139], v[200:203], v[20:23]
	v_mfma_f32_16x16x32_bf16 v[16:19], v[144:147], v[200:203], v[16:19]
	v_mfma_f32_16x16x32_bf16 v[68:71], v[140:143], v[160:163], v[68:71]
	v_mfma_f32_16x16x32_bf16 v[64:67], v[148:151], v[160:163], v[64:67]
	v_mfma_f32_16x16x32_bf16 v[52:55], v[140:143], v[172:175], v[52:55]
	v_mfma_f32_16x16x32_bf16 v[48:51], v[148:151], v[172:175], v[48:51]
	v_mfma_f32_16x16x32_bf16 v[36:39], v[140:143], v[196:199], v[36:39]
	v_mfma_f32_16x16x32_bf16 v[32:35], v[148:151], v[196:199], v[32:35]
	v_mfma_f32_16x16x32_bf16 v[20:23], v[140:143], v[204:207], v[20:23]
	v_mfma_f32_16x16x32_bf16 v[16:19], v[148:151], v[204:207], v[16:19]
	s_barrier
; #define G_STAGE(bufoff, gbase, o0, h64) do { \
;         __builtin_amdgcn_global_load_lds((const unsigned*)((const char*)(gbase) + (o0)), (LAS unsigned*)(lds + (bufoff) + ldsw), 16, 0, 0); \
;         __builtin_amdgcn_global_load_lds((const unsigned*)((const char*)(gbase) + (h64) + (o0)), (LAS unsigned*)(lds + (bufoff) + ldsw + 8192), 16, 0, 0); } while (0)
; #define G_LDA(dst, b, h) do { _Pragma("unroll") for (int m = 0; m < 4; ++m) _Pragma("unroll") for (int k = 0; k < 2; ++k) dst[m][k] = *(const LAS bf16x8*)(lds + G_SA(b, h) + aoff + m * 2048 + k * 1024); } while (0)
; #define G_LDB(dst, b, h) do { _Pragma("unroll") for (int n = 0; n < 2; ++n) _Pragma("unroll") for (int k = 0; k < 2; ++k) dst[n][k] = *(const LAS bf16x8*)(lds + G_SB(b, h) + boff + n * 2048 + k * 1024); } while (0)
; #define G_WAIT_V(n) asm volatile("s_waitcnt vmcnt(" #n ")" ::: "memory")
; #define G_WAIT_L(n) asm volatile("s_waitcnt lgkmcnt(" #n ")" ::: "memory")
; #define G_BAR __builtin_amdgcn_s_barrier()
; #define G_SCHED __builtin_amdgcn_sched_barrier(0)
;     ...
;             G_STAGE(G_SB(0, 1), b2 + chB, cB0, qB);
;             G_WAIT_V(6); G_BAR; G_MMA(1, 1, At, B1); G_BAR;
;             G_LDB(B0, 1, 0); G_SCHED; G_LDA(At, 1, 0); G_STAGE(G_SA(0, 1), a2 + chA, cA0, qA);
;             G_WAIT_L(8); G_BAR; G_WAIT_L(0); G_MMA(0, 0, At, B0); G_BAR; G_SCHED;
;             G_LDB(B1, 1, 1); G_STAGE(G_SB(1, 0), b3, cB0, qB);
;             G_BAR; G_WAIT_L(0); G_MMA(0, 1, At, B1); G_BAR;
	s_add_i32 s4, s44, s27
	v_lshl_add_u64 v[136:137], v[184:185], 0, s[54:55]
	s_mov_b32 m0, s4
	s_nop 0
	global_load_lds_dwordx4 v[136:137], off
	v_lshl_add_u64 v[136:137], v[184:185], 0, s[58:59]
	s_add_i32 m0, s4, 0x2000
	s_nop 0
	global_load_lds_dwordx4 v[136:137], off
	s_waitcnt vmcnt(6)
	s_barrier
	v_mfma_f32_16x16x32_bf16 v[60:63], v[208:211], v[152:155], v[60:63]
	v_mfma_f32_16x16x32_bf16 v[56:59], v[216:219], v[152:155], v[56:59]
	v_mfma_f32_16x16x32_bf16 v[44:47], v[208:211], v[164:167], v[44:47]
	v_mfma_f32_16x16x32_bf16 v[40:43], v[216:219], v[164:167], v[40:43]
	v_mfma_f32_16x16x32_bf16 v[28:31], v[208:211], v[176:179], v[28:31]
	v_mfma_f32_16x16x32_bf16 v[24:27], v[216:219], v[176:179], v[24:27]
	v_mfma_f32_16x16x32_bf16 v[12:15], v[208:211], v[200:203], v[12:15]
	v_mfma_f32_16x16x32_bf16 v[8:11], v[216:219], v[200:203], v[8:11]
	v_mfma_f32_16x16x32_bf16 v[60:63], v[212:215], v[160:163], v[60:63]
	v_mfma_f32_16x16x32_bf16 v[56:59], v[220:223], v[160:163], v[56:59]
	v_mfma_f32_16x16x32_bf16 v[44:47], v[212:215], v[172:175], v[44:47]
	v_mfma_f32_16x16x32_bf16 v[40:43], v[220:223], v[172:175], v[40:43]
	v_mfma_f32_16x16x32_bf16 v[28:31], v[212:215], v[196:199], v[28:31]
	v_mfma_f32_16x16x32_bf16 v[24:27], v[220:223], v[196:199], v[24:27]
	v_mfma_f32_16x16x32_bf16 v[12:15], v[212:215], v[204:207], v[12:15]
	v_mfma_f32_16x16x32_bf16 v[8:11], v[220:223], v[204:207], v[8:11]
	s_barrier
	s_add_i32 s4, 0, 0x18000
	v_add_u32_e32 v0, s4, v181
	ds_read_b128 v[136:139], v0
	ds_read_b128 v[140:143], v0 offset:1024
	ds_read_b128 v[144:147], v0 offset:2048
	ds_read_b128 v[148:151], v0 offset:3072
	s_mov_b32 m0, s31
	v_lshl_add_u64 v[208:209], v[224:225], 0, s[54:55]
	ds_read_b128 v[152:155], v182 offset:32768
	ds_read_b128 v[160:163], v182 offset:33792
	ds_read_b128 v[164:167], v182 offset:34816
	ds_read_b128 v[172:175], v182 offset:35840
	ds_read_b128 v[176:179], v182 offset:36864
	ds_read_b128 v[196:199], v182 offset:37888
	ds_read_b128 v[200:203], v182 offset:38912
	ds_read_b128 v[204:207], v182 offset:39936
	global_load_lds_dwordx4 v[208:209], off
	v_lshl_add_u64 v[208:209], v[224:225], 0, s[58:59]
	s_mov_b32 m0, s34
	s_nop 0
	global_load_lds_dwordx4 v[208:209], off
	s_waitcnt lgkmcnt(8)
	s_barrier
	s_waitcnt lgkmcnt(0)
	v_mfma_f32_16x16x32_bf16 v[132:135], v[136:139], v[152:155], v[132:135]
	v_mfma_f32_16x16x32_bf16 v[128:131], v[144:147], v[152:155], v[128:131]
	v_mfma_f32_16x16x32_bf16 v[116:119], v[136:139], v[164:167], v[116:119]
	v_mfma_f32_16x16x32_bf16 v[112:115], v[144:147], v[164:167], v[112:115]
	v_mfma_f32_16x16x32_bf16 v[100:103], v[136:139], v[176:179], v[100:103]
	v_mfma_f32_16x16x32_bf16 v[96:99], v[144:147], v[176:179], v[96:99]
	v_mfma_f32_16x16x32_bf16 v[84:87], v[136:139], v[200:203], v[84:87]
	v_mfma_f32_16x16x32_bf16 v[80:83], v[144:147], v[200:203], v[80:83]
	v_mfma_f32_16x16x32_bf16 v[132:135], v[140:143], v[160:163], v[132:135]
	v_mfma_f32_16x16x32_bf16 v[128:131], v[148:151], v[160:163], v[128:131]
	v_mfma_f32_16x16x32_bf16 v[116:119], v[140:143], v[172:175], v[116:119]
	v_mfma_f32_16x16x32_bf16 v[112:115], v[148:151], v[172:175], v[112:115]
	v_mfma_f32_16x16x32_bf16 v[100:103], v[140:143], v[196:199], v[100:103]
	v_mfma_f32_16x16x32_bf16 v[96:99], v[148:151], v[196:199], v[96:99]
	v_mfma_f32_16x16x32_bf16 v[84:87], v[140:143], v[204:207], v[84:87]
	v_mfma_f32_16x16x32_bf16 v[80:83], v[148:151], v[204:207], v[80:83]
	s_barrier
	s_add_i32 s5, 0, 0x1c000
	s_add_i32 s4, s4, s27
	v_add_u32_e32 v0, s5, v181
	v_lshl_add_u64 v[226:227], v[184:185], 0, s[46:47]
	s_mov_b32 m0, s4
	ds_read_b128 v[208:211], v0
	ds_read_b128 v[212:215], v0 offset:1024
	ds_read_b128 v[216:219], v0 offset:2048
	ds_read_b128 v[220:223], v0 offset:3072
	global_load_lds_dwordx4 v[226:227], off
	v_lshl_add_u64 v[226:227], v[184:185], 0, s[62:63]
	s_add_i32 m0, s4, 0x2000
	s_nop 0
	global_load_lds_dwordx4 v[226:227], off
	s_barrier
; #define G_STAGE(bufoff, gbase, o0, h64) do { \
;         __builtin_amdgcn_global_load_lds((const unsigned*)((const char*)(gbase) + (o0)), (LAS unsigned*)(lds + (bufoff) + ldsw), 16, 0, 0); \
;         __builtin_amdgcn_global_load_lds((const unsigned*)((const char*)(gbase) + (h64) + (o0)), (LAS unsigned*)(lds + (bufoff) + ldsw + 8192), 16, 0, 0); } while (0)
; #define G_LDA(dst, b, h) do { _Pragma("unroll") for (int m = 0; m < 4; ++m) _Pragma("unroll") for (int k = 0; k < 2; ++k) dst[m][k] = *(const LAS bf16x8*)(lds + G_SA(b, h) + aoff + m * 2048 + k * 1024); } while (0)
; #define G_LDB(dst, b, h) do { _Pragma("unroll") for (int n = 0; n < 2; ++n) _Pragma("unroll") for (int k = 0; k < 2; ++k) dst[n][k] = *(const LAS bf16x8*)(lds + G_SB(b, h) + boff + n * 2048 + k * 1024); } while (0)
; #define G_WAIT_V(n) asm volatile("s_waitcnt vmcnt(" #n ")" ::: "memory")
; #define G_WAIT_L(n) asm volatile("s_waitcnt lgkmcnt(" #n ")" ::: "memory")
; #define G_BAR __builtin_amdgcn_s_barrier()
; #define G_SCHED __builtin_amdgcn_sched_barrier(0)
;     ...
;             G_LDB(B1, 1, 1); G_STAGE(G_SB(1, 0), b3, cB0, qB);
;             G_BAR; G_WAIT_L(0); G_MMA(0, 1, At, B1); G_BAR;
;             G_LDA(At, 1, 1); G_STAGE(G_SA(1, 0), a3, cA0, qA);
;             G_BAR; G_WAIT_L(0); G_MMA(1, 0, At, B0); G_BAR; G_SCHED;
;             G_STAGE(G_SB(1, 1), b3 + chB, cB0, qB);
;             G_WAIT_V(6); G_BAR; G_MMA(1, 1, At, B1); G_BAR;
;         }
	s_waitcnt lgkmcnt(0)
	v_mfma_f32_16x16x32_bf16 v[124:127], v[208:211], v[152:155], v[124:127]
	v_mfma_f32_16x16x32_bf16 v[120:123], v[216:219], v[152:155], v[120:123]
	v_mfma_f32_16x16x32_bf16 v[108:111], v[208:211], v[164:167], v[108:111]
	v_mfma_f32_16x16x32_bf16 v[104:107], v[216:219], v[164:167], v[104:107]
	v_mfma_f32_16x16x32_bf16 v[92:95], v[208:211], v[176:179], v[92:95]
	v_mfma_f32_16x16x32_bf16 v[88:91], v[216:219], v[176:179], v[88:91]
	v_mfma_f32_16x16x32_bf16 v[76:79], v[208:211], v[200:203], v[76:79]
	v_mfma_f32_16x16x32_bf16 v[72:75], v[216:219], v[200:203], v[72:75]
	v_mfma_f32_16x16x32_bf16 v[124:127], v[212:215], v[160:163], v[124:127]
	v_mfma_f32_16x16x32_bf16 v[120:123], v[220:223], v[160:163], v[120:123]
	v_mfma_f32_16x16x32_bf16 v[108:111], v[212:215], v[172:175], v[108:111]
	v_mfma_f32_16x16x32_bf16 v[104:107], v[220:223], v[172:175], v[104:107]
	v_mfma_f32_16x16x32_bf16 v[92:95], v[212:215], v[196:199], v[92:95]
	v_mfma_f32_16x16x32_bf16 v[88:91], v[220:223], v[196:199], v[88:91]
	v_mfma_f32_16x16x32_bf16 v[76:79], v[212:215], v[204:207], v[76:79]
	v_mfma_f32_16x16x32_bf16 v[72:75], v[220:223], v[204:207], v[72:75]
	s_barrier
	s_mov_b32 m0, s35
	v_lshl_add_u64 v[226:227], v[224:225], 0, s[46:47]
	ds_read_b128 v[152:155], v182 offset:49152
	ds_read_b128 v[160:163], v182 offset:50176
	ds_read_b128 v[164:167], v182 offset:51200
	ds_read_b128 v[172:175], v182 offset:52224
	ds_read_b128 v[176:179], v182 offset:53248
	ds_read_b128 v[196:199], v182 offset:54272
	ds_read_b128 v[200:203], v182 offset:55296
	ds_read_b128 v[204:207], v182 offset:56320
	global_load_lds_dwordx4 v[226:227], off
	v_lshl_add_u64 v[224:225], v[224:225], 0, s[62:63]
	s_mov_b32 m0, s36
	s_nop 0
	global_load_lds_dwordx4 v[224:225], off
	s_barrier
	s_waitcnt lgkmcnt(0)
	v_mfma_f32_16x16x32_bf16 v[68:71], v[136:139], v[152:155], v[68:71]
	v_mfma_f32_16x16x32_bf16 v[64:67], v[144:147], v[152:155], v[64:67]
	v_mfma_f32_16x16x32_bf16 v[52:55], v[136:139], v[164:167], v[52:55]
	v_mfma_f32_16x16x32_bf16 v[48:51], v[144:147], v[164:167], v[48:51]
	v_mfma_f32_16x16x32_bf16 v[36:39], v[136:139], v[176:179], v[36:39]
	v_mfma_f32_16x16x32_bf16 v[32:35], v[144:147], v[176:179], v[32:35]
	v_mfma_f32_16x16x32_bf16 v[20:23], v[136:139], v[200:203], v[20:23]
	v_mfma_f32_16x16x32_bf16 v[16:19], v[144:147], v[200:203], v[16:19]
	v_mfma_f32_16x16x32_bf16 v[68:71], v[140:143], v[160:163], v[68:71]
	v_mfma_f32_16x16x32_bf16 v[64:67], v[148:151], v[160:163], v[64:67]
	v_mfma_f32_16x16x32_bf16 v[52:55], v[140:143], v[172:175], v[52:55]
	v_mfma_f32_16x16x32_bf16 v[48:51], v[148:151], v[172:175], v[48:51]
	v_mfma_f32_16x16x32_bf16 v[36:39], v[140:143], v[196:199], v[36:39]
	v_mfma_f32_16x16x32_bf16 v[32:35], v[148:151], v[196:199], v[32:35]
	v_mfma_f32_16x16x32_bf16 v[20:23], v[140:143], v[204:207], v[20:23]
	v_mfma_f32_16x16x32_bf16 v[16:19], v[148:151], v[204:207], v[16:19]
	s_barrier
	s_add_i32 s4, s5, s27
	v_lshl_add_u64 v[136:137], v[184:185], 0, s[64:65]
	s_mov_b32 m0, s4
	s_nop 0
	global_load_lds_dwordx4 v[136:137], off
	v_lshl_add_u64 v[136:137], v[184:185], 0, s[66:67]
	s_add_i32 m0, s4, 0x2000
	s_nop 0
	global_load_lds_dwordx4 v[136:137], off
	s_add_i32 s24, s24, 2
	s_add_u32 s2, s2, 0x100
	s_addc_u32 s3, s3, 0
	s_add_u32 s22, s22, 0x100
	s_addc_u32 s23, s23, 0
	s_cmp_gt_u32 s24, 13
	s_waitcnt vmcnt(6)
	s_barrier
	v_mfma_f32_16x16x32_bf16 v[60:63], v[208:211], v[152:155], v[60:63]
	v_mfma_f32_16x16x32_bf16 v[56:59], v[216:219], v[152:155], v[56:59]
	v_mfma_f32_16x16x32_bf16 v[44:47], v[208:211], v[164:167], v[44:47]
	v_mfma_f32_16x16x32_bf16 v[40:43], v[216:219], v[164:167], v[40:43]
	v_mfma_f32_16x16x32_bf16 v[28:31], v[208:211], v[176:179], v[28:31]
	v_mfma_f32_16x16x32_bf16 v[24:27], v[216:219], v[176:179], v[24:27]
	v_mfma_f32_16x16x32_bf16 v[12:15], v[208:211], v[200:203], v[12:15]
	v_mfma_f32_16x16x32_bf16 v[8:11], v[216:219], v[200:203], v[8:11]
	v_mfma_f32_16x16x32_bf16 v[60:63], v[212:215], v[160:163], v[60:63]
	v_mfma_f32_16x16x32_bf16 v[56:59], v[220:223], v[160:163], v[56:59]
	v_mfma_f32_16x16x32_bf16 v[44:47], v[212:215], v[172:175], v[44:47]
	v_mfma_f32_16x16x32_bf16 v[40:43], v[220:223], v[172:175], v[40:43]
	v_mfma_f32_16x16x32_bf16 v[28:31], v[212:215], v[196:199], v[28:31]
	v_mfma_f32_16x16x32_bf16 v[24:27], v[220:223], v[196:199], v[24:27]
	v_mfma_f32_16x16x32_bf16 v[12:15], v[212:215], v[204:207], v[12:15]
	v_mfma_f32_16x16x32_bf16 v[8:11], v[220:223], v[204:207], v[8:11]
	s_cbranch_scc0 .Ldb_PLE1_cont
	v_readfirstlane_b32 s101, v186
	s_cmpk_gt_u32 s101, 0xff
	s_cbranch_scc1 .Ldb_PLE1_exit
	s_barrier
	s_branch .Ldb_PLE1_exit
